# GEMM K-loops: loop counter / address bump / exit test hoisted above the loop-back barrier (back-edge rotation, 9 loops)
# speedup vs baseline: 1.0086x; 1.0086x over previous
; #define PG8_STAGE(bufoff, gbase, voff) do { _Pragma("unroll") for (int _i = 0; _i < 2; ++_i) \
;         __builtin_amdgcn_global_load_lds((const unsigned*)((const char*)(gbase) + (voff)[_i]), (PG8_LAS unsigned*)(lds + (bufoff) + ldsw + _i * 8192), 16, 0, 0); } while (0)
; #define PG8_LDA(dst, b, h) do { _Pragma("unroll") for (int m = 0; m < 4; ++m) _Pragma("unroll") for (int k = 0; k < 2; ++k) dst[m][k] = *(const PG8_LAS bf16x8*)(lds + PG8_SA(b, h) + aoff + m * 2048 + k * 1024); } while (0)
; #define PG8_LDB(dst, b, h) do { _Pragma("unroll") for (int n = 0; n < 2; ++n) _Pragma("unroll") for (int k = 0; k < 2; ++k) dst[n][k] = *(const PG8_LAS bf16x8*)(lds + PG8_SB(b, h) + boff + n * 2048 + k * 1024); } while (0)
; #define PG8_MMA(ai, bj, At, Bt) do { __builtin_amdgcn_s_setprio(1); _Pragma("unroll") for (int m = 0; m < 4; ++m) _Pragma("unroll") for (int n = 0; n < 2; ++n) _Pragma("unroll") for (int k = 0; k < 2; ++k) \
;         acc[ai][bj][m][n] = __builtin_amdgcn_mfma_f32_16x16x32_bf16(Bt[n][k], At[m][k], acc[ai][bj][m][n], 0, 0, 0); __builtin_amdgcn_s_setprio(0); } while (0)
; #define PG8_WAIT_V(n) asm volatile("s_waitcnt vmcnt(" #n ")" ::: "memory")
; #define PG8_WAIT_L(n) asm volatile("s_waitcnt lgkmcnt(" #n ")" ::: "memory")
; #define PG8_BAR __builtin_amdgcn_s_barrier()
; #define PG8_SCHED __builtin_amdgcn_sched_barrier(0)
; template <class Epi, class Sched, bool ALIGN_EPI = false, bool SP2 = false>
; __device__ __forceinline__ void gemm_phase(PG8_LAS unsigned char* lds, const Gemm g, const Sched& S, const Epi& E) {
;     ...
;             PG8_LDB(B0, 0, 0); PG8_LDB(B1, 0, 1); PG8_SCHED; PG8_LDA(At, 0, 0); PG8_STAGE(PG8_SA(1, 1), a1 + hstep, voffA);
;             PG8_WAIT_V(8); PG8_WAIT_L(0); PG8_BAR; PG8_MMA(0, 0, At, B0); PG8_MMA(0, 1, At, B1); PG8_BAR; PG8_SCHED;
;             PG8_LDA(At, 0, 1); PG8_STAGE(PG8_SB(0, 0), b2, voffB); PG8_STAGE(PG8_SB(0, 1), b2 + hstep, voffB); PG8_STAGE(PG8_SA(0, 0), a2, voffA);
;             PG8_WAIT_V(8); PG8_WAIT_L(0); PG8_BAR; PG8_MMA(1, 0, At, B0); PG8_MMA(1, 1, At, B1); PG8_BAR; PG8_SCHED;
.LBB0_293:
	ds_read_b128 v[144:147], v151
	ds_read_b128 v[154:157], v151 offset:1024
	ds_read_b128 v[158:161], v151 offset:2048
	ds_read_b128 v[162:165], v151 offset:3072
	ds_read_b128 v[166:169], v152
	ds_read_b128 v[170:173], v152 offset:1024
	ds_read_b128 v[174:177], v152 offset:2048
	ds_read_b128 v[178:181], v152 offset:3072
	s_add_u32 s26, s24, 0xfffc0080
	s_addc_u32 s27, s25, -1
	s_cmp_eq_u32 s50, 12
	s_cselect_b32 s29, s17, s27
	s_cselect_b32 s28, s46, s26
	s_cselect_b32 s27, s15, s49
	s_cselect_b32 s26, s47, s48
	v_lshl_add_u64 v[194:195], s[24:25], 0, v[136:137]
	s_add_i32 m0, s23, 0xc000
	ds_read_b128 v[182:185], v153
	ds_read_b128 v[186:189], v153 offset:1024
	ds_read_b128 v[190:193], v153 offset:2048
	ds_read_b128 v[198:201], v153 offset:3072
	ds_read_b128 v[202:205], v153 offset:4096
	ds_read_b128 v[206:209], v153 offset:5120
	ds_read_b128 v[210:213], v153 offset:6144
	ds_read_b128 v[214:217], v153 offset:7168
	global_load_lds_dwordx4 v[194:195], off
	v_lshl_add_u64 v[194:195], s[24:25], 0, v[138:139]
	s_add_i32 m0, s23, 0xe000
	s_nop 0
	global_load_lds_dwordx4 v[194:195], off
	s_waitcnt vmcnt(8)
	s_waitcnt lgkmcnt(0)
	s_barrier
	s_setprio 1
	s_waitcnt lgkmcnt(0)
	v_mfma_f32_16x16x32_bf16 v[124:127], v[144:147], v[182:185], v[124:127]
	v_mfma_f32_16x16x32_bf16 v[120:123], v[158:161], v[182:185], v[120:123]
	v_mfma_f32_16x16x32_bf16 v[108:111], v[144:147], v[190:193], v[108:111]
	v_mfma_f32_16x16x32_bf16 v[104:107], v[158:161], v[190:193], v[104:107]
	v_mfma_f32_16x16x32_bf16 v[92:95], v[144:147], v[202:205], v[92:95]
	v_mfma_f32_16x16x32_bf16 v[88:91], v[158:161], v[202:205], v[88:91]
	v_mfma_f32_16x16x32_bf16 v[76:79], v[144:147], v[210:213], v[76:79]
	v_mfma_f32_16x16x32_bf16 v[72:75], v[158:161], v[210:213], v[72:75]
	v_mfma_f32_16x16x32_bf16 v[124:127], v[154:157], v[186:189], v[124:127]
	v_mfma_f32_16x16x32_bf16 v[120:123], v[162:165], v[186:189], v[120:123]
	v_mfma_f32_16x16x32_bf16 v[108:111], v[154:157], v[198:201], v[108:111]
	v_mfma_f32_16x16x32_bf16 v[104:107], v[162:165], v[198:201], v[104:107]
	v_mfma_f32_16x16x32_bf16 v[92:95], v[154:157], v[206:209], v[92:95]
	v_mfma_f32_16x16x32_bf16 v[88:91], v[162:165], v[206:209], v[88:91]
	v_mfma_f32_16x16x32_bf16 v[76:79], v[154:157], v[214:217], v[76:79]
	v_mfma_f32_16x16x32_bf16 v[72:75], v[162:165], v[214:217], v[72:75]
	s_setprio 0
	s_setprio 1
	v_mfma_f32_16x16x32_bf16 v[116:119], v[166:169], v[182:185], v[116:119]
	v_mfma_f32_16x16x32_bf16 v[112:115], v[174:177], v[182:185], v[112:115]
	v_mfma_f32_16x16x32_bf16 v[100:103], v[166:169], v[190:193], v[100:103]
	v_mfma_f32_16x16x32_bf16 v[96:99], v[174:177], v[190:193], v[96:99]
	v_mfma_f32_16x16x32_bf16 v[84:87], v[166:169], v[202:205], v[84:87]
	v_mfma_f32_16x16x32_bf16 v[80:83], v[174:177], v[202:205], v[80:83]
	v_mfma_f32_16x16x32_bf16 v[68:71], v[166:169], v[210:213], v[68:71]
	v_mfma_f32_16x16x32_bf16 v[64:67], v[174:177], v[210:213], v[64:67]
	v_mfma_f32_16x16x32_bf16 v[116:119], v[170:173], v[186:189], v[116:119]
	v_mfma_f32_16x16x32_bf16 v[112:115], v[178:181], v[186:189], v[112:115]
	v_mfma_f32_16x16x32_bf16 v[100:103], v[170:173], v[198:201], v[100:103]
	v_mfma_f32_16x16x32_bf16 v[96:99], v[178:181], v[198:201], v[96:99]
	v_mfma_f32_16x16x32_bf16 v[84:87], v[170:173], v[206:209], v[84:87]
	v_mfma_f32_16x16x32_bf16 v[80:83], v[178:181], v[206:209], v[80:83]
	v_mfma_f32_16x16x32_bf16 v[68:71], v[170:173], v[214:217], v[68:71]
	v_mfma_f32_16x16x32_bf16 v[64:67], v[178:181], v[214:217], v[64:67]
	s_setprio 0
	s_barrier
	s_add_i32 s51, s42, s30
	v_lshl_add_u64 v[194:195], s[26:27], 0, v[130:131]
	s_mov_b32 m0, s51
	ds_read_b128 v[182:185], v153 offset:16384
	ds_read_b128 v[186:189], v153 offset:17408
	ds_read_b128 v[190:193], v153 offset:18432
	ds_read_b128 v[198:201], v153 offset:19456
	ds_read_b128 v[202:205], v153 offset:20480
	ds_read_b128 v[206:209], v153 offset:21504
	ds_read_b128 v[210:213], v153 offset:22528
	ds_read_b128 v[214:217], v153 offset:23552
	global_load_lds_dwordx4 v[194:195], off
	s_add_i32 m0, s51, 0x2000
	s_add_u32 s52, s26, 0x40000
	v_lshl_add_u64 v[218:219], s[26:27], 0, v[134:135]
	s_addc_u32 s53, s27, 0
	s_add_i32 s51, s43, s30
	global_load_lds_dwordx4 v[218:219], off
	v_lshl_add_u64 v[220:221], s[52:53], 0, v[130:131]
	s_mov_b32 m0, s51
	v_lshl_add_u64 v[222:223], s[28:29], 0, v[132:133]
	global_load_lds_dwordx4 v[220:221], off
	v_lshl_add_u64 v[220:221], s[52:53], 0, v[134:135]
	s_add_i32 m0, s51, 0x2000
	s_nop 0
	global_load_lds_dwordx4 v[220:221], off
	v_lshl_add_u64 v[220:221], s[28:29], 0, v[128:129]
	s_mov_b32 m0, s23
	s_nop 0
	global_load_lds_dwordx4 v[220:221], off
	s_mov_b32 m0, s34
	s_nop 0
	global_load_lds_dwordx4 v[222:223], off
	s_waitcnt vmcnt(8)
	s_waitcnt lgkmcnt(0)
	s_barrier
; #define PG8_STAGE(bufoff, gbase, voff) do { _Pragma("unroll") for (int _i = 0; _i < 2; ++_i) \
;         __builtin_amdgcn_global_load_lds((const unsigned*)((const char*)(gbase) + (voff)[_i]), (PG8_LAS unsigned*)(lds + (bufoff) + ldsw + _i * 8192), 16, 0, 0); } while (0)
; #define PG8_LDA(dst, b, h) do { _Pragma("unroll") for (int m = 0; m < 4; ++m) _Pragma("unroll") for (int k = 0; k < 2; ++k) dst[m][k] = *(const PG8_LAS bf16x8*)(lds + PG8_SA(b, h) + aoff + m * 2048 + k * 1024); } while (0)
; #define PG8_LDB(dst, b, h) do { _Pragma("unroll") for (int n = 0; n < 2; ++n) _Pragma("unroll") for (int k = 0; k < 2; ++k) dst[n][k] = *(const PG8_LAS bf16x8*)(lds + PG8_SB(b, h) + boff + n * 2048 + k * 1024); } while (0)
; #define PG8_MMA(ai, bj, At, Bt) do { __builtin_amdgcn_s_setprio(1); _Pragma("unroll") for (int m = 0; m < 4; ++m) _Pragma("unroll") for (int n = 0; n < 2; ++n) _Pragma("unroll") for (int k = 0; k < 2; ++k) \
;         acc[ai][bj][m][n] = __builtin_amdgcn_mfma_f32_16x16x32_bf16(Bt[n][k], At[m][k], acc[ai][bj][m][n], 0, 0, 0); __builtin_amdgcn_s_setprio(0); } while (0)
; #define PG8_WAIT_V(n) asm volatile("s_waitcnt vmcnt(" #n ")" ::: "memory")
; #define PG8_WAIT_L(n) asm volatile("s_waitcnt lgkmcnt(" #n ")" ::: "memory")
; #define PG8_BAR __builtin_amdgcn_s_barrier()
; #define PG8_SCHED __builtin_amdgcn_sched_barrier(0)
; template <class Epi, class Sched, bool ALIGN_EPI = false, bool SP2 = false>
; __device__ __forceinline__ void gemm_phase(PG8_LAS unsigned char* lds, const Gemm g, const Sched& S, const Epi& E) {
;     ...
;             PG8_WAIT_V(8); PG8_WAIT_L(0); PG8_BAR; PG8_MMA(1, 0, At, B0); PG8_MMA(1, 1, At, B1); PG8_BAR; PG8_SCHED;
;             PG8_LDB(B0, 1, 0); PG8_LDB(B1, 1, 1); PG8_SCHED; PG8_LDA(At, 1, 0); PG8_STAGE(PG8_SA(0, 1), a2 + hstep, voffA);
;             PG8_WAIT_V(8); PG8_WAIT_L(0); PG8_BAR; PG8_MMA(0, 0, At, B0); PG8_MMA(0, 1, At, B1); PG8_BAR; PG8_SCHED;
	s_setprio 1
	s_waitcnt lgkmcnt(0)
	v_mfma_f32_16x16x32_bf16 v[60:63], v[144:147], v[182:185], v[60:63]
	v_mfma_f32_16x16x32_bf16 v[56:59], v[158:161], v[182:185], v[56:59]
	v_mfma_f32_16x16x32_bf16 v[44:47], v[144:147], v[190:193], v[44:47]
	v_mfma_f32_16x16x32_bf16 v[40:43], v[158:161], v[190:193], v[40:43]
	v_mfma_f32_16x16x32_bf16 v[28:31], v[144:147], v[202:205], v[28:31]
	v_mfma_f32_16x16x32_bf16 v[24:27], v[158:161], v[202:205], v[24:27]
	v_mfma_f32_16x16x32_bf16 v[12:15], v[144:147], v[210:213], v[12:15]
	v_mfma_f32_16x16x32_bf16 v[8:11], v[158:161], v[210:213], v[8:11]
	v_mfma_f32_16x16x32_bf16 v[60:63], v[154:157], v[186:189], v[60:63]
	v_mfma_f32_16x16x32_bf16 v[56:59], v[162:165], v[186:189], v[56:59]
	v_mfma_f32_16x16x32_bf16 v[44:47], v[154:157], v[198:201], v[44:47]
	v_mfma_f32_16x16x32_bf16 v[40:43], v[162:165], v[198:201], v[40:43]
	v_mfma_f32_16x16x32_bf16 v[28:31], v[154:157], v[206:209], v[28:31]
	v_mfma_f32_16x16x32_bf16 v[24:27], v[162:165], v[206:209], v[24:27]
	v_mfma_f32_16x16x32_bf16 v[12:15], v[154:157], v[214:217], v[12:15]
	v_mfma_f32_16x16x32_bf16 v[8:11], v[162:165], v[214:217], v[8:11]
	s_setprio 0
	s_setprio 1
	v_mfma_f32_16x16x32_bf16 v[52:55], v[166:169], v[182:185], v[52:55]
	v_mfma_f32_16x16x32_bf16 v[48:51], v[174:177], v[182:185], v[48:51]
	v_mfma_f32_16x16x32_bf16 v[36:39], v[166:169], v[190:193], v[36:39]
	v_mfma_f32_16x16x32_bf16 v[32:35], v[174:177], v[190:193], v[32:35]
	v_mfma_f32_16x16x32_bf16 v[20:23], v[166:169], v[202:205], v[20:23]
	v_mfma_f32_16x16x32_bf16 v[16:19], v[174:177], v[202:205], v[16:19]
	v_mfma_f32_16x16x32_bf16 v[4:7], v[166:169], v[210:213], v[4:7]
	v_mfma_f32_16x16x32_bf16 v[0:3], v[174:177], v[210:213], v[0:3]
	v_mfma_f32_16x16x32_bf16 v[52:55], v[170:173], v[186:189], v[52:55]
	v_mfma_f32_16x16x32_bf16 v[48:51], v[178:181], v[186:189], v[48:51]
	v_mfma_f32_16x16x32_bf16 v[36:39], v[170:173], v[198:201], v[36:39]
	v_mfma_f32_16x16x32_bf16 v[32:35], v[178:181], v[198:201], v[32:35]
	v_mfma_f32_16x16x32_bf16 v[20:23], v[170:173], v[206:209], v[20:23]
	v_mfma_f32_16x16x32_bf16 v[16:19], v[178:181], v[206:209], v[16:19]
	v_mfma_f32_16x16x32_bf16 v[4:7], v[170:173], v[214:217], v[4:7]
	v_mfma_f32_16x16x32_bf16 v[0:3], v[178:181], v[214:217], v[0:3]
	s_setprio 0
	s_barrier
	s_add_i32 s51, 0, 0x18000
	s_add_i32 s52, 0, 0x1c000
	v_add_u32_e32 v162, s51, v149
	v_add_u32_e32 v178, s52, v149
	ds_read_b128 v[144:147], v162
	ds_read_b128 v[154:157], v162 offset:1024
	ds_read_b128 v[158:161], v162 offset:2048
	ds_read_b128 v[162:165], v162 offset:3072
	ds_read_b128 v[166:169], v178
	ds_read_b128 v[170:173], v178 offset:1024
	ds_read_b128 v[174:177], v178 offset:2048
	ds_read_b128 v[178:181], v178 offset:3072
	s_add_u32 s28, s28, 0x40000
	s_addc_u32 s29, s29, 0
	s_mov_b32 m0, s35
	v_lshl_add_u64 v[224:225], s[28:29], 0, v[128:129]
	ds_read_b128 v[182:185], v153 offset:32768
	ds_read_b128 v[186:189], v153 offset:33792
	ds_read_b128 v[190:193], v153 offset:34816
	ds_read_b128 v[198:201], v153 offset:35840
	ds_read_b128 v[202:205], v153 offset:36864
	ds_read_b128 v[206:209], v153 offset:37888
	ds_read_b128 v[210:213], v153 offset:38912
	ds_read_b128 v[214:217], v153 offset:39936
	global_load_lds_dwordx4 v[224:225], off
	v_lshl_add_u64 v[224:225], s[28:29], 0, v[132:133]
	s_mov_b32 m0, s36
	s_nop 0
	global_load_lds_dwordx4 v[224:225], off
	s_waitcnt vmcnt(8)
	s_waitcnt lgkmcnt(0)
	s_barrier
	s_setprio 1
	s_waitcnt lgkmcnt(0)
	v_mfma_f32_16x16x32_bf16 v[124:127], v[144:147], v[182:185], v[124:127]
	v_mfma_f32_16x16x32_bf16 v[120:123], v[158:161], v[182:185], v[120:123]
	v_mfma_f32_16x16x32_bf16 v[108:111], v[144:147], v[190:193], v[108:111]
	v_mfma_f32_16x16x32_bf16 v[104:107], v[158:161], v[190:193], v[104:107]
	v_mfma_f32_16x16x32_bf16 v[92:95], v[144:147], v[202:205], v[92:95]
	v_mfma_f32_16x16x32_bf16 v[88:91], v[158:161], v[202:205], v[88:91]
	v_mfma_f32_16x16x32_bf16 v[76:79], v[144:147], v[210:213], v[76:79]
	v_mfma_f32_16x16x32_bf16 v[72:75], v[158:161], v[210:213], v[72:75]
	v_mfma_f32_16x16x32_bf16 v[124:127], v[154:157], v[186:189], v[124:127]
	v_mfma_f32_16x16x32_bf16 v[120:123], v[162:165], v[186:189], v[120:123]
	v_mfma_f32_16x16x32_bf16 v[108:111], v[154:157], v[198:201], v[108:111]
	v_mfma_f32_16x16x32_bf16 v[104:107], v[162:165], v[198:201], v[104:107]
	v_mfma_f32_16x16x32_bf16 v[92:95], v[154:157], v[206:209], v[92:95]
	v_mfma_f32_16x16x32_bf16 v[88:91], v[162:165], v[206:209], v[88:91]
	v_mfma_f32_16x16x32_bf16 v[76:79], v[154:157], v[214:217], v[76:79]
	v_mfma_f32_16x16x32_bf16 v[72:75], v[162:165], v[214:217], v[72:75]
	s_setprio 0
	s_setprio 1
	v_mfma_f32_16x16x32_bf16 v[116:119], v[166:169], v[182:185], v[116:119]
	v_mfma_f32_16x16x32_bf16 v[112:115], v[174:177], v[182:185], v[112:115]
	v_mfma_f32_16x16x32_bf16 v[100:103], v[166:169], v[190:193], v[100:103]
	v_mfma_f32_16x16x32_bf16 v[96:99], v[174:177], v[190:193], v[96:99]
	v_mfma_f32_16x16x32_bf16 v[84:87], v[166:169], v[202:205], v[84:87]
	v_mfma_f32_16x16x32_bf16 v[80:83], v[174:177], v[202:205], v[80:83]
	v_mfma_f32_16x16x32_bf16 v[68:71], v[166:169], v[210:213], v[68:71]
	v_mfma_f32_16x16x32_bf16 v[64:67], v[174:177], v[210:213], v[64:67]
	v_mfma_f32_16x16x32_bf16 v[116:119], v[170:173], v[186:189], v[116:119]
	v_mfma_f32_16x16x32_bf16 v[112:115], v[178:181], v[186:189], v[112:115]
	v_mfma_f32_16x16x32_bf16 v[100:103], v[170:173], v[198:201], v[100:103]
	v_mfma_f32_16x16x32_bf16 v[96:99], v[178:181], v[198:201], v[96:99]
	v_mfma_f32_16x16x32_bf16 v[84:87], v[170:173], v[206:209], v[84:87]
	v_mfma_f32_16x16x32_bf16 v[80:83], v[178:181], v[206:209], v[80:83]
	v_mfma_f32_16x16x32_bf16 v[68:71], v[170:173], v[214:217], v[68:71]
	v_mfma_f32_16x16x32_bf16 v[64:67], v[178:181], v[214:217], v[64:67]
	s_setprio 0
	s_barrier
; #define PG8_STAGE(bufoff, gbase, voff) do { _Pragma("unroll") for (int _i = 0; _i < 2; ++_i) \
;         __builtin_amdgcn_global_load_lds((const unsigned*)((const char*)(gbase) + (voff)[_i]), (PG8_LAS unsigned*)(lds + (bufoff) + ldsw + _i * 8192), 16, 0, 0); } while (0)
; #define PG8_LDA(dst, b, h) do { _Pragma("unroll") for (int m = 0; m < 4; ++m) _Pragma("unroll") for (int k = 0; k < 2; ++k) dst[m][k] = *(const PG8_LAS bf16x8*)(lds + PG8_SA(b, h) + aoff + m * 2048 + k * 1024); } while (0)
; #define PG8_MMA(ai, bj, At, Bt) do { __builtin_amdgcn_s_setprio(1); _Pragma("unroll") for (int m = 0; m < 4; ++m) _Pragma("unroll") for (int n = 0; n < 2; ++n) _Pragma("unroll") for (int k = 0; k < 2; ++k) \
;         acc[ai][bj][m][n] = __builtin_amdgcn_mfma_f32_16x16x32_bf16(Bt[n][k], At[m][k], acc[ai][bj][m][n], 0, 0, 0); __builtin_amdgcn_s_setprio(0); } while (0)
; #define PG8_WAIT_V(n) asm volatile("s_waitcnt vmcnt(" #n ")" ::: "memory")
; #define PG8_WAIT_L(n) asm volatile("s_waitcnt lgkmcnt(" #n ")" ::: "memory")
; #define PG8_BAR __builtin_amdgcn_s_barrier()
; #define PG8_SCHED __builtin_amdgcn_sched_barrier(0)
; template <class Epi, class Sched, bool ALIGN_EPI = false, bool SP2 = false>
; __device__ __forceinline__ void gemm_phase(PG8_LAS unsigned char* lds, const Gemm g, const Sched& S, const Epi& E) {
;     ...
;         for (int t = 0; t < nt; t += 2) {
;     ...
;             PG8_LDA(At, 1, 1); PG8_STAGE(PG8_SB(1, 0), b3, voffB); PG8_STAGE(PG8_SB(1, 1), b3 + hstep, voffB); PG8_STAGE(PG8_SA(1, 0), a3, voffA);
;             PG8_WAIT_V(8); PG8_WAIT_L(0); PG8_BAR; PG8_MMA(1, 0, At, B0); PG8_MMA(1, 1, At, B1); PG8_BAR; PG8_SCHED;
	s_add_i32 s28, s51, s30
	v_lshl_add_u64 v[194:195], v[194:195], 0, s[10:11]
	s_mov_b32 m0, s28
	ds_read_b128 v[182:185], v153 offset:49152
	ds_read_b128 v[186:189], v153 offset:50176
	ds_read_b128 v[190:193], v153 offset:51200
	ds_read_b128 v[198:201], v153 offset:52224
	ds_read_b128 v[202:205], v153 offset:53248
	ds_read_b128 v[206:209], v153 offset:54272
	ds_read_b128 v[210:213], v153 offset:55296
	ds_read_b128 v[214:217], v153 offset:56320
	global_load_lds_dwordx4 v[194:195], off
	s_add_i32 m0, s28, 0x2000
	s_add_u32 s26, s26, 0x40080
	v_lshl_add_u64 v[194:195], v[218:219], 0, s[10:11]
	s_addc_u32 s27, s27, 0
	s_add_i32 s28, s52, s30
	global_load_lds_dwordx4 v[194:195], off
	v_lshl_add_u64 v[194:195], s[26:27], 0, v[130:131]
	s_mov_b32 m0, s28
	s_nop 0
	global_load_lds_dwordx4 v[194:195], off
	v_lshl_add_u64 v[194:195], s[26:27], 0, v[134:135]
	s_add_i32 m0, s28, 0x2000
	s_nop 0
	global_load_lds_dwordx4 v[194:195], off
	v_lshl_add_u64 v[194:195], v[220:221], 0, s[10:11]
	s_mov_b32 m0, s39
	s_nop 0
	global_load_lds_dwordx4 v[194:195], off
	v_lshl_add_u64 v[194:195], v[222:223], 0, s[10:11]
	s_mov_b32 m0, s40
	s_nop 0
	global_load_lds_dwordx4 v[194:195], off
	s_waitcnt vmcnt(8)
	s_waitcnt lgkmcnt(0)
	s_barrier
	s_setprio 1
	s_waitcnt lgkmcnt(0)
	v_mfma_f32_16x16x32_bf16 v[60:63], v[144:147], v[182:185], v[60:63]
	v_mfma_f32_16x16x32_bf16 v[56:59], v[158:161], v[182:185], v[56:59]
	v_mfma_f32_16x16x32_bf16 v[44:47], v[144:147], v[190:193], v[44:47]
	v_mfma_f32_16x16x32_bf16 v[40:43], v[158:161], v[190:193], v[40:43]
	v_mfma_f32_16x16x32_bf16 v[28:31], v[144:147], v[202:205], v[28:31]
	v_mfma_f32_16x16x32_bf16 v[24:27], v[158:161], v[202:205], v[24:27]
	v_mfma_f32_16x16x32_bf16 v[12:15], v[144:147], v[210:213], v[12:15]
	v_mfma_f32_16x16x32_bf16 v[8:11], v[158:161], v[210:213], v[8:11]
	v_mfma_f32_16x16x32_bf16 v[60:63], v[154:157], v[186:189], v[60:63]
	v_mfma_f32_16x16x32_bf16 v[56:59], v[162:165], v[186:189], v[56:59]
	v_mfma_f32_16x16x32_bf16 v[44:47], v[154:157], v[198:201], v[44:47]
	v_mfma_f32_16x16x32_bf16 v[40:43], v[162:165], v[198:201], v[40:43]
	v_mfma_f32_16x16x32_bf16 v[28:31], v[154:157], v[206:209], v[28:31]
	v_mfma_f32_16x16x32_bf16 v[24:27], v[162:165], v[206:209], v[24:27]
	v_mfma_f32_16x16x32_bf16 v[12:15], v[154:157], v[214:217], v[12:15]
	v_mfma_f32_16x16x32_bf16 v[8:11], v[162:165], v[214:217], v[8:11]
	s_setprio 0
	s_setprio 1
	v_mfma_f32_16x16x32_bf16 v[52:55], v[166:169], v[182:185], v[52:55]
	v_mfma_f32_16x16x32_bf16 v[48:51], v[174:177], v[182:185], v[48:51]
	v_mfma_f32_16x16x32_bf16 v[36:39], v[166:169], v[190:193], v[36:39]
	v_mfma_f32_16x16x32_bf16 v[32:35], v[174:177], v[190:193], v[32:35]
	v_mfma_f32_16x16x32_bf16 v[20:23], v[166:169], v[202:205], v[20:23]
	v_mfma_f32_16x16x32_bf16 v[16:19], v[174:177], v[202:205], v[16:19]
	v_mfma_f32_16x16x32_bf16 v[4:7], v[166:169], v[210:213], v[4:7]
	v_mfma_f32_16x16x32_bf16 v[0:3], v[174:177], v[210:213], v[0:3]
	v_mfma_f32_16x16x32_bf16 v[52:55], v[170:173], v[186:189], v[52:55]
	v_mfma_f32_16x16x32_bf16 v[48:51], v[178:181], v[186:189], v[48:51]
	v_mfma_f32_16x16x32_bf16 v[36:39], v[170:173], v[198:201], v[36:39]
	v_mfma_f32_16x16x32_bf16 v[32:35], v[178:181], v[198:201], v[32:35]
	v_mfma_f32_16x16x32_bf16 v[20:23], v[170:173], v[206:209], v[20:23]
	v_mfma_f32_16x16x32_bf16 v[16:19], v[178:181], v[206:209], v[16:19]
	v_mfma_f32_16x16x32_bf16 v[4:7], v[170:173], v[214:217], v[4:7]
	v_mfma_f32_16x16x32_bf16 v[0:3], v[178:181], v[214:217], v[0:3]
	s_setprio 0
	s_add_i32 s50, s50, 2
	s_add_u32 s24, s24, 0x100
	s_addc_u32 s25, s25, 0
	s_add_u32 s48, s48, 0x100
	s_addc_u32 s49, s49, 0
	s_cmp_gt_u32 s50, 13
	s_barrier
	s_cbranch_scc0 .LBB0_293
	s_and_b64 vcc, exec, s[12:13]
	s_cbranch_vccz .LBB0_296
	s_barrier

; #define PG8_STAGE(bufoff, gbase, voff) do { _Pragma("unroll") for (int _i = 0; _i < 2; ++_i) \
;         __builtin_amdgcn_global_load_lds((const unsigned*)((const char*)(gbase) + (voff)[_i]), (PG8_LAS unsigned*)(lds + (bufoff) + ldsw + _i * 8192), 16, 0, 0); } while (0)
; #define PG8_LDA(dst, b, h) do { _Pragma("unroll") for (int m = 0; m < 4; ++m) _Pragma("unroll") for (int k = 0; k < 2; ++k) dst[m][k] = *(const PG8_LAS bf16x8*)(lds + PG8_SA(b, h) + aoff + m * 2048 + k * 1024); } while (0)
; #define PG8_LDB(dst, b, h) do { _Pragma("unroll") for (int n = 0; n < 2; ++n) _Pragma("unroll") for (int k = 0; k < 2; ++k) dst[n][k] = *(const PG8_LAS bf16x8*)(lds + PG8_SB(b, h) + boff + n * 2048 + k * 1024); } while (0)
; #define PG8_MMA(ai, bj, At, Bt) do { __builtin_amdgcn_s_setprio(1); _Pragma("unroll") for (int m = 0; m < 4; ++m) _Pragma("unroll") for (int n = 0; n < 2; ++n) _Pragma("unroll") for (int k = 0; k < 2; ++k) \
;         acc[ai][bj][m][n] = __builtin_amdgcn_mfma_f32_16x16x32_bf16(Bt[n][k], At[m][k], acc[ai][bj][m][n], 0, 0, 0); __builtin_amdgcn_s_setprio(0); } while (0)
; #define PG8_WAIT_V(n) asm volatile("s_waitcnt vmcnt(" #n ")" ::: "memory")
; #define PG8_WAIT_L(n) asm volatile("s_waitcnt lgkmcnt(" #n ")" ::: "memory")
; #define PG8_BAR __builtin_amdgcn_s_barrier()
; template <class Epi, class Sched, bool ALIGN_EPI = false, bool SP2 = false>
; __device__ __forceinline__ void gemm_phase(PG8_LAS unsigned char* lds, const Gemm g, const Sched& S, const Epi& E) {
;     ...
;             const char* a1 = cA + (size_t)(t + 1) * kstep;
;             const char* a2 = last ? nA : cA + (size_t)(t + 2) * kstep; const char* b2 = last ? nB : cB + (size_t)(t + 2) * kstep;
;             const char* a3 = a2 + kstep; const char* b3 = b2 + kstep;
;             if (last && has_next) S.a_ready(nxt);
;             if constexpr (SP2) {
;             PG8_LDB(B0, 0, 0); PG8_LDB(B1, 0, 1); PG8_SCHED; PG8_LDA(At, 0, 0); PG8_STAGE(PG8_SA(1, 1), a1 + hstep, voffA);
;             PG8_WAIT_V(8); PG8_WAIT_L(0); PG8_BAR; PG8_MMA(0, 0, At, B0); PG8_MMA(0, 1, At, B1); PG8_BAR; PG8_SCHED;
;             PG8_LDA(At, 0, 1); PG8_STAGE(PG8_SB(0, 0), b2, voffB); PG8_STAGE(PG8_SB(0, 1), b2 + hstep, voffB); PG8_STAGE(PG8_SA(0, 0), a2, voffA);
;             PG8_WAIT_V(8); PG8_WAIT_L(0); PG8_BAR; PG8_MMA(1, 0, At, B0); PG8_MMA(1, 1, At, B1); PG8_BAR; PG8_SCHED;
.LBB0_370:
	ds_read_b128 v[144:147], v151
	ds_read_b128 v[156:159], v151 offset:1024
	ds_read_b128 v[160:163], v151 offset:2048
	ds_read_b128 v[164:167], v151 offset:3072
	ds_read_b128 v[168:171], v152
	ds_read_b128 v[172:175], v152 offset:1024
	ds_read_b128 v[176:179], v152 offset:2048
	ds_read_b128 v[180:183], v152 offset:3072
	s_add_u32 s24, s22, 0xfff50080
	s_addc_u32 s25, s23, -1
	s_cmp_eq_u32 s48, 40
	s_cselect_b32 s27, s5, s25
	s_cselect_b32 s26, s4, s24
	s_cselect_b32 s25, s21, s47
	s_cselect_b32 s24, s20, s46
	v_lshl_add_u64 v[218:219], s[22:23], 0, v[136:137]
	s_add_i32 m0, s29, 0xc000
	ds_read_b128 v[184:187], v153
	ds_read_b128 v[188:191], v153 offset:1024
	ds_read_b128 v[192:195], v153 offset:2048
	ds_read_b128 v[198:201], v153 offset:3072
	ds_read_b128 v[202:205], v153 offset:4096
	ds_read_b128 v[206:209], v153 offset:5120
	ds_read_b128 v[210:213], v153 offset:6144
	ds_read_b128 v[214:217], v153 offset:7168
	global_load_lds_dwordx4 v[218:219], off
	v_lshl_add_u64 v[218:219], s[22:23], 0, v[138:139]
	s_add_i32 m0, s29, 0xe000
	s_nop 0
	global_load_lds_dwordx4 v[218:219], off
	s_waitcnt vmcnt(8)
	s_waitcnt lgkmcnt(0)
	s_barrier
	s_setprio 1
	s_waitcnt lgkmcnt(0)
	v_mfma_f32_16x16x32_bf16 v[124:127], v[144:147], v[184:187], v[124:127]
	v_mfma_f32_16x16x32_bf16 v[120:123], v[160:163], v[184:187], v[120:123]
	v_mfma_f32_16x16x32_bf16 v[108:111], v[144:147], v[192:195], v[108:111]
	v_mfma_f32_16x16x32_bf16 v[104:107], v[160:163], v[192:195], v[104:107]
	v_mfma_f32_16x16x32_bf16 v[92:95], v[144:147], v[202:205], v[92:95]
	v_mfma_f32_16x16x32_bf16 v[88:91], v[160:163], v[202:205], v[88:91]
	v_mfma_f32_16x16x32_bf16 v[76:79], v[144:147], v[210:213], v[76:79]
	v_mfma_f32_16x16x32_bf16 v[72:75], v[160:163], v[210:213], v[72:75]
	v_mfma_f32_16x16x32_bf16 v[124:127], v[156:159], v[188:191], v[124:127]
	v_mfma_f32_16x16x32_bf16 v[120:123], v[164:167], v[188:191], v[120:123]
	v_mfma_f32_16x16x32_bf16 v[108:111], v[156:159], v[198:201], v[108:111]
	v_mfma_f32_16x16x32_bf16 v[104:107], v[164:167], v[198:201], v[104:107]
	v_mfma_f32_16x16x32_bf16 v[92:95], v[156:159], v[206:209], v[92:95]
	v_mfma_f32_16x16x32_bf16 v[88:91], v[164:167], v[206:209], v[88:91]
	v_mfma_f32_16x16x32_bf16 v[76:79], v[156:159], v[214:217], v[76:79]
	v_mfma_f32_16x16x32_bf16 v[72:75], v[164:167], v[214:217], v[72:75]
	s_setprio 0
	s_setprio 1
	v_mfma_f32_16x16x32_bf16 v[116:119], v[168:171], v[184:187], v[116:119]
	v_mfma_f32_16x16x32_bf16 v[112:115], v[176:179], v[184:187], v[112:115]
	v_mfma_f32_16x16x32_bf16 v[100:103], v[168:171], v[192:195], v[100:103]
	v_mfma_f32_16x16x32_bf16 v[96:99], v[176:179], v[192:195], v[96:99]
	v_mfma_f32_16x16x32_bf16 v[84:87], v[168:171], v[202:205], v[84:87]
	v_mfma_f32_16x16x32_bf16 v[80:83], v[176:179], v[202:205], v[80:83]
	v_mfma_f32_16x16x32_bf16 v[68:71], v[168:171], v[210:213], v[68:71]
	v_mfma_f32_16x16x32_bf16 v[64:67], v[176:179], v[210:213], v[64:67]
	v_mfma_f32_16x16x32_bf16 v[116:119], v[172:175], v[188:191], v[116:119]
	v_mfma_f32_16x16x32_bf16 v[112:115], v[180:183], v[188:191], v[112:115]
	v_mfma_f32_16x16x32_bf16 v[100:103], v[172:175], v[198:201], v[100:103]
	v_mfma_f32_16x16x32_bf16 v[96:99], v[180:183], v[198:201], v[96:99]
	v_mfma_f32_16x16x32_bf16 v[84:87], v[172:175], v[206:209], v[84:87]
	v_mfma_f32_16x16x32_bf16 v[80:83], v[180:183], v[206:209], v[80:83]
	v_mfma_f32_16x16x32_bf16 v[68:71], v[172:175], v[214:217], v[68:71]
	v_mfma_f32_16x16x32_bf16 v[64:67], v[180:183], v[214:217], v[64:67]
	s_setprio 0
	s_barrier
	s_add_i32 s49, s40, s28
	v_lshl_add_u64 v[218:219], s[24:25], 0, v[130:131]
	s_mov_b32 m0, s49
	ds_read_b128 v[184:187], v153 offset:16384
	ds_read_b128 v[188:191], v153 offset:17408
	ds_read_b128 v[192:195], v153 offset:18432
	ds_read_b128 v[198:201], v153 offset:19456
	ds_read_b128 v[202:205], v153 offset:20480
	ds_read_b128 v[206:209], v153 offset:21504
	ds_read_b128 v[210:213], v153 offset:22528
	ds_read_b128 v[214:217], v153 offset:23552
	global_load_lds_dwordx4 v[218:219], off
	s_add_i32 m0, s49, 0x2000
	s_add_u32 s50, s24, 0xb0000
	v_lshl_add_u64 v[220:221], s[24:25], 0, v[134:135]
	s_addc_u32 s51, s25, 0
	s_add_i32 s49, s41, s28
	global_load_lds_dwordx4 v[220:221], off
	v_lshl_add_u64 v[222:223], s[50:51], 0, v[130:131]
	s_mov_b32 m0, s49
	v_lshl_add_u64 v[224:225], s[26:27], 0, v[132:133]
	global_load_lds_dwordx4 v[222:223], off
	v_lshl_add_u64 v[222:223], s[50:51], 0, v[134:135]
	s_add_i32 m0, s49, 0x2000
	s_nop 0
	global_load_lds_dwordx4 v[222:223], off
	v_lshl_add_u64 v[222:223], s[26:27], 0, v[128:129]
	s_mov_b32 m0, s29
	s_nop 0
	global_load_lds_dwordx4 v[222:223], off
	s_mov_b32 m0, s30
	s_nop 0
	global_load_lds_dwordx4 v[224:225], off
	s_waitcnt vmcnt(8)
	s_waitcnt lgkmcnt(0)
	s_barrier
; #define PG8_STAGE(bufoff, gbase, voff) do { _Pragma("unroll") for (int _i = 0; _i < 2; ++_i) \
;         __builtin_amdgcn_global_load_lds((const unsigned*)((const char*)(gbase) + (voff)[_i]), (PG8_LAS unsigned*)(lds + (bufoff) + ldsw + _i * 8192), 16, 0, 0); } while (0)
; #define PG8_LDA(dst, b, h) do { _Pragma("unroll") for (int m = 0; m < 4; ++m) _Pragma("unroll") for (int k = 0; k < 2; ++k) dst[m][k] = *(const PG8_LAS bf16x8*)(lds + PG8_SA(b, h) + aoff + m * 2048 + k * 1024); } while (0)
; #define PG8_LDB(dst, b, h) do { _Pragma("unroll") for (int n = 0; n < 2; ++n) _Pragma("unroll") for (int k = 0; k < 2; ++k) dst[n][k] = *(const PG8_LAS bf16x8*)(lds + PG8_SB(b, h) + boff + n * 2048 + k * 1024); } while (0)
; #define PG8_MMA(ai, bj, At, Bt) do { __builtin_amdgcn_s_setprio(1); _Pragma("unroll") for (int m = 0; m < 4; ++m) _Pragma("unroll") for (int n = 0; n < 2; ++n) _Pragma("unroll") for (int k = 0; k < 2; ++k) \
;         acc[ai][bj][m][n] = __builtin_amdgcn_mfma_f32_16x16x32_bf16(Bt[n][k], At[m][k], acc[ai][bj][m][n], 0, 0, 0); __builtin_amdgcn_s_setprio(0); } while (0)
; #define PG8_WAIT_V(n) asm volatile("s_waitcnt vmcnt(" #n ")" ::: "memory")
; #define PG8_WAIT_L(n) asm volatile("s_waitcnt lgkmcnt(" #n ")" ::: "memory")
; #define PG8_BAR __builtin_amdgcn_s_barrier()
; #define PG8_SCHED __builtin_amdgcn_sched_barrier(0)
; template <class Epi, class Sched, bool ALIGN_EPI = false, bool SP2 = false>
; __device__ __forceinline__ void gemm_phase(PG8_LAS unsigned char* lds, const Gemm g, const Sched& S, const Epi& E) {
;     ...
;             PG8_WAIT_V(8); PG8_WAIT_L(0); PG8_BAR; PG8_MMA(1, 0, At, B0); PG8_MMA(1, 1, At, B1); PG8_BAR; PG8_SCHED;
;             PG8_LDB(B0, 1, 0); PG8_LDB(B1, 1, 1); PG8_SCHED; PG8_LDA(At, 1, 0); PG8_STAGE(PG8_SA(0, 1), a2 + hstep, voffA);
;             PG8_WAIT_V(8); PG8_WAIT_L(0); PG8_BAR; PG8_MMA(0, 0, At, B0); PG8_MMA(0, 1, At, B1); PG8_BAR; PG8_SCHED;
	s_setprio 1
	s_waitcnt lgkmcnt(0)
	v_mfma_f32_16x16x32_bf16 v[60:63], v[144:147], v[184:187], v[60:63]
	v_mfma_f32_16x16x32_bf16 v[56:59], v[160:163], v[184:187], v[56:59]
	v_mfma_f32_16x16x32_bf16 v[44:47], v[144:147], v[192:195], v[44:47]
	v_mfma_f32_16x16x32_bf16 v[40:43], v[160:163], v[192:195], v[40:43]
	v_mfma_f32_16x16x32_bf16 v[28:31], v[144:147], v[202:205], v[28:31]
	v_mfma_f32_16x16x32_bf16 v[24:27], v[160:163], v[202:205], v[24:27]
	v_mfma_f32_16x16x32_bf16 v[12:15], v[144:147], v[210:213], v[12:15]
	v_mfma_f32_16x16x32_bf16 v[8:11], v[160:163], v[210:213], v[8:11]
	v_mfma_f32_16x16x32_bf16 v[60:63], v[156:159], v[188:191], v[60:63]
	v_mfma_f32_16x16x32_bf16 v[56:59], v[164:167], v[188:191], v[56:59]
	v_mfma_f32_16x16x32_bf16 v[44:47], v[156:159], v[198:201], v[44:47]
	v_mfma_f32_16x16x32_bf16 v[40:43], v[164:167], v[198:201], v[40:43]
	v_mfma_f32_16x16x32_bf16 v[28:31], v[156:159], v[206:209], v[28:31]
	v_mfma_f32_16x16x32_bf16 v[24:27], v[164:167], v[206:209], v[24:27]
	v_mfma_f32_16x16x32_bf16 v[12:15], v[156:159], v[214:217], v[12:15]
	v_mfma_f32_16x16x32_bf16 v[8:11], v[164:167], v[214:217], v[8:11]
	s_setprio 0
	s_setprio 1
	v_mfma_f32_16x16x32_bf16 v[52:55], v[168:171], v[184:187], v[52:55]
	v_mfma_f32_16x16x32_bf16 v[48:51], v[176:179], v[184:187], v[48:51]
	v_mfma_f32_16x16x32_bf16 v[36:39], v[168:171], v[192:195], v[36:39]
	v_mfma_f32_16x16x32_bf16 v[32:35], v[176:179], v[192:195], v[32:35]
	v_mfma_f32_16x16x32_bf16 v[20:23], v[168:171], v[202:205], v[20:23]
	v_mfma_f32_16x16x32_bf16 v[16:19], v[176:179], v[202:205], v[16:19]
	v_mfma_f32_16x16x32_bf16 v[4:7], v[168:171], v[210:213], v[4:7]
	v_mfma_f32_16x16x32_bf16 v[0:3], v[176:179], v[210:213], v[0:3]
	v_mfma_f32_16x16x32_bf16 v[52:55], v[172:175], v[188:191], v[52:55]
	v_mfma_f32_16x16x32_bf16 v[48:51], v[180:183], v[188:191], v[48:51]
	v_mfma_f32_16x16x32_bf16 v[36:39], v[172:175], v[198:201], v[36:39]
	v_mfma_f32_16x16x32_bf16 v[32:35], v[180:183], v[198:201], v[32:35]
	v_mfma_f32_16x16x32_bf16 v[20:23], v[172:175], v[206:209], v[20:23]
	v_mfma_f32_16x16x32_bf16 v[16:19], v[180:183], v[206:209], v[16:19]
	v_mfma_f32_16x16x32_bf16 v[4:7], v[172:175], v[214:217], v[4:7]
	v_mfma_f32_16x16x32_bf16 v[0:3], v[180:183], v[214:217], v[0:3]
	s_setprio 0
	s_barrier
	s_add_i32 s49, 0, 0x18000
	v_add_u32_e32 v155, s49, v149
	s_add_i32 s50, 0, 0x1c000
	ds_read_b128 v[144:147], v155
	ds_read_b128 v[156:159], v155 offset:1024
	ds_read_b128 v[160:163], v155 offset:2048
	ds_read_b128 v[164:167], v155 offset:3072
	v_add_u32_e32 v155, s50, v149
	ds_read_b128 v[168:171], v155
	ds_read_b128 v[172:175], v155 offset:1024
	ds_read_b128 v[176:179], v155 offset:2048
	ds_read_b128 v[180:183], v155 offset:3072
	s_add_u32 s26, s26, 0xb0000
	s_addc_u32 s27, s27, 0
	s_mov_b32 m0, s31
	v_lshl_add_u64 v[226:227], s[26:27], 0, v[128:129]
	ds_read_b128 v[184:187], v153 offset:32768
	ds_read_b128 v[188:191], v153 offset:33792
	ds_read_b128 v[192:195], v153 offset:34816
	ds_read_b128 v[198:201], v153 offset:35840
	ds_read_b128 v[202:205], v153 offset:36864
	ds_read_b128 v[206:209], v153 offset:37888
	ds_read_b128 v[210:213], v153 offset:38912
	ds_read_b128 v[214:217], v153 offset:39936
	global_load_lds_dwordx4 v[226:227], off
	v_lshl_add_u64 v[226:227], s[26:27], 0, v[132:133]
	s_mov_b32 m0, s33
	s_nop 0
	global_load_lds_dwordx4 v[226:227], off
	s_waitcnt vmcnt(8)
	s_waitcnt lgkmcnt(0)
	s_barrier
	s_setprio 1
	s_waitcnt lgkmcnt(0)
	v_mfma_f32_16x16x32_bf16 v[124:127], v[144:147], v[184:187], v[124:127]
	v_mfma_f32_16x16x32_bf16 v[120:123], v[160:163], v[184:187], v[120:123]
	v_mfma_f32_16x16x32_bf16 v[108:111], v[144:147], v[192:195], v[108:111]
	v_mfma_f32_16x16x32_bf16 v[104:107], v[160:163], v[192:195], v[104:107]
	v_mfma_f32_16x16x32_bf16 v[92:95], v[144:147], v[202:205], v[92:95]
	v_mfma_f32_16x16x32_bf16 v[88:91], v[160:163], v[202:205], v[88:91]
	v_mfma_f32_16x16x32_bf16 v[76:79], v[144:147], v[210:213], v[76:79]
	v_mfma_f32_16x16x32_bf16 v[72:75], v[160:163], v[210:213], v[72:75]
	v_mfma_f32_16x16x32_bf16 v[124:127], v[156:159], v[188:191], v[124:127]
	v_mfma_f32_16x16x32_bf16 v[120:123], v[164:167], v[188:191], v[120:123]
	v_mfma_f32_16x16x32_bf16 v[108:111], v[156:159], v[198:201], v[108:111]
	v_mfma_f32_16x16x32_bf16 v[104:107], v[164:167], v[198:201], v[104:107]
	v_mfma_f32_16x16x32_bf16 v[92:95], v[156:159], v[206:209], v[92:95]
	v_mfma_f32_16x16x32_bf16 v[88:91], v[164:167], v[206:209], v[88:91]
	v_mfma_f32_16x16x32_bf16 v[76:79], v[156:159], v[214:217], v[76:79]
	v_mfma_f32_16x16x32_bf16 v[72:75], v[164:167], v[214:217], v[72:75]
	s_setprio 0
	s_setprio 1
	v_mfma_f32_16x16x32_bf16 v[116:119], v[168:171], v[184:187], v[116:119]
	v_mfma_f32_16x16x32_bf16 v[112:115], v[176:179], v[184:187], v[112:115]
	v_mfma_f32_16x16x32_bf16 v[100:103], v[168:171], v[192:195], v[100:103]
	v_mfma_f32_16x16x32_bf16 v[96:99], v[176:179], v[192:195], v[96:99]
	v_mfma_f32_16x16x32_bf16 v[84:87], v[168:171], v[202:205], v[84:87]
	v_mfma_f32_16x16x32_bf16 v[80:83], v[176:179], v[202:205], v[80:83]
	v_mfma_f32_16x16x32_bf16 v[68:71], v[168:171], v[210:213], v[68:71]
	v_mfma_f32_16x16x32_bf16 v[64:67], v[176:179], v[210:213], v[64:67]
	v_mfma_f32_16x16x32_bf16 v[116:119], v[172:175], v[188:191], v[116:119]
	v_mfma_f32_16x16x32_bf16 v[112:115], v[180:183], v[188:191], v[112:115]
	v_mfma_f32_16x16x32_bf16 v[100:103], v[172:175], v[198:201], v[100:103]
	v_mfma_f32_16x16x32_bf16 v[96:99], v[180:183], v[198:201], v[96:99]
	v_mfma_f32_16x16x32_bf16 v[84:87], v[172:175], v[206:209], v[84:87]
	v_mfma_f32_16x16x32_bf16 v[80:83], v[180:183], v[206:209], v[80:83]
	v_mfma_f32_16x16x32_bf16 v[68:71], v[172:175], v[214:217], v[68:71]
	v_mfma_f32_16x16x32_bf16 v[64:67], v[180:183], v[214:217], v[64:67]
	s_setprio 0
	s_barrier
; #define PG8_STAGE(bufoff, gbase, voff) do { _Pragma("unroll") for (int _i = 0; _i < 2; ++_i) \
;         __builtin_amdgcn_global_load_lds((const unsigned*)((const char*)(gbase) + (voff)[_i]), (PG8_LAS unsigned*)(lds + (bufoff) + ldsw + _i * 8192), 16, 0, 0); } while (0)
; #define PG8_LDA(dst, b, h) do { _Pragma("unroll") for (int m = 0; m < 4; ++m) _Pragma("unroll") for (int k = 0; k < 2; ++k) dst[m][k] = *(const PG8_LAS bf16x8*)(lds + PG8_SA(b, h) + aoff + m * 2048 + k * 1024); } while (0)
; #define PG8_MMA(ai, bj, At, Bt) do { __builtin_amdgcn_s_setprio(1); _Pragma("unroll") for (int m = 0; m < 4; ++m) _Pragma("unroll") for (int n = 0; n < 2; ++n) _Pragma("unroll") for (int k = 0; k < 2; ++k) \
;         acc[ai][bj][m][n] = __builtin_amdgcn_mfma_f32_16x16x32_bf16(Bt[n][k], At[m][k], acc[ai][bj][m][n], 0, 0, 0); __builtin_amdgcn_s_setprio(0); } while (0)
; #define PG8_WAIT_V(n) asm volatile("s_waitcnt vmcnt(" #n ")" ::: "memory")
; #define PG8_WAIT_L(n) asm volatile("s_waitcnt lgkmcnt(" #n ")" ::: "memory")
; #define PG8_BAR __builtin_amdgcn_s_barrier()
; #define PG8_SCHED __builtin_amdgcn_sched_barrier(0)
; template <class Epi, class Sched, bool ALIGN_EPI = false, bool SP2 = false>
; __device__ __forceinline__ void gemm_phase(PG8_LAS unsigned char* lds, const Gemm g, const Sched& S, const Epi& E) {
;     ...
;             PG8_LDA(At, 1, 1); PG8_STAGE(PG8_SB(1, 0), b3, voffB); PG8_STAGE(PG8_SB(1, 1), b3 + hstep, voffB); PG8_STAGE(PG8_SA(1, 0), a3, voffA);
;             PG8_WAIT_V(8); PG8_WAIT_L(0); PG8_BAR; PG8_MMA(1, 0, At, B0); PG8_MMA(1, 1, At, B1); PG8_BAR; PG8_SCHED;
;     ...
;         if constexpr (ALIGN_EPI) { if (wr == 0) PG8_BAR; }
	s_add_i32 s26, s49, s28
	v_lshl_add_u64 v[218:219], v[218:219], 0, s[16:17]
	s_mov_b32 m0, s26
	ds_read_b128 v[184:187], v153 offset:49152
	ds_read_b128 v[188:191], v153 offset:50176
	ds_read_b128 v[192:195], v153 offset:51200
	ds_read_b128 v[198:201], v153 offset:52224
	ds_read_b128 v[202:205], v153 offset:53248
	ds_read_b128 v[206:209], v153 offset:54272
	ds_read_b128 v[210:213], v153 offset:55296
	ds_read_b128 v[214:217], v153 offset:56320
	global_load_lds_dwordx4 v[218:219], off
	s_add_i32 m0, s26, 0x2000
	s_add_u32 s24, s24, 0xb0080
	v_lshl_add_u64 v[218:219], v[220:221], 0, s[16:17]
	s_addc_u32 s25, s25, 0
	s_add_i32 s26, s50, s28
	global_load_lds_dwordx4 v[218:219], off
	v_lshl_add_u64 v[218:219], s[24:25], 0, v[130:131]
	s_mov_b32 m0, s26
	s_nop 0
	global_load_lds_dwordx4 v[218:219], off
	v_lshl_add_u64 v[218:219], s[24:25], 0, v[134:135]
	s_add_i32 m0, s26, 0x2000
	s_nop 0
	global_load_lds_dwordx4 v[218:219], off
	v_lshl_add_u64 v[218:219], v[222:223], 0, s[16:17]
	s_mov_b32 m0, s37
	s_nop 0
	global_load_lds_dwordx4 v[218:219], off
	v_lshl_add_u64 v[218:219], v[224:225], 0, s[16:17]
	s_mov_b32 m0, s38
	s_nop 0
	global_load_lds_dwordx4 v[218:219], off
	s_waitcnt vmcnt(8)
	s_waitcnt lgkmcnt(0)
	s_barrier
	s_setprio 1
	s_waitcnt lgkmcnt(0)
	v_mfma_f32_16x16x32_bf16 v[60:63], v[144:147], v[184:187], v[60:63]
	v_mfma_f32_16x16x32_bf16 v[56:59], v[160:163], v[184:187], v[56:59]
	v_mfma_f32_16x16x32_bf16 v[44:47], v[144:147], v[192:195], v[44:47]
	v_mfma_f32_16x16x32_bf16 v[40:43], v[160:163], v[192:195], v[40:43]
	v_mfma_f32_16x16x32_bf16 v[28:31], v[144:147], v[202:205], v[28:31]
	v_mfma_f32_16x16x32_bf16 v[24:27], v[160:163], v[202:205], v[24:27]
	v_mfma_f32_16x16x32_bf16 v[12:15], v[144:147], v[210:213], v[12:15]
	v_mfma_f32_16x16x32_bf16 v[8:11], v[160:163], v[210:213], v[8:11]
	v_mfma_f32_16x16x32_bf16 v[60:63], v[156:159], v[188:191], v[60:63]
	v_mfma_f32_16x16x32_bf16 v[56:59], v[164:167], v[188:191], v[56:59]
	v_mfma_f32_16x16x32_bf16 v[44:47], v[156:159], v[198:201], v[44:47]
	v_mfma_f32_16x16x32_bf16 v[40:43], v[164:167], v[198:201], v[40:43]
	v_mfma_f32_16x16x32_bf16 v[28:31], v[156:159], v[206:209], v[28:31]
	v_mfma_f32_16x16x32_bf16 v[24:27], v[164:167], v[206:209], v[24:27]
	v_mfma_f32_16x16x32_bf16 v[12:15], v[156:159], v[214:217], v[12:15]
	v_mfma_f32_16x16x32_bf16 v[8:11], v[164:167], v[214:217], v[8:11]
	s_setprio 0
	s_setprio 1
	v_mfma_f32_16x16x32_bf16 v[52:55], v[168:171], v[184:187], v[52:55]
	v_mfma_f32_16x16x32_bf16 v[48:51], v[176:179], v[184:187], v[48:51]
	v_mfma_f32_16x16x32_bf16 v[36:39], v[168:171], v[192:195], v[36:39]
	v_mfma_f32_16x16x32_bf16 v[32:35], v[176:179], v[192:195], v[32:35]
	v_mfma_f32_16x16x32_bf16 v[20:23], v[168:171], v[202:205], v[20:23]
	v_mfma_f32_16x16x32_bf16 v[16:19], v[176:179], v[202:205], v[16:19]
	v_mfma_f32_16x16x32_bf16 v[4:7], v[168:171], v[210:213], v[4:7]
	v_mfma_f32_16x16x32_bf16 v[0:3], v[176:179], v[210:213], v[0:3]
	v_mfma_f32_16x16x32_bf16 v[52:55], v[172:175], v[188:191], v[52:55]
	v_mfma_f32_16x16x32_bf16 v[48:51], v[180:183], v[188:191], v[48:51]
	v_mfma_f32_16x16x32_bf16 v[36:39], v[172:175], v[198:201], v[36:39]
	v_mfma_f32_16x16x32_bf16 v[32:35], v[180:183], v[198:201], v[32:35]
	v_mfma_f32_16x16x32_bf16 v[20:23], v[172:175], v[206:209], v[20:23]
	v_mfma_f32_16x16x32_bf16 v[16:19], v[180:183], v[206:209], v[16:19]
	v_mfma_f32_16x16x32_bf16 v[4:7], v[172:175], v[214:217], v[4:7]
	v_mfma_f32_16x16x32_bf16 v[0:3], v[180:183], v[214:217], v[0:3]
	s_setprio 0
	s_add_i32 s48, s48, 2
	s_add_u32 s22, s22, 0x100
	s_addc_u32 s23, s23, 0
	s_add_u32 s46, s46, 0x100
	s_addc_u32 s47, s47, 0
	s_cmp_gt_u32 s48, 41
	s_barrier
	s_cbranch_scc0 .LBB0_370
	s_and_b64 vcc, exec, s[18:19]
	s_cbranch_vccz .LBB0_373
	s_barrier

; #define PG8_STAGE(bufoff, gbase, voff) do { _Pragma("unroll") for (int _i = 0; _i < 2; ++_i) \
;         __builtin_amdgcn_global_load_lds((const unsigned*)((const char*)(gbase) + (voff)[_i]), (PG8_LAS unsigned*)(lds + (bufoff) + ldsw + _i * 8192), 16, 0, 0); } while (0)
; #define PG8_LDA(dst, b, h) do { _Pragma("unroll") for (int m = 0; m < 4; ++m) _Pragma("unroll") for (int k = 0; k < 2; ++k) dst[m][k] = *(const PG8_LAS bf16x8*)(lds + PG8_SA(b, h) + aoff + m * 2048 + k * 1024); } while (0)
; #define PG8_LDB(dst, b, h) do { _Pragma("unroll") for (int n = 0; n < 2; ++n) _Pragma("unroll") for (int k = 0; k < 2; ++k) dst[n][k] = *(const PG8_LAS bf16x8*)(lds + PG8_SB(b, h) + boff + n * 2048 + k * 1024); } while (0)
; #define PG8_MMA(ai, bj, At, Bt) do { __builtin_amdgcn_s_setprio(1); _Pragma("unroll") for (int m = 0; m < 4; ++m) _Pragma("unroll") for (int n = 0; n < 2; ++n) _Pragma("unroll") for (int k = 0; k < 2; ++k) \
;         acc[ai][bj][m][n] = __builtin_amdgcn_mfma_f32_16x16x32_bf16(Bt[n][k], At[m][k], acc[ai][bj][m][n], 0, 0, 0); __builtin_amdgcn_s_setprio(0); } while (0)
; #define PG8_WAIT_V(n) asm volatile("s_waitcnt vmcnt(" #n ")" ::: "memory")
; #define PG8_WAIT_L(n) asm volatile("s_waitcnt lgkmcnt(" #n ")" ::: "memory")
; #define PG8_BAR __builtin_amdgcn_s_barrier()
; template <class Epi, class Sched, bool ALIGN_EPI = false, bool SP2 = false>
; __device__ __forceinline__ void gemm_phase(PG8_LAS unsigned char* lds, const Gemm g, const Sched& S, const Epi& E) {
;     ...
;             const char* a1 = cA + (size_t)(t + 1) * kstep;
;             const char* a2 = last ? nA : cA + (size_t)(t + 2) * kstep; const char* b2 = last ? nB : cB + (size_t)(t + 2) * kstep;
;             const char* a3 = a2 + kstep; const char* b3 = b2 + kstep;
;             if (last && has_next) S.a_ready(nxt);
;             if constexpr (SP2) {
;             PG8_LDB(B0, 0, 0); PG8_LDB(B1, 0, 1); PG8_SCHED; PG8_LDA(At, 0, 0); PG8_STAGE(PG8_SA(1, 1), a1 + hstep, voffA);
;             PG8_WAIT_V(8); PG8_WAIT_L(0); PG8_BAR; PG8_MMA(0, 0, At, B0); PG8_MMA(0, 1, At, B1); PG8_BAR; PG8_SCHED;
;             PG8_LDA(At, 0, 1); PG8_STAGE(PG8_SB(0, 0), b2, voffB); PG8_STAGE(PG8_SB(0, 1), b2 + hstep, voffB); PG8_STAGE(PG8_SA(0, 0), a2, voffA);
;             PG8_WAIT_V(8); PG8_WAIT_L(0); PG8_BAR; PG8_MMA(1, 0, At, B0); PG8_MMA(1, 1, At, B1); PG8_BAR; PG8_SCHED;
.LBB0_525:
	ds_read_b128 v[144:147], v157
	ds_read_b128 v[148:151], v157 offset:1024
	ds_read_b128 v[162:165], v157 offset:2048
	ds_read_b128 v[166:169], v157 offset:3072
	ds_read_b128 v[170:173], v158
	ds_read_b128 v[174:177], v158 offset:1024
	ds_read_b128 v[178:181], v158 offset:2048
	ds_read_b128 v[182:185], v158 offset:3072
	s_add_u32 s34, s30, 0xfffc0080
	s_addc_u32 s35, s31, -1
	s_cmp_eq_u32 s53, 12
	s_cselect_b32 s37, s3, s35
	s_cselect_b32 s36, s23, s34
	s_cselect_b32 s35, s21, s52
	s_cselect_b32 s34, s50, s51
	v_lshl_add_u64 v[194:195], s[30:31], 0, v[136:137]
	s_add_i32 m0, s29, 0xc000
	ds_read_b128 v[186:189], v159
	ds_read_b128 v[190:193], v159 offset:1024
	ds_read_b128 v[198:201], v159 offset:2048
	ds_read_b128 v[202:205], v159 offset:3072
	ds_read_b128 v[206:209], v159 offset:4096
	ds_read_b128 v[210:213], v159 offset:5120
	ds_read_b128 v[214:217], v159 offset:6144
	ds_read_b128 v[218:221], v159 offset:7168
	global_load_lds_dwordx4 v[194:195], off
	v_lshl_add_u64 v[194:195], s[30:31], 0, v[138:139]
	s_add_i32 m0, s29, 0xe000
	s_nop 0
	global_load_lds_dwordx4 v[194:195], off
	s_waitcnt vmcnt(8)
	s_waitcnt lgkmcnt(0)
	s_barrier
	s_setprio 1
	s_waitcnt lgkmcnt(0)
	v_mfma_f32_16x16x32_bf16 v[124:127], v[144:147], v[186:189], v[124:127]
	v_mfma_f32_16x16x32_bf16 v[120:123], v[162:165], v[186:189], v[120:123]
	v_mfma_f32_16x16x32_bf16 v[116:119], v[144:147], v[198:201], v[116:119]
	v_mfma_f32_16x16x32_bf16 v[112:115], v[162:165], v[198:201], v[112:115]
	v_mfma_f32_16x16x32_bf16 v[108:111], v[144:147], v[206:209], v[108:111]
	v_mfma_f32_16x16x32_bf16 v[104:107], v[162:165], v[206:209], v[104:107]
	v_mfma_f32_16x16x32_bf16 v[100:103], v[144:147], v[214:217], v[100:103]
	v_mfma_f32_16x16x32_bf16 v[96:99], v[162:165], v[214:217], v[96:99]
	v_mfma_f32_16x16x32_bf16 v[124:127], v[148:151], v[190:193], v[124:127]
	v_mfma_f32_16x16x32_bf16 v[120:123], v[166:169], v[190:193], v[120:123]
	v_mfma_f32_16x16x32_bf16 v[116:119], v[148:151], v[202:205], v[116:119]
	v_mfma_f32_16x16x32_bf16 v[112:115], v[166:169], v[202:205], v[112:115]
	v_mfma_f32_16x16x32_bf16 v[108:111], v[148:151], v[210:213], v[108:111]
	v_mfma_f32_16x16x32_bf16 v[104:107], v[166:169], v[210:213], v[104:107]
	v_mfma_f32_16x16x32_bf16 v[100:103], v[148:151], v[218:221], v[100:103]
	v_mfma_f32_16x16x32_bf16 v[96:99], v[166:169], v[218:221], v[96:99]
	s_setprio 0
	s_setprio 1
	v_mfma_f32_16x16x32_bf16 v[64:67], v[170:173], v[186:189], v[64:67]
	v_mfma_f32_16x16x32_bf16 v[56:59], v[178:181], v[186:189], v[56:59]
	v_mfma_f32_16x16x32_bf16 v[52:55], v[170:173], v[198:201], v[52:55]
	v_mfma_f32_16x16x32_bf16 v[48:51], v[178:181], v[198:201], v[48:51]
	v_mfma_f32_16x16x32_bf16 v[44:47], v[170:173], v[206:209], v[44:47]
	v_mfma_f32_16x16x32_bf16 v[40:43], v[178:181], v[206:209], v[40:43]
	v_mfma_f32_16x16x32_bf16 v[36:39], v[170:173], v[214:217], v[36:39]
	v_mfma_f32_16x16x32_bf16 v[32:35], v[178:181], v[214:217], v[32:35]
	v_mfma_f32_16x16x32_bf16 v[64:67], v[174:177], v[190:193], v[64:67]
	v_mfma_f32_16x16x32_bf16 v[56:59], v[182:185], v[190:193], v[56:59]
	v_mfma_f32_16x16x32_bf16 v[52:55], v[174:177], v[202:205], v[52:55]
	v_mfma_f32_16x16x32_bf16 v[48:51], v[182:185], v[202:205], v[48:51]
	v_mfma_f32_16x16x32_bf16 v[44:47], v[174:177], v[210:213], v[44:47]
	v_mfma_f32_16x16x32_bf16 v[40:43], v[182:185], v[210:213], v[40:43]
	v_mfma_f32_16x16x32_bf16 v[36:39], v[174:177], v[218:221], v[36:39]
	v_mfma_f32_16x16x32_bf16 v[32:35], v[182:185], v[218:221], v[32:35]
	s_setprio 0
	s_barrier
	s_add_i32 s54, s47, s33
	v_lshl_add_u64 v[194:195], s[34:35], 0, v[130:131]
	s_mov_b32 m0, s54
	ds_read_b128 v[186:189], v159 offset:16384
	ds_read_b128 v[190:193], v159 offset:17408
	ds_read_b128 v[198:201], v159 offset:18432
	ds_read_b128 v[202:205], v159 offset:19456
	ds_read_b128 v[206:209], v159 offset:20480
	ds_read_b128 v[210:213], v159 offset:21504
	ds_read_b128 v[214:217], v159 offset:22528
	ds_read_b128 v[218:221], v159 offset:23552
	global_load_lds_dwordx4 v[194:195], off
	s_add_i32 m0, s54, 0x2000
	s_add_u32 s54, s34, 0x40000
	v_lshl_add_u64 v[222:223], s[34:35], 0, v[134:135]
	s_addc_u32 s55, s35, 0
	s_add_i32 s56, s48, s33
	global_load_lds_dwordx4 v[222:223], off
	v_lshl_add_u64 v[224:225], s[54:55], 0, v[130:131]
	s_mov_b32 m0, s56
	v_lshl_add_u64 v[226:227], s[36:37], 0, v[132:133]
	global_load_lds_dwordx4 v[224:225], off
	v_lshl_add_u64 v[224:225], s[54:55], 0, v[134:135]
	s_add_i32 m0, s56, 0x2000
	s_nop 0
	global_load_lds_dwordx4 v[224:225], off
	v_lshl_add_u64 v[224:225], s[36:37], 0, v[128:129]
	s_mov_b32 m0, s29
	s_nop 0
	global_load_lds_dwordx4 v[224:225], off
	s_mov_b32 m0, s38
	s_nop 0
	global_load_lds_dwordx4 v[226:227], off
	s_waitcnt vmcnt(8)
	s_waitcnt lgkmcnt(0)
	s_barrier
; #define PG8_STAGE(bufoff, gbase, voff) do { _Pragma("unroll") for (int _i = 0; _i < 2; ++_i) \
;         __builtin_amdgcn_global_load_lds((const unsigned*)((const char*)(gbase) + (voff)[_i]), (PG8_LAS unsigned*)(lds + (bufoff) + ldsw + _i * 8192), 16, 0, 0); } while (0)
; #define PG8_LDA(dst, b, h) do { _Pragma("unroll") for (int m = 0; m < 4; ++m) _Pragma("unroll") for (int k = 0; k < 2; ++k) dst[m][k] = *(const PG8_LAS bf16x8*)(lds + PG8_SA(b, h) + aoff + m * 2048 + k * 1024); } while (0)
; #define PG8_LDB(dst, b, h) do { _Pragma("unroll") for (int n = 0; n < 2; ++n) _Pragma("unroll") for (int k = 0; k < 2; ++k) dst[n][k] = *(const PG8_LAS bf16x8*)(lds + PG8_SB(b, h) + boff + n * 2048 + k * 1024); } while (0)
; #define PG8_MMA(ai, bj, At, Bt) do { __builtin_amdgcn_s_setprio(1); _Pragma("unroll") for (int m = 0; m < 4; ++m) _Pragma("unroll") for (int n = 0; n < 2; ++n) _Pragma("unroll") for (int k = 0; k < 2; ++k) \
;         acc[ai][bj][m][n] = __builtin_amdgcn_mfma_f32_16x16x32_bf16(Bt[n][k], At[m][k], acc[ai][bj][m][n], 0, 0, 0); __builtin_amdgcn_s_setprio(0); } while (0)
; #define PG8_WAIT_V(n) asm volatile("s_waitcnt vmcnt(" #n ")" ::: "memory")
; #define PG8_WAIT_L(n) asm volatile("s_waitcnt lgkmcnt(" #n ")" ::: "memory")
; #define PG8_BAR __builtin_amdgcn_s_barrier()
; #define PG8_SCHED __builtin_amdgcn_sched_barrier(0)
; template <class Epi, class Sched, bool ALIGN_EPI = false, bool SP2 = false>
; __device__ __forceinline__ void gemm_phase(PG8_LAS unsigned char* lds, const Gemm g, const Sched& S, const Epi& E) {
;     ...
;             PG8_WAIT_V(8); PG8_WAIT_L(0); PG8_BAR; PG8_MMA(1, 0, At, B0); PG8_MMA(1, 1, At, B1); PG8_BAR; PG8_SCHED;
;             PG8_LDB(B0, 1, 0); PG8_LDB(B1, 1, 1); PG8_SCHED; PG8_LDA(At, 1, 0); PG8_STAGE(PG8_SA(0, 1), a2 + hstep, voffA);
;             PG8_WAIT_V(8); PG8_WAIT_L(0); PG8_BAR; PG8_MMA(0, 0, At, B0); PG8_MMA(0, 1, At, B1); PG8_BAR; PG8_SCHED;
	s_setprio 1
	s_waitcnt lgkmcnt(0)
	v_mfma_f32_16x16x32_bf16 v[92:95], v[144:147], v[186:189], v[92:95]
	v_mfma_f32_16x16x32_bf16 v[88:91], v[162:165], v[186:189], v[88:91]
	v_mfma_f32_16x16x32_bf16 v[84:87], v[144:147], v[198:201], v[84:87]
	v_mfma_f32_16x16x32_bf16 v[80:83], v[162:165], v[198:201], v[80:83]
	v_mfma_f32_16x16x32_bf16 v[76:79], v[144:147], v[206:209], v[76:79]
	v_mfma_f32_16x16x32_bf16 v[72:75], v[162:165], v[206:209], v[72:75]
	v_mfma_f32_16x16x32_bf16 v[68:71], v[144:147], v[214:217], v[68:71]
	v_mfma_f32_16x16x32_bf16 v[60:63], v[162:165], v[214:217], v[60:63]
	v_mfma_f32_16x16x32_bf16 v[92:95], v[148:151], v[190:193], v[92:95]
	v_mfma_f32_16x16x32_bf16 v[88:91], v[166:169], v[190:193], v[88:91]
	v_mfma_f32_16x16x32_bf16 v[84:87], v[148:151], v[202:205], v[84:87]
	v_mfma_f32_16x16x32_bf16 v[80:83], v[166:169], v[202:205], v[80:83]
	v_mfma_f32_16x16x32_bf16 v[76:79], v[148:151], v[210:213], v[76:79]
	v_mfma_f32_16x16x32_bf16 v[72:75], v[166:169], v[210:213], v[72:75]
	v_mfma_f32_16x16x32_bf16 v[68:71], v[148:151], v[218:221], v[68:71]
	v_mfma_f32_16x16x32_bf16 v[60:63], v[166:169], v[218:221], v[60:63]
	s_setprio 0
	s_setprio 1
	v_mfma_f32_16x16x32_bf16 v[28:31], v[170:173], v[186:189], v[28:31]
	v_mfma_f32_16x16x32_bf16 v[24:27], v[178:181], v[186:189], v[24:27]
	v_mfma_f32_16x16x32_bf16 v[20:23], v[170:173], v[198:201], v[20:23]
	v_mfma_f32_16x16x32_bf16 v[16:19], v[178:181], v[198:201], v[16:19]
	v_mfma_f32_16x16x32_bf16 v[12:15], v[170:173], v[206:209], v[12:15]
	v_mfma_f32_16x16x32_bf16 v[8:11], v[178:181], v[206:209], v[8:11]
	v_mfma_f32_16x16x32_bf16 v[4:7], v[170:173], v[214:217], v[4:7]
	v_mfma_f32_16x16x32_bf16 v[0:3], v[178:181], v[214:217], v[0:3]
	v_mfma_f32_16x16x32_bf16 v[28:31], v[174:177], v[190:193], v[28:31]
	v_mfma_f32_16x16x32_bf16 v[24:27], v[182:185], v[190:193], v[24:27]
	v_mfma_f32_16x16x32_bf16 v[20:23], v[174:177], v[202:205], v[20:23]
	v_mfma_f32_16x16x32_bf16 v[16:19], v[182:185], v[202:205], v[16:19]
	v_mfma_f32_16x16x32_bf16 v[12:15], v[174:177], v[210:213], v[12:15]
	v_mfma_f32_16x16x32_bf16 v[8:11], v[182:185], v[210:213], v[8:11]
	v_mfma_f32_16x16x32_bf16 v[4:7], v[174:177], v[218:221], v[4:7]
	v_mfma_f32_16x16x32_bf16 v[0:3], v[182:185], v[218:221], v[0:3]
	s_setprio 0
	s_barrier
	s_add_i32 s54, 0, 0x18000
	v_add_u32_e32 v152, s54, v155
	s_add_i32 s55, 0, 0x1c000
	ds_read_b128 v[144:147], v152
	ds_read_b128 v[148:151], v152 offset:1024
	ds_read_b128 v[162:165], v152 offset:2048
	ds_read_b128 v[166:169], v152 offset:3072
	v_add_u32_e32 v152, s55, v155
	ds_read_b128 v[170:173], v152
	ds_read_b128 v[174:177], v152 offset:1024
	ds_read_b128 v[178:181], v152 offset:2048
	ds_read_b128 v[182:185], v152 offset:3072
	s_add_u32 s36, s36, 0x40000
	s_addc_u32 s37, s37, 0
	s_mov_b32 m0, s39
	v_lshl_add_u64 v[228:229], s[36:37], 0, v[128:129]
	ds_read_b128 v[186:189], v159 offset:32768
	ds_read_b128 v[190:193], v159 offset:33792
	ds_read_b128 v[198:201], v159 offset:34816
	ds_read_b128 v[202:205], v159 offset:35840
	ds_read_b128 v[206:209], v159 offset:36864
	ds_read_b128 v[210:213], v159 offset:37888
	ds_read_b128 v[214:217], v159 offset:38912
	ds_read_b128 v[218:221], v159 offset:39936
	global_load_lds_dwordx4 v[228:229], off
	v_lshl_add_u64 v[228:229], s[36:37], 0, v[132:133]
	s_mov_b32 m0, s40
	s_nop 0
	global_load_lds_dwordx4 v[228:229], off
	s_waitcnt vmcnt(8)
	s_waitcnt lgkmcnt(0)
	s_barrier
	s_setprio 1
	s_waitcnt lgkmcnt(0)
	v_mfma_f32_16x16x32_bf16 v[124:127], v[144:147], v[186:189], v[124:127]
	v_mfma_f32_16x16x32_bf16 v[120:123], v[162:165], v[186:189], v[120:123]
	v_mfma_f32_16x16x32_bf16 v[116:119], v[144:147], v[198:201], v[116:119]
	v_mfma_f32_16x16x32_bf16 v[112:115], v[162:165], v[198:201], v[112:115]
	v_mfma_f32_16x16x32_bf16 v[108:111], v[144:147], v[206:209], v[108:111]
	v_mfma_f32_16x16x32_bf16 v[104:107], v[162:165], v[206:209], v[104:107]
	v_mfma_f32_16x16x32_bf16 v[100:103], v[144:147], v[214:217], v[100:103]
	v_mfma_f32_16x16x32_bf16 v[96:99], v[162:165], v[214:217], v[96:99]
	v_mfma_f32_16x16x32_bf16 v[124:127], v[148:151], v[190:193], v[124:127]
	v_mfma_f32_16x16x32_bf16 v[120:123], v[166:169], v[190:193], v[120:123]
	v_mfma_f32_16x16x32_bf16 v[116:119], v[148:151], v[202:205], v[116:119]
	v_mfma_f32_16x16x32_bf16 v[112:115], v[166:169], v[202:205], v[112:115]
	v_mfma_f32_16x16x32_bf16 v[108:111], v[148:151], v[210:213], v[108:111]
	v_mfma_f32_16x16x32_bf16 v[104:107], v[166:169], v[210:213], v[104:107]
	v_mfma_f32_16x16x32_bf16 v[100:103], v[148:151], v[218:221], v[100:103]
	v_mfma_f32_16x16x32_bf16 v[96:99], v[166:169], v[218:221], v[96:99]
	s_setprio 0
	s_setprio 1
	v_mfma_f32_16x16x32_bf16 v[64:67], v[170:173], v[186:189], v[64:67]
	v_mfma_f32_16x16x32_bf16 v[56:59], v[178:181], v[186:189], v[56:59]
	v_mfma_f32_16x16x32_bf16 v[52:55], v[170:173], v[198:201], v[52:55]
	v_mfma_f32_16x16x32_bf16 v[48:51], v[178:181], v[198:201], v[48:51]
	v_mfma_f32_16x16x32_bf16 v[44:47], v[170:173], v[206:209], v[44:47]
	v_mfma_f32_16x16x32_bf16 v[40:43], v[178:181], v[206:209], v[40:43]
	v_mfma_f32_16x16x32_bf16 v[36:39], v[170:173], v[214:217], v[36:39]
	v_mfma_f32_16x16x32_bf16 v[32:35], v[178:181], v[214:217], v[32:35]
	v_mfma_f32_16x16x32_bf16 v[64:67], v[174:177], v[190:193], v[64:67]
	v_mfma_f32_16x16x32_bf16 v[56:59], v[182:185], v[190:193], v[56:59]
	v_mfma_f32_16x16x32_bf16 v[52:55], v[174:177], v[202:205], v[52:55]
	v_mfma_f32_16x16x32_bf16 v[48:51], v[182:185], v[202:205], v[48:51]
	v_mfma_f32_16x16x32_bf16 v[44:47], v[174:177], v[210:213], v[44:47]
	v_mfma_f32_16x16x32_bf16 v[40:43], v[182:185], v[210:213], v[40:43]
	v_mfma_f32_16x16x32_bf16 v[36:39], v[174:177], v[218:221], v[36:39]
	v_mfma_f32_16x16x32_bf16 v[32:35], v[182:185], v[218:221], v[32:35]
	s_setprio 0
	s_barrier
; #define PG8_STAGE(bufoff, gbase, voff) do { _Pragma("unroll") for (int _i = 0; _i < 2; ++_i) \
;         __builtin_amdgcn_global_load_lds((const unsigned*)((const char*)(gbase) + (voff)[_i]), (PG8_LAS unsigned*)(lds + (bufoff) + ldsw + _i * 8192), 16, 0, 0); } while (0)
; #define PG8_LDA(dst, b, h) do { _Pragma("unroll") for (int m = 0; m < 4; ++m) _Pragma("unroll") for (int k = 0; k < 2; ++k) dst[m][k] = *(const PG8_LAS bf16x8*)(lds + PG8_SA(b, h) + aoff + m * 2048 + k * 1024); } while (0)
; #define PG8_MMA(ai, bj, At, Bt) do { __builtin_amdgcn_s_setprio(1); _Pragma("unroll") for (int m = 0; m < 4; ++m) _Pragma("unroll") for (int n = 0; n < 2; ++n) _Pragma("unroll") for (int k = 0; k < 2; ++k) \
;         acc[ai][bj][m][n] = __builtin_amdgcn_mfma_f32_16x16x32_bf16(Bt[n][k], At[m][k], acc[ai][bj][m][n], 0, 0, 0); __builtin_amdgcn_s_setprio(0); } while (0)
; #define PG8_WAIT_V(n) asm volatile("s_waitcnt vmcnt(" #n ")" ::: "memory")
; #define PG8_WAIT_L(n) asm volatile("s_waitcnt lgkmcnt(" #n ")" ::: "memory")
; #define PG8_BAR __builtin_amdgcn_s_barrier()
; #define PG8_SCHED __builtin_amdgcn_sched_barrier(0)
; template <class Epi, class Sched, bool ALIGN_EPI = false, bool SP2 = false>
; __device__ __forceinline__ void gemm_phase(PG8_LAS unsigned char* lds, const Gemm g, const Sched& S, const Epi& E) {
;     ...
;             PG8_LDA(At, 1, 1); PG8_STAGE(PG8_SB(1, 0), b3, voffB); PG8_STAGE(PG8_SB(1, 1), b3 + hstep, voffB); PG8_STAGE(PG8_SA(1, 0), a3, voffA);
;             PG8_WAIT_V(8); PG8_WAIT_L(0); PG8_BAR; PG8_MMA(1, 0, At, B0); PG8_MMA(1, 1, At, B1); PG8_BAR; PG8_SCHED;
;     ...
;         if constexpr (ALIGN_EPI) { if (wr == 0) PG8_BAR; }
	s_add_i32 s36, s54, s33
	v_lshl_add_u64 v[194:195], v[194:195], 0, s[14:15]
	s_mov_b32 m0, s36
	ds_read_b128 v[186:189], v159 offset:49152
	ds_read_b128 v[190:193], v159 offset:50176
	ds_read_b128 v[198:201], v159 offset:51200
	ds_read_b128 v[202:205], v159 offset:52224
	ds_read_b128 v[206:209], v159 offset:53248
	ds_read_b128 v[210:213], v159 offset:54272
	ds_read_b128 v[214:217], v159 offset:55296
	ds_read_b128 v[218:221], v159 offset:56320
	global_load_lds_dwordx4 v[194:195], off
	s_add_i32 m0, s36, 0x2000
	s_add_u32 s34, s34, 0x40080
	v_lshl_add_u64 v[194:195], v[222:223], 0, s[14:15]
	s_addc_u32 s35, s35, 0
	s_add_i32 s36, s55, s33
	global_load_lds_dwordx4 v[194:195], off
	v_lshl_add_u64 v[194:195], s[34:35], 0, v[130:131]
	s_mov_b32 m0, s36
	s_nop 0
	global_load_lds_dwordx4 v[194:195], off
	v_lshl_add_u64 v[194:195], s[34:35], 0, v[134:135]
	s_add_i32 m0, s36, 0x2000
	s_nop 0
	global_load_lds_dwordx4 v[194:195], off
	v_lshl_add_u64 v[194:195], v[224:225], 0, s[14:15]
	s_mov_b32 m0, s44
	s_nop 0
	global_load_lds_dwordx4 v[194:195], off
	v_lshl_add_u64 v[194:195], v[226:227], 0, s[14:15]
	s_mov_b32 m0, s45
	s_nop 0
	global_load_lds_dwordx4 v[194:195], off
	s_waitcnt vmcnt(8)
	s_waitcnt lgkmcnt(0)
	s_barrier
	s_setprio 1
	s_waitcnt lgkmcnt(0)
	v_mfma_f32_16x16x32_bf16 v[92:95], v[144:147], v[186:189], v[92:95]
	v_mfma_f32_16x16x32_bf16 v[88:91], v[162:165], v[186:189], v[88:91]
	v_mfma_f32_16x16x32_bf16 v[84:87], v[144:147], v[198:201], v[84:87]
	v_mfma_f32_16x16x32_bf16 v[80:83], v[162:165], v[198:201], v[80:83]
	v_mfma_f32_16x16x32_bf16 v[76:79], v[144:147], v[206:209], v[76:79]
	v_mfma_f32_16x16x32_bf16 v[72:75], v[162:165], v[206:209], v[72:75]
	v_mfma_f32_16x16x32_bf16 v[68:71], v[144:147], v[214:217], v[68:71]
	v_mfma_f32_16x16x32_bf16 v[60:63], v[162:165], v[214:217], v[60:63]
	v_mfma_f32_16x16x32_bf16 v[92:95], v[148:151], v[190:193], v[92:95]
	v_mfma_f32_16x16x32_bf16 v[88:91], v[166:169], v[190:193], v[88:91]
	v_mfma_f32_16x16x32_bf16 v[84:87], v[148:151], v[202:205], v[84:87]
	v_mfma_f32_16x16x32_bf16 v[80:83], v[166:169], v[202:205], v[80:83]
	v_mfma_f32_16x16x32_bf16 v[76:79], v[148:151], v[210:213], v[76:79]
	v_mfma_f32_16x16x32_bf16 v[72:75], v[166:169], v[210:213], v[72:75]
	v_mfma_f32_16x16x32_bf16 v[68:71], v[148:151], v[218:221], v[68:71]
	v_mfma_f32_16x16x32_bf16 v[60:63], v[166:169], v[218:221], v[60:63]
	s_setprio 0
	s_setprio 1
	v_mfma_f32_16x16x32_bf16 v[28:31], v[170:173], v[186:189], v[28:31]
	v_mfma_f32_16x16x32_bf16 v[24:27], v[178:181], v[186:189], v[24:27]
	v_mfma_f32_16x16x32_bf16 v[20:23], v[170:173], v[198:201], v[20:23]
	v_mfma_f32_16x16x32_bf16 v[16:19], v[178:181], v[198:201], v[16:19]
	v_mfma_f32_16x16x32_bf16 v[12:15], v[170:173], v[206:209], v[12:15]
	v_mfma_f32_16x16x32_bf16 v[8:11], v[178:181], v[206:209], v[8:11]
	v_mfma_f32_16x16x32_bf16 v[4:7], v[170:173], v[214:217], v[4:7]
	v_mfma_f32_16x16x32_bf16 v[0:3], v[178:181], v[214:217], v[0:3]
	v_mfma_f32_16x16x32_bf16 v[28:31], v[174:177], v[190:193], v[28:31]
	v_mfma_f32_16x16x32_bf16 v[24:27], v[182:185], v[190:193], v[24:27]
	v_mfma_f32_16x16x32_bf16 v[20:23], v[174:177], v[202:205], v[20:23]
	v_mfma_f32_16x16x32_bf16 v[16:19], v[182:185], v[202:205], v[16:19]
	v_mfma_f32_16x16x32_bf16 v[12:15], v[174:177], v[210:213], v[12:15]
	v_mfma_f32_16x16x32_bf16 v[8:11], v[182:185], v[210:213], v[8:11]
	v_mfma_f32_16x16x32_bf16 v[4:7], v[174:177], v[218:221], v[4:7]
	v_mfma_f32_16x16x32_bf16 v[0:3], v[182:185], v[218:221], v[0:3]
	s_setprio 0
	s_add_i32 s53, s53, 2
	s_add_u32 s30, s30, 0x100
	s_addc_u32 s31, s31, 0
	s_add_u32 s51, s51, 0x100
	s_addc_u32 s52, s52, 0
	s_cmp_gt_u32 s53, 13
	s_barrier
	s_cbranch_scc0 .LBB0_525
	s_and_b64 vcc, exec, s[16:17]
	s_cbranch_vccz .LBB0_528
	s_barrier

; #define PG8_STAGE(bufoff, gbase, voff) do { _Pragma("unroll") for (int _i = 0; _i < 2; ++_i) \
;         __builtin_amdgcn_global_load_lds((const unsigned*)((const char*)(gbase) + (voff)[_i]), (PG8_LAS unsigned*)(lds + (bufoff) + ldsw + _i * 8192), 16, 0, 0); } while (0)
; #define PG8_LDA(dst, b, h) do { _Pragma("unroll") for (int m = 0; m < 4; ++m) _Pragma("unroll") for (int k = 0; k < 2; ++k) dst[m][k] = *(const PG8_LAS bf16x8*)(lds + PG8_SA(b, h) + aoff + m * 2048 + k * 1024); } while (0)
; #define PG8_LDB(dst, b, h) do { _Pragma("unroll") for (int n = 0; n < 2; ++n) _Pragma("unroll") for (int k = 0; k < 2; ++k) dst[n][k] = *(const PG8_LAS bf16x8*)(lds + PG8_SB(b, h) + boff + n * 2048 + k * 1024); } while (0)
; #define PG8_MMA(ai, bj, At, Bt) do { __builtin_amdgcn_s_setprio(1); _Pragma("unroll") for (int m = 0; m < 4; ++m) _Pragma("unroll") for (int n = 0; n < 2; ++n) _Pragma("unroll") for (int k = 0; k < 2; ++k) \
;         acc[ai][bj][m][n] = __builtin_amdgcn_mfma_f32_16x16x32_bf16(Bt[n][k], At[m][k], acc[ai][bj][m][n], 0, 0, 0); __builtin_amdgcn_s_setprio(0); } while (0)
; #define PG8_WAIT_V(n) asm volatile("s_waitcnt vmcnt(" #n ")" ::: "memory")
; #define PG8_WAIT_L(n) asm volatile("s_waitcnt lgkmcnt(" #n ")" ::: "memory")
; #define PG8_BAR __builtin_amdgcn_s_barrier()
; template <class Epi, class Sched, bool ALIGN_EPI = false, bool SP2 = false>
; __device__ __forceinline__ void gemm_phase(PG8_LAS unsigned char* lds, const Gemm g, const Sched& S, const Epi& E) {
;     ...
;             const char* a1 = cA + (size_t)(t + 1) * kstep;
;             const char* a2 = last ? nA : cA + (size_t)(t + 2) * kstep; const char* b2 = last ? nB : cB + (size_t)(t + 2) * kstep;
;             const char* a3 = a2 + kstep; const char* b3 = b2 + kstep;
;             if (last && has_next) S.a_ready(nxt);
;             if constexpr (SP2) {
;             PG8_LDB(B0, 0, 0); PG8_LDB(B1, 0, 1); PG8_SCHED; PG8_LDA(At, 0, 0); PG8_STAGE(PG8_SA(1, 1), a1 + hstep, voffA);
;             PG8_WAIT_V(8); PG8_WAIT_L(0); PG8_BAR; PG8_MMA(0, 0, At, B0); PG8_MMA(0, 1, At, B1); PG8_BAR; PG8_SCHED;
;             PG8_LDA(At, 0, 1); PG8_STAGE(PG8_SB(0, 0), b2, voffB); PG8_STAGE(PG8_SB(0, 1), b2 + hstep, voffB); PG8_STAGE(PG8_SA(0, 0), a2, voffA);
;             PG8_WAIT_V(8); PG8_WAIT_L(0); PG8_BAR; PG8_MMA(1, 0, At, B0); PG8_MMA(1, 1, At, B1); PG8_BAR; PG8_SCHED;
.LBB0_706:
	ds_read_b128 v[164:167], v161
	ds_read_b128 v[168:171], v161 offset:1024
	ds_read_b128 v[172:175], v161 offset:2048
	ds_read_b128 v[176:179], v161 offset:3072
	ds_read_b128 v[180:183], v162
	ds_read_b128 v[184:187], v162 offset:1024
	ds_read_b128 v[188:191], v162 offset:2048
	ds_read_b128 v[192:195], v162 offset:3072
	s_add_i32 s54, s26, 2
	s_add_u32 s55, s24, 0x80
	s_addc_u32 s27, s25, 0
	s_cmp_eq_u32 s43, s26
	s_cselect_b32 s26, s4, s55
	s_cselect_b32 s27, s5, s27
	s_cselect_b32 s57, s23, s53
	s_cselect_b32 s56, s22, s52
	s_mov_b32 m0, s47
	v_lshl_add_u64 v[230:231], s[24:25], 0, v[136:137]
	ds_read_b128 v[198:201], v163
	ds_read_b128 v[202:205], v163 offset:1024
	ds_read_b128 v[206:209], v163 offset:2048
	ds_read_b128 v[210:213], v163 offset:3072
	ds_read_b128 v[214:217], v163 offset:4096
	ds_read_b128 v[218:221], v163 offset:5120
	ds_read_b128 v[222:225], v163 offset:6144
	ds_read_b128 v[226:229], v163 offset:7168
	global_load_lds_dwordx4 v[230:231], off
	v_lshl_add_u64 v[230:231], s[24:25], 0, v[138:139]
	s_add_i32 m0, s35, 0xe000
	s_nop 0
	global_load_lds_dwordx4 v[230:231], off
	s_waitcnt vmcnt(8)
	s_waitcnt lgkmcnt(0)
	s_barrier
	s_setprio 1
	s_waitcnt lgkmcnt(0)
	v_mfma_f32_16x16x32_bf16 v[124:127], v[164:167], v[198:201], v[124:127]
	v_mfma_f32_16x16x32_bf16 v[120:123], v[172:175], v[198:201], v[120:123]
	v_mfma_f32_16x16x32_bf16 v[116:119], v[164:167], v[206:209], v[116:119]
	v_mfma_f32_16x16x32_bf16 v[112:115], v[172:175], v[206:209], v[112:115]
	v_mfma_f32_16x16x32_bf16 v[108:111], v[164:167], v[214:217], v[108:111]
	v_mfma_f32_16x16x32_bf16 v[104:107], v[172:175], v[214:217], v[104:107]
	v_mfma_f32_16x16x32_bf16 v[100:103], v[164:167], v[222:225], v[100:103]
	v_mfma_f32_16x16x32_bf16 v[96:99], v[172:175], v[222:225], v[96:99]
	v_mfma_f32_16x16x32_bf16 v[124:127], v[168:171], v[202:205], v[124:127]
	v_mfma_f32_16x16x32_bf16 v[120:123], v[176:179], v[202:205], v[120:123]
	v_mfma_f32_16x16x32_bf16 v[116:119], v[168:171], v[210:213], v[116:119]
	v_mfma_f32_16x16x32_bf16 v[112:115], v[176:179], v[210:213], v[112:115]
	v_mfma_f32_16x16x32_bf16 v[108:111], v[168:171], v[218:221], v[108:111]
	v_mfma_f32_16x16x32_bf16 v[104:107], v[176:179], v[218:221], v[104:107]
	v_mfma_f32_16x16x32_bf16 v[100:103], v[168:171], v[226:229], v[100:103]
	v_mfma_f32_16x16x32_bf16 v[96:99], v[176:179], v[226:229], v[96:99]
	s_setprio 0
	s_setprio 1
	v_mfma_f32_16x16x32_bf16 v[60:63], v[180:183], v[198:201], v[60:63]
	v_mfma_f32_16x16x32_bf16 v[56:59], v[188:191], v[198:201], v[56:59]
	v_mfma_f32_16x16x32_bf16 v[52:55], v[180:183], v[206:209], v[52:55]
	v_mfma_f32_16x16x32_bf16 v[48:51], v[188:191], v[206:209], v[48:51]
	v_mfma_f32_16x16x32_bf16 v[44:47], v[180:183], v[214:217], v[44:47]
	v_mfma_f32_16x16x32_bf16 v[40:43], v[188:191], v[214:217], v[40:43]
	v_mfma_f32_16x16x32_bf16 v[36:39], v[180:183], v[222:225], v[36:39]
	v_mfma_f32_16x16x32_bf16 v[32:35], v[188:191], v[222:225], v[32:35]
	v_mfma_f32_16x16x32_bf16 v[60:63], v[184:187], v[202:205], v[60:63]
	v_mfma_f32_16x16x32_bf16 v[56:59], v[192:195], v[202:205], v[56:59]
	v_mfma_f32_16x16x32_bf16 v[52:55], v[184:187], v[210:213], v[52:55]
	v_mfma_f32_16x16x32_bf16 v[48:51], v[192:195], v[210:213], v[48:51]
	v_mfma_f32_16x16x32_bf16 v[44:47], v[184:187], v[218:221], v[44:47]
	v_mfma_f32_16x16x32_bf16 v[40:43], v[192:195], v[218:221], v[40:43]
	v_mfma_f32_16x16x32_bf16 v[36:39], v[184:187], v[226:229], v[36:39]
	v_mfma_f32_16x16x32_bf16 v[32:35], v[192:195], v[226:229], v[32:35]
	s_setprio 0
	s_barrier
	s_add_i32 s55, s44, s34
	v_lshl_add_u64 v[230:231], s[56:57], 0, v[132:133]
	s_mov_b32 m0, s55
	ds_read_b128 v[198:201], v163 offset:16384
	ds_read_b128 v[202:205], v163 offset:17408
	ds_read_b128 v[206:209], v163 offset:18432
	ds_read_b128 v[210:213], v163 offset:19456
	ds_read_b128 v[214:217], v163 offset:20480
	ds_read_b128 v[218:221], v163 offset:21504
	ds_read_b128 v[222:225], v163 offset:22528
	ds_read_b128 v[226:229], v163 offset:23552
	global_load_lds_dwordx4 v[230:231], off
	s_add_i32 m0, s55, 0x2000
	v_lshl_add_u64 v[232:233], s[56:57], 0, v[128:129]
	s_add_u32 s56, s56, s10
	s_addc_u32 s57, s57, s11
	s_add_i32 s55, s45, s34
	global_load_lds_dwordx4 v[232:233], off
	v_lshl_add_u64 v[234:235], s[56:57], 0, v[132:133]
	s_mov_b32 m0, s55
	v_lshl_add_u64 v[236:237], s[56:57], 0, v[128:129]
	global_load_lds_dwordx4 v[234:235], off
	s_add_i32 m0, s55, 0x2000
	v_lshl_add_u64 v[238:239], s[26:27], 0, v[134:135]
	global_load_lds_dwordx4 v[236:237], off
	s_mov_b32 m0, s35
	v_lshl_add_u64 v[240:241], s[26:27], 0, v[130:131]
	global_load_lds_dwordx4 v[238:239], off
	s_mov_b32 m0, s36
	s_nop 0
	global_load_lds_dwordx4 v[240:241], off
	s_waitcnt vmcnt(8)
	s_waitcnt lgkmcnt(0)
	s_barrier
; #define PG8_STAGE(bufoff, gbase, voff) do { _Pragma("unroll") for (int _i = 0; _i < 2; ++_i) \
;         __builtin_amdgcn_global_load_lds((const unsigned*)((const char*)(gbase) + (voff)[_i]), (PG8_LAS unsigned*)(lds + (bufoff) + ldsw + _i * 8192), 16, 0, 0); } while (0)
; #define PG8_LDA(dst, b, h) do { _Pragma("unroll") for (int m = 0; m < 4; ++m) _Pragma("unroll") for (int k = 0; k < 2; ++k) dst[m][k] = *(const PG8_LAS bf16x8*)(lds + PG8_SA(b, h) + aoff + m * 2048 + k * 1024); } while (0)
; #define PG8_LDB(dst, b, h) do { _Pragma("unroll") for (int n = 0; n < 2; ++n) _Pragma("unroll") for (int k = 0; k < 2; ++k) dst[n][k] = *(const PG8_LAS bf16x8*)(lds + PG8_SB(b, h) + boff + n * 2048 + k * 1024); } while (0)
; #define PG8_MMA(ai, bj, At, Bt) do { __builtin_amdgcn_s_setprio(1); _Pragma("unroll") for (int m = 0; m < 4; ++m) _Pragma("unroll") for (int n = 0; n < 2; ++n) _Pragma("unroll") for (int k = 0; k < 2; ++k) \
;         acc[ai][bj][m][n] = __builtin_amdgcn_mfma_f32_16x16x32_bf16(Bt[n][k], At[m][k], acc[ai][bj][m][n], 0, 0, 0); __builtin_amdgcn_s_setprio(0); } while (0)
; #define PG8_WAIT_V(n) asm volatile("s_waitcnt vmcnt(" #n ")" ::: "memory")
; #define PG8_WAIT_L(n) asm volatile("s_waitcnt lgkmcnt(" #n ")" ::: "memory")
; #define PG8_BAR __builtin_amdgcn_s_barrier()
; #define PG8_SCHED __builtin_amdgcn_sched_barrier(0)
; template <class Epi, class Sched, bool ALIGN_EPI = false, bool SP2 = false>
; __device__ __forceinline__ void gemm_phase(PG8_LAS unsigned char* lds, const Gemm g, const Sched& S, const Epi& E) {
;     ...
;             PG8_WAIT_V(8); PG8_WAIT_L(0); PG8_BAR; PG8_MMA(1, 0, At, B0); PG8_MMA(1, 1, At, B1); PG8_BAR; PG8_SCHED;
;             PG8_LDB(B0, 1, 0); PG8_LDB(B1, 1, 1); PG8_SCHED; PG8_LDA(At, 1, 0); PG8_STAGE(PG8_SA(0, 1), a2 + hstep, voffA);
;             PG8_WAIT_V(8); PG8_WAIT_L(0); PG8_BAR; PG8_MMA(0, 0, At, B0); PG8_MMA(0, 1, At, B1); PG8_BAR; PG8_SCHED;
	s_setprio 1
	s_waitcnt lgkmcnt(0)
	v_mfma_f32_16x16x32_bf16 v[92:95], v[164:167], v[198:201], v[92:95]
	v_mfma_f32_16x16x32_bf16 v[88:91], v[172:175], v[198:201], v[88:91]
	v_mfma_f32_16x16x32_bf16 v[84:87], v[164:167], v[206:209], v[84:87]
	v_mfma_f32_16x16x32_bf16 v[80:83], v[172:175], v[206:209], v[80:83]
	v_mfma_f32_16x16x32_bf16 v[76:79], v[164:167], v[214:217], v[76:79]
	v_mfma_f32_16x16x32_bf16 v[72:75], v[172:175], v[214:217], v[72:75]
	v_mfma_f32_16x16x32_bf16 v[68:71], v[164:167], v[222:225], v[68:71]
	v_mfma_f32_16x16x32_bf16 v[64:67], v[172:175], v[222:225], v[64:67]
	v_mfma_f32_16x16x32_bf16 v[92:95], v[168:171], v[202:205], v[92:95]
	v_mfma_f32_16x16x32_bf16 v[88:91], v[176:179], v[202:205], v[88:91]
	v_mfma_f32_16x16x32_bf16 v[84:87], v[168:171], v[210:213], v[84:87]
	v_mfma_f32_16x16x32_bf16 v[80:83], v[176:179], v[210:213], v[80:83]
	v_mfma_f32_16x16x32_bf16 v[76:79], v[168:171], v[218:221], v[76:79]
	v_mfma_f32_16x16x32_bf16 v[72:75], v[176:179], v[218:221], v[72:75]
	v_mfma_f32_16x16x32_bf16 v[68:71], v[168:171], v[226:229], v[68:71]
	v_mfma_f32_16x16x32_bf16 v[64:67], v[176:179], v[226:229], v[64:67]
	s_setprio 0
	s_setprio 1
	v_mfma_f32_16x16x32_bf16 v[28:31], v[180:183], v[198:201], v[28:31]
	v_mfma_f32_16x16x32_bf16 v[24:27], v[188:191], v[198:201], v[24:27]
	v_mfma_f32_16x16x32_bf16 v[20:23], v[180:183], v[206:209], v[20:23]
	v_mfma_f32_16x16x32_bf16 v[16:19], v[188:191], v[206:209], v[16:19]
	v_mfma_f32_16x16x32_bf16 v[12:15], v[180:183], v[214:217], v[12:15]
	v_mfma_f32_16x16x32_bf16 v[8:11], v[188:191], v[214:217], v[8:11]
	v_mfma_f32_16x16x32_bf16 v[4:7], v[180:183], v[222:225], v[4:7]
	v_mfma_f32_16x16x32_bf16 v[0:3], v[188:191], v[222:225], v[0:3]
	v_mfma_f32_16x16x32_bf16 v[28:31], v[184:187], v[202:205], v[28:31]
	v_mfma_f32_16x16x32_bf16 v[24:27], v[192:195], v[202:205], v[24:27]
	v_mfma_f32_16x16x32_bf16 v[20:23], v[184:187], v[210:213], v[20:23]
	v_mfma_f32_16x16x32_bf16 v[16:19], v[192:195], v[210:213], v[16:19]
	v_mfma_f32_16x16x32_bf16 v[12:15], v[184:187], v[218:221], v[12:15]
	v_mfma_f32_16x16x32_bf16 v[8:11], v[192:195], v[218:221], v[8:11]
	v_mfma_f32_16x16x32_bf16 v[4:7], v[184:187], v[226:229], v[4:7]
	v_mfma_f32_16x16x32_bf16 v[0:3], v[192:195], v[226:229], v[0:3]
	s_setprio 0
	s_barrier
	s_add_i32 s55, 0, 0x18000
	s_add_i32 s56, 0, 0x1c000
	v_add_u32_e32 v176, s55, v145
	v_add_u32_e32 v192, s56, v145
	ds_read_b128 v[164:167], v176
	ds_read_b128 v[168:171], v176 offset:1024
	ds_read_b128 v[172:175], v176 offset:2048
	ds_read_b128 v[176:179], v176 offset:3072
	ds_read_b128 v[180:183], v192
	ds_read_b128 v[184:187], v192 offset:1024
	ds_read_b128 v[188:191], v192 offset:2048
	ds_read_b128 v[192:195], v192 offset:3072
	s_add_u32 s26, s26, s10
	s_addc_u32 s27, s27, s11
	s_mov_b32 m0, s37
	v_lshl_add_u64 v[242:243], s[26:27], 0, v[134:135]
	ds_read_b128 v[198:201], v163 offset:32768
	ds_read_b128 v[202:205], v163 offset:33792
	ds_read_b128 v[206:209], v163 offset:34816
	ds_read_b128 v[210:213], v163 offset:35840
	ds_read_b128 v[214:217], v163 offset:36864
	ds_read_b128 v[218:221], v163 offset:37888
	ds_read_b128 v[222:225], v163 offset:38912
	ds_read_b128 v[226:229], v163 offset:39936
	global_load_lds_dwordx4 v[242:243], off
	v_lshl_add_u64 v[242:243], s[26:27], 0, v[130:131]
	s_mov_b32 m0, s38
	s_nop 0
	global_load_lds_dwordx4 v[242:243], off
	s_waitcnt vmcnt(8)
	s_waitcnt lgkmcnt(0)
	s_barrier
	s_setprio 1
	s_waitcnt lgkmcnt(0)
	v_mfma_f32_16x16x32_bf16 v[124:127], v[164:167], v[198:201], v[124:127]
	v_mfma_f32_16x16x32_bf16 v[120:123], v[172:175], v[198:201], v[120:123]
	v_mfma_f32_16x16x32_bf16 v[116:119], v[164:167], v[206:209], v[116:119]
	v_mfma_f32_16x16x32_bf16 v[112:115], v[172:175], v[206:209], v[112:115]
	v_mfma_f32_16x16x32_bf16 v[108:111], v[164:167], v[214:217], v[108:111]
	v_mfma_f32_16x16x32_bf16 v[104:107], v[172:175], v[214:217], v[104:107]
	v_mfma_f32_16x16x32_bf16 v[100:103], v[164:167], v[222:225], v[100:103]
	v_mfma_f32_16x16x32_bf16 v[96:99], v[172:175], v[222:225], v[96:99]
	v_mfma_f32_16x16x32_bf16 v[124:127], v[168:171], v[202:205], v[124:127]
	v_mfma_f32_16x16x32_bf16 v[120:123], v[176:179], v[202:205], v[120:123]
	v_mfma_f32_16x16x32_bf16 v[116:119], v[168:171], v[210:213], v[116:119]
	v_mfma_f32_16x16x32_bf16 v[112:115], v[176:179], v[210:213], v[112:115]
	v_mfma_f32_16x16x32_bf16 v[108:111], v[168:171], v[218:221], v[108:111]
	v_mfma_f32_16x16x32_bf16 v[104:107], v[176:179], v[218:221], v[104:107]
	v_mfma_f32_16x16x32_bf16 v[100:103], v[168:171], v[226:229], v[100:103]
	v_mfma_f32_16x16x32_bf16 v[96:99], v[176:179], v[226:229], v[96:99]
	s_setprio 0
	s_setprio 1
	v_mfma_f32_16x16x32_bf16 v[60:63], v[180:183], v[198:201], v[60:63]
	v_mfma_f32_16x16x32_bf16 v[56:59], v[188:191], v[198:201], v[56:59]
	v_mfma_f32_16x16x32_bf16 v[52:55], v[180:183], v[206:209], v[52:55]
	v_mfma_f32_16x16x32_bf16 v[48:51], v[188:191], v[206:209], v[48:51]
	v_mfma_f32_16x16x32_bf16 v[44:47], v[180:183], v[214:217], v[44:47]
	v_mfma_f32_16x16x32_bf16 v[40:43], v[188:191], v[214:217], v[40:43]
	v_mfma_f32_16x16x32_bf16 v[36:39], v[180:183], v[222:225], v[36:39]
	v_mfma_f32_16x16x32_bf16 v[32:35], v[188:191], v[222:225], v[32:35]
	v_mfma_f32_16x16x32_bf16 v[60:63], v[184:187], v[202:205], v[60:63]
	v_mfma_f32_16x16x32_bf16 v[56:59], v[192:195], v[202:205], v[56:59]
	v_mfma_f32_16x16x32_bf16 v[52:55], v[184:187], v[210:213], v[52:55]
	v_mfma_f32_16x16x32_bf16 v[48:51], v[192:195], v[210:213], v[48:51]
	v_mfma_f32_16x16x32_bf16 v[44:47], v[184:187], v[218:221], v[44:47]
	v_mfma_f32_16x16x32_bf16 v[40:43], v[192:195], v[218:221], v[40:43]
	v_mfma_f32_16x16x32_bf16 v[36:39], v[184:187], v[226:229], v[36:39]
	v_mfma_f32_16x16x32_bf16 v[32:35], v[192:195], v[226:229], v[32:35]
	s_setprio 0
	s_barrier
; #define PG8_STAGE(bufoff, gbase, voff) do { _Pragma("unroll") for (int _i = 0; _i < 2; ++_i) \
;         __builtin_amdgcn_global_load_lds((const unsigned*)((const char*)(gbase) + (voff)[_i]), (PG8_LAS unsigned*)(lds + (bufoff) + ldsw + _i * 8192), 16, 0, 0); } while (0)
; #define PG8_LDA(dst, b, h) do { _Pragma("unroll") for (int m = 0; m < 4; ++m) _Pragma("unroll") for (int k = 0; k < 2; ++k) dst[m][k] = *(const PG8_LAS bf16x8*)(lds + PG8_SA(b, h) + aoff + m * 2048 + k * 1024); } while (0)
; #define PG8_MMA(ai, bj, At, Bt) do { __builtin_amdgcn_s_setprio(1); _Pragma("unroll") for (int m = 0; m < 4; ++m) _Pragma("unroll") for (int n = 0; n < 2; ++n) _Pragma("unroll") for (int k = 0; k < 2; ++k) \
;         acc[ai][bj][m][n] = __builtin_amdgcn_mfma_f32_16x16x32_bf16(Bt[n][k], At[m][k], acc[ai][bj][m][n], 0, 0, 0); __builtin_amdgcn_s_setprio(0); } while (0)
; #define PG8_WAIT_V(n) asm volatile("s_waitcnt vmcnt(" #n ")" ::: "memory")
; #define PG8_WAIT_L(n) asm volatile("s_waitcnt lgkmcnt(" #n ")" ::: "memory")
; #define PG8_BAR __builtin_amdgcn_s_barrier()
; #define PG8_SCHED __builtin_amdgcn_sched_barrier(0)
; template <class Epi, class Sched, bool ALIGN_EPI = false, bool SP2 = false>
; __device__ __forceinline__ void gemm_phase(PG8_LAS unsigned char* lds, const Gemm g, const Sched& S, const Epi& E) {
;     ...
;             PG8_LDA(At, 1, 1); PG8_STAGE(PG8_SB(1, 0), b3, voffB); PG8_STAGE(PG8_SB(1, 1), b3 + hstep, voffB); PG8_STAGE(PG8_SA(1, 0), a3, voffA);
;             PG8_WAIT_V(8); PG8_WAIT_L(0); PG8_BAR; PG8_MMA(1, 0, At, B0); PG8_MMA(1, 1, At, B1); PG8_BAR; PG8_SCHED;
	s_add_i32 s26, s55, s34
	v_lshl_add_u64 v[230:231], v[230:231], 0, s[18:19]
	s_mov_b32 m0, s26
	ds_read_b128 v[198:201], v163 offset:49152
	ds_read_b128 v[202:205], v163 offset:50176
	ds_read_b128 v[206:209], v163 offset:51200
	ds_read_b128 v[210:213], v163 offset:52224
	ds_read_b128 v[214:217], v163 offset:53248
	ds_read_b128 v[218:221], v163 offset:54272
	ds_read_b128 v[222:225], v163 offset:55296
	ds_read_b128 v[226:229], v163 offset:56320
	global_load_lds_dwordx4 v[230:231], off
	v_lshl_add_u64 v[230:231], v[232:233], 0, s[18:19]
	s_add_i32 m0, s26, 0x2000
	s_add_i32 s26, s56, s34
	global_load_lds_dwordx4 v[230:231], off
	v_lshl_add_u64 v[230:231], v[234:235], 0, s[18:19]
	s_mov_b32 m0, s26
	s_nop 0
	global_load_lds_dwordx4 v[230:231], off
	v_lshl_add_u64 v[230:231], v[236:237], 0, s[18:19]
	s_add_i32 m0, s26, 0x2000
	s_nop 0
	global_load_lds_dwordx4 v[230:231], off
	v_lshl_add_u64 v[230:231], v[238:239], 0, s[18:19]
	s_mov_b32 m0, s39
	s_nop 0
	global_load_lds_dwordx4 v[230:231], off
	v_lshl_add_u64 v[230:231], v[240:241], 0, s[18:19]
	s_mov_b32 m0, s40
	s_nop 0
	global_load_lds_dwordx4 v[230:231], off
	s_waitcnt vmcnt(8)
	s_waitcnt lgkmcnt(0)
	s_barrier
	s_setprio 1
	s_waitcnt lgkmcnt(0)
	v_mfma_f32_16x16x32_bf16 v[92:95], v[164:167], v[198:201], v[92:95]
	v_mfma_f32_16x16x32_bf16 v[88:91], v[172:175], v[198:201], v[88:91]
	v_mfma_f32_16x16x32_bf16 v[84:87], v[164:167], v[206:209], v[84:87]
	v_mfma_f32_16x16x32_bf16 v[80:83], v[172:175], v[206:209], v[80:83]
	v_mfma_f32_16x16x32_bf16 v[76:79], v[164:167], v[214:217], v[76:79]
	v_mfma_f32_16x16x32_bf16 v[72:75], v[172:175], v[214:217], v[72:75]
	v_mfma_f32_16x16x32_bf16 v[68:71], v[164:167], v[222:225], v[68:71]
	v_mfma_f32_16x16x32_bf16 v[64:67], v[172:175], v[222:225], v[64:67]
	v_mfma_f32_16x16x32_bf16 v[92:95], v[168:171], v[202:205], v[92:95]
	v_mfma_f32_16x16x32_bf16 v[88:91], v[176:179], v[202:205], v[88:91]
	v_mfma_f32_16x16x32_bf16 v[84:87], v[168:171], v[210:213], v[84:87]
	v_mfma_f32_16x16x32_bf16 v[80:83], v[176:179], v[210:213], v[80:83]
	v_mfma_f32_16x16x32_bf16 v[76:79], v[168:171], v[218:221], v[76:79]
	v_mfma_f32_16x16x32_bf16 v[72:75], v[176:179], v[218:221], v[72:75]
	v_mfma_f32_16x16x32_bf16 v[68:71], v[168:171], v[226:229], v[68:71]
	v_mfma_f32_16x16x32_bf16 v[64:67], v[176:179], v[226:229], v[64:67]
	s_setprio 0
	s_setprio 1
	v_mfma_f32_16x16x32_bf16 v[28:31], v[180:183], v[198:201], v[28:31]
	v_mfma_f32_16x16x32_bf16 v[24:27], v[188:191], v[198:201], v[24:27]
	v_mfma_f32_16x16x32_bf16 v[20:23], v[180:183], v[206:209], v[20:23]
	v_mfma_f32_16x16x32_bf16 v[16:19], v[188:191], v[206:209], v[16:19]
	v_mfma_f32_16x16x32_bf16 v[12:15], v[180:183], v[214:217], v[12:15]
	v_mfma_f32_16x16x32_bf16 v[8:11], v[188:191], v[214:217], v[8:11]
	v_mfma_f32_16x16x32_bf16 v[4:7], v[180:183], v[222:225], v[4:7]
	v_mfma_f32_16x16x32_bf16 v[0:3], v[188:191], v[222:225], v[0:3]
	v_mfma_f32_16x16x32_bf16 v[28:31], v[184:187], v[202:205], v[28:31]
	v_mfma_f32_16x16x32_bf16 v[24:27], v[192:195], v[202:205], v[24:27]
	v_mfma_f32_16x16x32_bf16 v[20:23], v[184:187], v[210:213], v[20:23]
	v_mfma_f32_16x16x32_bf16 v[16:19], v[192:195], v[210:213], v[16:19]
	v_mfma_f32_16x16x32_bf16 v[12:15], v[184:187], v[218:221], v[12:15]
	v_mfma_f32_16x16x32_bf16 v[8:11], v[192:195], v[218:221], v[8:11]
	v_mfma_f32_16x16x32_bf16 v[4:7], v[184:187], v[226:229], v[4:7]
	v_mfma_f32_16x16x32_bf16 v[0:3], v[192:195], v[226:229], v[0:3]
	s_setprio 0
	s_add_u32 s24, s24, 0x100
	s_addc_u32 s25, s25, 0
	s_add_u32 s52, s52, 0x100
	s_addc_u32 s53, s53, 0
	s_cmp_ge_i32 s54, s41
	s_mov_b32 s26, s54
	s_barrier
	s_cbranch_scc0 .LBB0_706

; #define PG8_STAGE(bufoff, gbase, voff) do { _Pragma("unroll") for (int _i = 0; _i < 2; ++_i) \
;         __builtin_amdgcn_global_load_lds((const unsigned*)((const char*)(gbase) + (voff)[_i]), (PG8_LAS unsigned*)(lds + (bufoff) + ldsw + _i * 8192), 16, 0, 0); } while (0)
; #define PG8_LDA(dst, b, h) do { _Pragma("unroll") for (int m = 0; m < 4; ++m) _Pragma("unroll") for (int k = 0; k < 2; ++k) dst[m][k] = *(const PG8_LAS bf16x8*)(lds + PG8_SA(b, h) + aoff + m * 2048 + k * 1024); } while (0)
; #define PG8_LDB(dst, b, h) do { _Pragma("unroll") for (int n = 0; n < 2; ++n) _Pragma("unroll") for (int k = 0; k < 2; ++k) dst[n][k] = *(const PG8_LAS bf16x8*)(lds + PG8_SB(b, h) + boff + n * 2048 + k * 1024); } while (0)
; #define PG8_MMA(ai, bj, At, Bt) do { __builtin_amdgcn_s_setprio(1); _Pragma("unroll") for (int m = 0; m < 4; ++m) _Pragma("unroll") for (int n = 0; n < 2; ++n) _Pragma("unroll") for (int k = 0; k < 2; ++k) \
;         acc[ai][bj][m][n] = __builtin_amdgcn_mfma_f32_16x16x32_bf16(Bt[n][k], At[m][k], acc[ai][bj][m][n], 0, 0, 0); __builtin_amdgcn_s_setprio(0); } while (0)
; #define PG8_WAIT_V(n) asm volatile("s_waitcnt vmcnt(" #n ")" ::: "memory")
; #define PG8_WAIT_L(n) asm volatile("s_waitcnt lgkmcnt(" #n ")" ::: "memory")
; #define PG8_BAR __builtin_amdgcn_s_barrier()
; template <class Epi, class Sched, bool ALIGN_EPI = false, bool SP2 = false>
; __device__ __forceinline__ void gemm_phase(PG8_LAS unsigned char* lds, const Gemm g, const Sched& S, const Epi& E) {
;     ...
;             const char* a1 = cA + (size_t)(t + 1) * kstep;
;             const char* a2 = last ? nA : cA + (size_t)(t + 2) * kstep; const char* b2 = last ? nB : cB + (size_t)(t + 2) * kstep;
;             const char* a3 = a2 + kstep; const char* b3 = b2 + kstep;
;             if (last && has_next) S.a_ready(nxt);
;             if constexpr (SP2) {
;             PG8_LDB(B0, 0, 0); PG8_LDB(B1, 0, 1); PG8_SCHED; PG8_LDA(At, 0, 0); PG8_STAGE(PG8_SA(1, 1), a1 + hstep, voffA);
;             PG8_WAIT_V(8); PG8_WAIT_L(0); PG8_BAR; PG8_MMA(0, 0, At, B0); PG8_MMA(0, 1, At, B1); PG8_BAR; PG8_SCHED;
;             PG8_LDA(At, 0, 1); PG8_STAGE(PG8_SB(0, 0), b2, voffB); PG8_STAGE(PG8_SB(0, 1), b2 + hstep, voffB); PG8_STAGE(PG8_SA(0, 0), a2, voffA);
;             PG8_WAIT_V(8); PG8_WAIT_L(0); PG8_BAR; PG8_MMA(1, 0, At, B0); PG8_MMA(1, 1, At, B1); PG8_BAR; PG8_SCHED;
.LBB0_731:
	ds_read_b128 v[166:169], v162
	ds_read_b128 v[170:173], v162 offset:1024
	ds_read_b128 v[174:177], v162 offset:2048
	ds_read_b128 v[178:181], v162 offset:3072
	ds_read_b128 v[182:185], v163
	ds_read_b128 v[186:189], v163 offset:1024
	ds_read_b128 v[190:193], v163 offset:2048
	ds_read_b128 v[198:201], v163 offset:3072
	s_add_i32 s50, s24, 2
	s_add_u32 s51, s22, 0x80
	s_addc_u32 s25, s23, 0
	s_cmp_eq_u32 s40, s24
	s_cselect_b32 s24, s4, s51
	s_cselect_b32 s25, s5, s25
	s_cselect_b32 s53, s21, s49
	s_cselect_b32 s52, s20, s48
	v_lshl_add_u64 v[194:195], s[22:23], 0, v[138:139]
	s_add_i32 m0, s27, 0xc000
	ds_read_b128 v[202:205], v164
	ds_read_b128 v[206:209], v164 offset:1024
	ds_read_b128 v[210:213], v164 offset:2048
	ds_read_b128 v[214:217], v164 offset:3072
	ds_read_b128 v[218:221], v164 offset:4096
	ds_read_b128 v[222:225], v164 offset:5120
	ds_read_b128 v[226:229], v164 offset:6144
	ds_read_b128 v[230:233], v164 offset:7168
	global_load_lds_dwordx4 v[194:195], off
	v_lshl_add_u64 v[194:195], s[22:23], 0, v[140:141]
	s_add_i32 m0, s27, 0xe000
	s_nop 0
	global_load_lds_dwordx4 v[194:195], off
	s_waitcnt vmcnt(8)
	s_waitcnt lgkmcnt(0)
	s_barrier
	s_setprio 1
	s_waitcnt lgkmcnt(0)
	v_mfma_f32_16x16x32_bf16 v[124:127], v[166:169], v[202:205], v[124:127]
	v_mfma_f32_16x16x32_bf16 v[120:123], v[174:177], v[202:205], v[120:123]
	v_mfma_f32_16x16x32_bf16 v[116:119], v[166:169], v[210:213], v[116:119]
	v_mfma_f32_16x16x32_bf16 v[112:115], v[174:177], v[210:213], v[112:115]
	v_mfma_f32_16x16x32_bf16 v[108:111], v[166:169], v[218:221], v[108:111]
	v_mfma_f32_16x16x32_bf16 v[104:107], v[174:177], v[218:221], v[104:107]
	v_mfma_f32_16x16x32_bf16 v[100:103], v[166:169], v[226:229], v[100:103]
	v_mfma_f32_16x16x32_bf16 v[96:99], v[174:177], v[226:229], v[96:99]
	v_mfma_f32_16x16x32_bf16 v[124:127], v[170:173], v[206:209], v[124:127]
	v_mfma_f32_16x16x32_bf16 v[120:123], v[178:181], v[206:209], v[120:123]
	v_mfma_f32_16x16x32_bf16 v[116:119], v[170:173], v[214:217], v[116:119]
	v_mfma_f32_16x16x32_bf16 v[112:115], v[178:181], v[214:217], v[112:115]
	v_mfma_f32_16x16x32_bf16 v[108:111], v[170:173], v[222:225], v[108:111]
	v_mfma_f32_16x16x32_bf16 v[104:107], v[178:181], v[222:225], v[104:107]
	v_mfma_f32_16x16x32_bf16 v[100:103], v[170:173], v[230:233], v[100:103]
	v_mfma_f32_16x16x32_bf16 v[96:99], v[178:181], v[230:233], v[96:99]
	s_setprio 0
	s_setprio 1
	v_mfma_f32_16x16x32_bf16 v[60:63], v[182:185], v[202:205], v[60:63]
	v_mfma_f32_16x16x32_bf16 v[56:59], v[190:193], v[202:205], v[56:59]
	v_mfma_f32_16x16x32_bf16 v[52:55], v[182:185], v[210:213], v[52:55]
	v_mfma_f32_16x16x32_bf16 v[48:51], v[190:193], v[210:213], v[48:51]
	v_mfma_f32_16x16x32_bf16 v[44:47], v[182:185], v[218:221], v[44:47]
	v_mfma_f32_16x16x32_bf16 v[40:43], v[190:193], v[218:221], v[40:43]
	v_mfma_f32_16x16x32_bf16 v[36:39], v[182:185], v[226:229], v[36:39]
	v_mfma_f32_16x16x32_bf16 v[32:35], v[190:193], v[226:229], v[32:35]
	v_mfma_f32_16x16x32_bf16 v[60:63], v[186:189], v[206:209], v[60:63]
	v_mfma_f32_16x16x32_bf16 v[56:59], v[198:201], v[206:209], v[56:59]
	v_mfma_f32_16x16x32_bf16 v[52:55], v[186:189], v[214:217], v[52:55]
	v_mfma_f32_16x16x32_bf16 v[48:51], v[198:201], v[214:217], v[48:51]
	v_mfma_f32_16x16x32_bf16 v[44:47], v[186:189], v[222:225], v[44:47]
	v_mfma_f32_16x16x32_bf16 v[40:43], v[198:201], v[222:225], v[40:43]
	v_mfma_f32_16x16x32_bf16 v[36:39], v[186:189], v[230:233], v[36:39]
	v_mfma_f32_16x16x32_bf16 v[32:35], v[198:201], v[230:233], v[32:35]
	s_setprio 0
	s_barrier
	s_add_i32 s51, s41, s26
	v_lshl_add_u64 v[194:195], s[52:53], 0, v[132:133]
	s_mov_b32 m0, s51
	ds_read_b128 v[202:205], v164 offset:16384
	ds_read_b128 v[206:209], v164 offset:17408
	ds_read_b128 v[210:213], v164 offset:18432
	ds_read_b128 v[214:217], v164 offset:19456
	ds_read_b128 v[218:221], v164 offset:20480
	ds_read_b128 v[222:225], v164 offset:21504
	ds_read_b128 v[226:229], v164 offset:22528
	ds_read_b128 v[230:233], v164 offset:23552
	global_load_lds_dwordx4 v[194:195], off
	s_add_i32 m0, s51, 0x2000
	v_lshl_add_u64 v[234:235], s[52:53], 0, v[128:129]
	s_add_u32 s52, s52, s10
	s_addc_u32 s53, s53, s11
	s_add_i32 s51, s42, s26
	global_load_lds_dwordx4 v[234:235], off
	v_lshl_add_u64 v[236:237], s[52:53], 0, v[132:133]
	s_mov_b32 m0, s51
	v_lshl_add_u64 v[238:239], s[52:53], 0, v[128:129]
	global_load_lds_dwordx4 v[236:237], off
	s_add_i32 m0, s51, 0x2000
	v_lshl_add_u64 v[240:241], s[24:25], 0, v[134:135]
	global_load_lds_dwordx4 v[238:239], off
	s_mov_b32 m0, s27
	v_lshl_add_u64 v[242:243], s[24:25], 0, v[130:131]
	global_load_lds_dwordx4 v[240:241], off
	s_mov_b32 m0, s30
	s_nop 0
	global_load_lds_dwordx4 v[242:243], off
	s_waitcnt vmcnt(8)
	s_waitcnt lgkmcnt(0)
	s_barrier
; #define PG8_STAGE(bufoff, gbase, voff) do { _Pragma("unroll") for (int _i = 0; _i < 2; ++_i) \
;         __builtin_amdgcn_global_load_lds((const unsigned*)((const char*)(gbase) + (voff)[_i]), (PG8_LAS unsigned*)(lds + (bufoff) + ldsw + _i * 8192), 16, 0, 0); } while (0)
; #define PG8_LDA(dst, b, h) do { _Pragma("unroll") for (int m = 0; m < 4; ++m) _Pragma("unroll") for (int k = 0; k < 2; ++k) dst[m][k] = *(const PG8_LAS bf16x8*)(lds + PG8_SA(b, h) + aoff + m * 2048 + k * 1024); } while (0)
; #define PG8_LDB(dst, b, h) do { _Pragma("unroll") for (int n = 0; n < 2; ++n) _Pragma("unroll") for (int k = 0; k < 2; ++k) dst[n][k] = *(const PG8_LAS bf16x8*)(lds + PG8_SB(b, h) + boff + n * 2048 + k * 1024); } while (0)
; #define PG8_MMA(ai, bj, At, Bt) do { __builtin_amdgcn_s_setprio(1); _Pragma("unroll") for (int m = 0; m < 4; ++m) _Pragma("unroll") for (int n = 0; n < 2; ++n) _Pragma("unroll") for (int k = 0; k < 2; ++k) \
;         acc[ai][bj][m][n] = __builtin_amdgcn_mfma_f32_16x16x32_bf16(Bt[n][k], At[m][k], acc[ai][bj][m][n], 0, 0, 0); __builtin_amdgcn_s_setprio(0); } while (0)
; #define PG8_WAIT_V(n) asm volatile("s_waitcnt vmcnt(" #n ")" ::: "memory")
; #define PG8_WAIT_L(n) asm volatile("s_waitcnt lgkmcnt(" #n ")" ::: "memory")
; #define PG8_BAR __builtin_amdgcn_s_barrier()
; #define PG8_SCHED __builtin_amdgcn_sched_barrier(0)
; template <class Epi, class Sched, bool ALIGN_EPI = false, bool SP2 = false>
; __device__ __forceinline__ void gemm_phase(PG8_LAS unsigned char* lds, const Gemm g, const Sched& S, const Epi& E) {
;     ...
;             PG8_WAIT_V(8); PG8_WAIT_L(0); PG8_BAR; PG8_MMA(1, 0, At, B0); PG8_MMA(1, 1, At, B1); PG8_BAR; PG8_SCHED;
;             PG8_LDB(B0, 1, 0); PG8_LDB(B1, 1, 1); PG8_SCHED; PG8_LDA(At, 1, 0); PG8_STAGE(PG8_SA(0, 1), a2 + hstep, voffA);
;             PG8_WAIT_V(8); PG8_WAIT_L(0); PG8_BAR; PG8_MMA(0, 0, At, B0); PG8_MMA(0, 1, At, B1); PG8_BAR; PG8_SCHED;
	s_setprio 1
	s_waitcnt lgkmcnt(0)
	v_mfma_f32_16x16x32_bf16 v[92:95], v[166:169], v[202:205], v[92:95]
	v_mfma_f32_16x16x32_bf16 v[88:91], v[174:177], v[202:205], v[88:91]
	v_mfma_f32_16x16x32_bf16 v[84:87], v[166:169], v[210:213], v[84:87]
	v_mfma_f32_16x16x32_bf16 v[80:83], v[174:177], v[210:213], v[80:83]
	v_mfma_f32_16x16x32_bf16 v[76:79], v[166:169], v[218:221], v[76:79]
	v_mfma_f32_16x16x32_bf16 v[72:75], v[174:177], v[218:221], v[72:75]
	v_mfma_f32_16x16x32_bf16 v[68:71], v[166:169], v[226:229], v[68:71]
	v_mfma_f32_16x16x32_bf16 v[64:67], v[174:177], v[226:229], v[64:67]
	v_mfma_f32_16x16x32_bf16 v[92:95], v[170:173], v[206:209], v[92:95]
	v_mfma_f32_16x16x32_bf16 v[88:91], v[178:181], v[206:209], v[88:91]
	v_mfma_f32_16x16x32_bf16 v[84:87], v[170:173], v[214:217], v[84:87]
	v_mfma_f32_16x16x32_bf16 v[80:83], v[178:181], v[214:217], v[80:83]
	v_mfma_f32_16x16x32_bf16 v[76:79], v[170:173], v[222:225], v[76:79]
	v_mfma_f32_16x16x32_bf16 v[72:75], v[178:181], v[222:225], v[72:75]
	v_mfma_f32_16x16x32_bf16 v[68:71], v[170:173], v[230:233], v[68:71]
	v_mfma_f32_16x16x32_bf16 v[64:67], v[178:181], v[230:233], v[64:67]
	s_setprio 0
	s_setprio 1
	v_mfma_f32_16x16x32_bf16 v[28:31], v[182:185], v[202:205], v[28:31]
	v_mfma_f32_16x16x32_bf16 v[24:27], v[190:193], v[202:205], v[24:27]
	v_mfma_f32_16x16x32_bf16 v[20:23], v[182:185], v[210:213], v[20:23]
	v_mfma_f32_16x16x32_bf16 v[16:19], v[190:193], v[210:213], v[16:19]
	v_mfma_f32_16x16x32_bf16 v[12:15], v[182:185], v[218:221], v[12:15]
	v_mfma_f32_16x16x32_bf16 v[8:11], v[190:193], v[218:221], v[8:11]
	v_mfma_f32_16x16x32_bf16 v[4:7], v[182:185], v[226:229], v[4:7]
	v_mfma_f32_16x16x32_bf16 v[0:3], v[190:193], v[226:229], v[0:3]
	v_mfma_f32_16x16x32_bf16 v[28:31], v[186:189], v[206:209], v[28:31]
	v_mfma_f32_16x16x32_bf16 v[24:27], v[198:201], v[206:209], v[24:27]
	v_mfma_f32_16x16x32_bf16 v[20:23], v[186:189], v[214:217], v[20:23]
	v_mfma_f32_16x16x32_bf16 v[16:19], v[198:201], v[214:217], v[16:19]
	v_mfma_f32_16x16x32_bf16 v[12:15], v[186:189], v[222:225], v[12:15]
	v_mfma_f32_16x16x32_bf16 v[8:11], v[198:201], v[222:225], v[8:11]
	v_mfma_f32_16x16x32_bf16 v[4:7], v[186:189], v[230:233], v[4:7]
	v_mfma_f32_16x16x32_bf16 v[0:3], v[198:201], v[230:233], v[0:3]
	s_setprio 0
	s_barrier
	s_add_i32 s51, 0, 0x18000
	v_add_u32_e32 v165, s51, v161
	s_add_i32 s52, 0, 0x1c000
	ds_read_b128 v[166:169], v165
	ds_read_b128 v[170:173], v165 offset:1024
	ds_read_b128 v[174:177], v165 offset:2048
	ds_read_b128 v[178:181], v165 offset:3072
	v_add_u32_e32 v165, s52, v161
	ds_read_b128 v[182:185], v165
	ds_read_b128 v[186:189], v165 offset:1024
	ds_read_b128 v[190:193], v165 offset:2048
	ds_read_b128 v[198:201], v165 offset:3072
	s_add_u32 s24, s24, s10
	s_addc_u32 s25, s25, s11
	s_mov_b32 m0, s31
	v_lshl_add_u64 v[244:245], s[24:25], 0, v[134:135]
	ds_read_b128 v[202:205], v164 offset:32768
	ds_read_b128 v[206:209], v164 offset:33792
	ds_read_b128 v[210:213], v164 offset:34816
	ds_read_b128 v[214:217], v164 offset:35840
	ds_read_b128 v[218:221], v164 offset:36864
	ds_read_b128 v[222:225], v164 offset:37888
	ds_read_b128 v[226:229], v164 offset:38912
	ds_read_b128 v[230:233], v164 offset:39936
	global_load_lds_dwordx4 v[244:245], off
	v_lshl_add_u64 v[244:245], s[24:25], 0, v[130:131]
	s_mov_b32 m0, s34
	s_nop 0
	global_load_lds_dwordx4 v[244:245], off
	s_waitcnt vmcnt(8)
	s_waitcnt lgkmcnt(0)
	s_barrier
	s_setprio 1
	s_waitcnt lgkmcnt(0)
	v_mfma_f32_16x16x32_bf16 v[124:127], v[166:169], v[202:205], v[124:127]
	v_mfma_f32_16x16x32_bf16 v[120:123], v[174:177], v[202:205], v[120:123]
	v_mfma_f32_16x16x32_bf16 v[116:119], v[166:169], v[210:213], v[116:119]
	v_mfma_f32_16x16x32_bf16 v[112:115], v[174:177], v[210:213], v[112:115]
	v_mfma_f32_16x16x32_bf16 v[108:111], v[166:169], v[218:221], v[108:111]
	v_mfma_f32_16x16x32_bf16 v[104:107], v[174:177], v[218:221], v[104:107]
	v_mfma_f32_16x16x32_bf16 v[100:103], v[166:169], v[226:229], v[100:103]
	v_mfma_f32_16x16x32_bf16 v[96:99], v[174:177], v[226:229], v[96:99]
	v_mfma_f32_16x16x32_bf16 v[124:127], v[170:173], v[206:209], v[124:127]
	v_mfma_f32_16x16x32_bf16 v[120:123], v[178:181], v[206:209], v[120:123]
	v_mfma_f32_16x16x32_bf16 v[116:119], v[170:173], v[214:217], v[116:119]
	v_mfma_f32_16x16x32_bf16 v[112:115], v[178:181], v[214:217], v[112:115]
	v_mfma_f32_16x16x32_bf16 v[108:111], v[170:173], v[222:225], v[108:111]
	v_mfma_f32_16x16x32_bf16 v[104:107], v[178:181], v[222:225], v[104:107]
	v_mfma_f32_16x16x32_bf16 v[100:103], v[170:173], v[230:233], v[100:103]
	v_mfma_f32_16x16x32_bf16 v[96:99], v[178:181], v[230:233], v[96:99]
	s_setprio 0
	s_setprio 1
	v_mfma_f32_16x16x32_bf16 v[60:63], v[182:185], v[202:205], v[60:63]
	v_mfma_f32_16x16x32_bf16 v[56:59], v[190:193], v[202:205], v[56:59]
	v_mfma_f32_16x16x32_bf16 v[52:55], v[182:185], v[210:213], v[52:55]
	v_mfma_f32_16x16x32_bf16 v[48:51], v[190:193], v[210:213], v[48:51]
	v_mfma_f32_16x16x32_bf16 v[44:47], v[182:185], v[218:221], v[44:47]
	v_mfma_f32_16x16x32_bf16 v[40:43], v[190:193], v[218:221], v[40:43]
	v_mfma_f32_16x16x32_bf16 v[36:39], v[182:185], v[226:229], v[36:39]
	v_mfma_f32_16x16x32_bf16 v[32:35], v[190:193], v[226:229], v[32:35]
	v_mfma_f32_16x16x32_bf16 v[60:63], v[186:189], v[206:209], v[60:63]
	v_mfma_f32_16x16x32_bf16 v[56:59], v[198:201], v[206:209], v[56:59]
	v_mfma_f32_16x16x32_bf16 v[52:55], v[186:189], v[214:217], v[52:55]
	v_mfma_f32_16x16x32_bf16 v[48:51], v[198:201], v[214:217], v[48:51]
	v_mfma_f32_16x16x32_bf16 v[44:47], v[186:189], v[222:225], v[44:47]
	v_mfma_f32_16x16x32_bf16 v[40:43], v[198:201], v[222:225], v[40:43]
	v_mfma_f32_16x16x32_bf16 v[36:39], v[186:189], v[230:233], v[36:39]
	v_mfma_f32_16x16x32_bf16 v[32:35], v[198:201], v[230:233], v[32:35]
	s_setprio 0
	s_barrier
; #define PG8_STAGE(bufoff, gbase, voff) do { _Pragma("unroll") for (int _i = 0; _i < 2; ++_i) \
;         __builtin_amdgcn_global_load_lds((const unsigned*)((const char*)(gbase) + (voff)[_i]), (PG8_LAS unsigned*)(lds + (bufoff) + ldsw + _i * 8192), 16, 0, 0); } while (0)
; #define PG8_LDA(dst, b, h) do { _Pragma("unroll") for (int m = 0; m < 4; ++m) _Pragma("unroll") for (int k = 0; k < 2; ++k) dst[m][k] = *(const PG8_LAS bf16x8*)(lds + PG8_SA(b, h) + aoff + m * 2048 + k * 1024); } while (0)
; #define PG8_MMA(ai, bj, At, Bt) do { __builtin_amdgcn_s_setprio(1); _Pragma("unroll") for (int m = 0; m < 4; ++m) _Pragma("unroll") for (int n = 0; n < 2; ++n) _Pragma("unroll") for (int k = 0; k < 2; ++k) \
;         acc[ai][bj][m][n] = __builtin_amdgcn_mfma_f32_16x16x32_bf16(Bt[n][k], At[m][k], acc[ai][bj][m][n], 0, 0, 0); __builtin_amdgcn_s_setprio(0); } while (0)
; #define PG8_WAIT_V(n) asm volatile("s_waitcnt vmcnt(" #n ")" ::: "memory")
; #define PG8_WAIT_L(n) asm volatile("s_waitcnt lgkmcnt(" #n ")" ::: "memory")
; #define PG8_BAR __builtin_amdgcn_s_barrier()
; #define PG8_SCHED __builtin_amdgcn_sched_barrier(0)
; template <class Epi, class Sched, bool ALIGN_EPI = false, bool SP2 = false>
; __device__ __forceinline__ void gemm_phase(PG8_LAS unsigned char* lds, const Gemm g, const Sched& S, const Epi& E) {
;     ...
;             PG8_LDA(At, 1, 1); PG8_STAGE(PG8_SB(1, 0), b3, voffB); PG8_STAGE(PG8_SB(1, 1), b3 + hstep, voffB); PG8_STAGE(PG8_SA(1, 0), a3, voffA);
;             PG8_WAIT_V(8); PG8_WAIT_L(0); PG8_BAR; PG8_MMA(1, 0, At, B0); PG8_MMA(1, 1, At, B1); PG8_BAR; PG8_SCHED;
	s_add_i32 s24, s51, s26
	v_lshl_add_u64 v[194:195], v[194:195], 0, s[16:17]
	s_mov_b32 m0, s24
	ds_read_b128 v[202:205], v164 offset:49152
	ds_read_b128 v[206:209], v164 offset:50176
	ds_read_b128 v[210:213], v164 offset:51200
	ds_read_b128 v[214:217], v164 offset:52224
	ds_read_b128 v[218:221], v164 offset:53248
	ds_read_b128 v[222:225], v164 offset:54272
	ds_read_b128 v[226:229], v164 offset:55296
	ds_read_b128 v[230:233], v164 offset:56320
	global_load_lds_dwordx4 v[194:195], off
	v_lshl_add_u64 v[194:195], v[234:235], 0, s[16:17]
	s_add_i32 m0, s24, 0x2000
	s_add_i32 s24, s52, s26
	global_load_lds_dwordx4 v[194:195], off
	v_lshl_add_u64 v[194:195], v[236:237], 0, s[16:17]
	s_mov_b32 m0, s24
	s_nop 0
	global_load_lds_dwordx4 v[194:195], off
	v_lshl_add_u64 v[194:195], v[238:239], 0, s[16:17]
	s_add_i32 m0, s24, 0x2000
	s_nop 0
	global_load_lds_dwordx4 v[194:195], off
	v_lshl_add_u64 v[194:195], v[240:241], 0, s[16:17]
	s_mov_b32 m0, s36
	s_nop 0
	global_load_lds_dwordx4 v[194:195], off
	v_lshl_add_u64 v[194:195], v[242:243], 0, s[16:17]
	s_mov_b32 m0, s37
	s_nop 0
	global_load_lds_dwordx4 v[194:195], off
	s_waitcnt vmcnt(8)
	s_waitcnt lgkmcnt(0)
	s_barrier
	s_setprio 1
	s_waitcnt lgkmcnt(0)
	v_mfma_f32_16x16x32_bf16 v[92:95], v[166:169], v[202:205], v[92:95]
	v_mfma_f32_16x16x32_bf16 v[88:91], v[174:177], v[202:205], v[88:91]
	v_mfma_f32_16x16x32_bf16 v[84:87], v[166:169], v[210:213], v[84:87]
	v_mfma_f32_16x16x32_bf16 v[80:83], v[174:177], v[210:213], v[80:83]
	v_mfma_f32_16x16x32_bf16 v[76:79], v[166:169], v[218:221], v[76:79]
	v_mfma_f32_16x16x32_bf16 v[72:75], v[174:177], v[218:221], v[72:75]
	v_mfma_f32_16x16x32_bf16 v[68:71], v[166:169], v[226:229], v[68:71]
	v_mfma_f32_16x16x32_bf16 v[64:67], v[174:177], v[226:229], v[64:67]
	v_mfma_f32_16x16x32_bf16 v[92:95], v[170:173], v[206:209], v[92:95]
	v_mfma_f32_16x16x32_bf16 v[88:91], v[178:181], v[206:209], v[88:91]
	v_mfma_f32_16x16x32_bf16 v[84:87], v[170:173], v[214:217], v[84:87]
	v_mfma_f32_16x16x32_bf16 v[80:83], v[178:181], v[214:217], v[80:83]
	v_mfma_f32_16x16x32_bf16 v[76:79], v[170:173], v[222:225], v[76:79]
	v_mfma_f32_16x16x32_bf16 v[72:75], v[178:181], v[222:225], v[72:75]
	v_mfma_f32_16x16x32_bf16 v[68:71], v[170:173], v[230:233], v[68:71]
	v_mfma_f32_16x16x32_bf16 v[64:67], v[178:181], v[230:233], v[64:67]
	s_setprio 0
	s_setprio 1
	v_mfma_f32_16x16x32_bf16 v[28:31], v[182:185], v[202:205], v[28:31]
	v_mfma_f32_16x16x32_bf16 v[24:27], v[190:193], v[202:205], v[24:27]
	v_mfma_f32_16x16x32_bf16 v[20:23], v[182:185], v[210:213], v[20:23]
	v_mfma_f32_16x16x32_bf16 v[16:19], v[190:193], v[210:213], v[16:19]
	v_mfma_f32_16x16x32_bf16 v[12:15], v[182:185], v[218:221], v[12:15]
	v_mfma_f32_16x16x32_bf16 v[8:11], v[190:193], v[218:221], v[8:11]
	v_mfma_f32_16x16x32_bf16 v[4:7], v[182:185], v[226:229], v[4:7]
	v_mfma_f32_16x16x32_bf16 v[0:3], v[190:193], v[226:229], v[0:3]
	v_mfma_f32_16x16x32_bf16 v[28:31], v[186:189], v[206:209], v[28:31]
	v_mfma_f32_16x16x32_bf16 v[24:27], v[198:201], v[206:209], v[24:27]
	v_mfma_f32_16x16x32_bf16 v[20:23], v[186:189], v[214:217], v[20:23]
	v_mfma_f32_16x16x32_bf16 v[16:19], v[198:201], v[214:217], v[16:19]
	v_mfma_f32_16x16x32_bf16 v[12:15], v[186:189], v[222:225], v[12:15]
	v_mfma_f32_16x16x32_bf16 v[8:11], v[198:201], v[222:225], v[8:11]
	v_mfma_f32_16x16x32_bf16 v[4:7], v[186:189], v[230:233], v[4:7]
	v_mfma_f32_16x16x32_bf16 v[0:3], v[198:201], v[230:233], v[0:3]
	s_setprio 0
	s_add_u32 s22, s22, 0x100
	s_addc_u32 s23, s23, 0
	s_add_u32 s48, s48, 0x100
	s_addc_u32 s49, s49, 0
	s_cmp_ge_i32 s50, s38
	s_mov_b32 s24, s50
	s_barrier
	s_cbranch_scc0 .LBB0_731

; #define PG8_STAGE(bufoff, gbase, voff) do { _Pragma("unroll") for (int _i = 0; _i < 2; ++_i) \
;         __builtin_amdgcn_global_load_lds((const unsigned*)((const char*)(gbase) + (voff)[_i]), (PG8_LAS unsigned*)(lds + (bufoff) + ldsw + _i * 8192), 16, 0, 0); } while (0)
; #define PG8_LDA(dst, b, h) do { _Pragma("unroll") for (int m = 0; m < 4; ++m) _Pragma("unroll") for (int k = 0; k < 2; ++k) dst[m][k] = *(const PG8_LAS bf16x8*)(lds + PG8_SA(b, h) + aoff + m * 2048 + k * 1024); } while (0)
; #define PG8_LDB(dst, b, h) do { _Pragma("unroll") for (int n = 0; n < 2; ++n) _Pragma("unroll") for (int k = 0; k < 2; ++k) dst[n][k] = *(const PG8_LAS bf16x8*)(lds + PG8_SB(b, h) + boff + n * 2048 + k * 1024); } while (0)
; #define PG8_MMA(ai, bj, At, Bt) do { __builtin_amdgcn_s_setprio(1); _Pragma("unroll") for (int m = 0; m < 4; ++m) _Pragma("unroll") for (int n = 0; n < 2; ++n) _Pragma("unroll") for (int k = 0; k < 2; ++k) \
;         acc[ai][bj][m][n] = __builtin_amdgcn_mfma_f32_16x16x32_bf16(Bt[n][k], At[m][k], acc[ai][bj][m][n], 0, 0, 0); __builtin_amdgcn_s_setprio(0); } while (0)
; #define PG8_WAIT_V(n) asm volatile("s_waitcnt vmcnt(" #n ")" ::: "memory")
; #define PG8_WAIT_L(n) asm volatile("s_waitcnt lgkmcnt(" #n ")" ::: "memory")
; #define PG8_BAR __builtin_amdgcn_s_barrier()
; template <class Epi, class Sched, bool ALIGN_EPI = false, bool SP2 = false>
; __device__ __forceinline__ void gemm_phase(PG8_LAS unsigned char* lds, const Gemm g, const Sched& S, const Epi& E) {
;     ...
;             const char* a1 = cA + (size_t)(t + 1) * kstep;
;             const char* a2 = last ? nA : cA + (size_t)(t + 2) * kstep; const char* b2 = last ? nB : cB + (size_t)(t + 2) * kstep;
;             const char* a3 = a2 + kstep; const char* b3 = b2 + kstep;
;             if (last && has_next) S.a_ready(nxt);
;             if constexpr (SP2) {
;             PG8_LDB(B0, 0, 0); PG8_LDB(B1, 0, 1); PG8_SCHED; PG8_LDA(At, 0, 0); PG8_STAGE(PG8_SA(1, 1), a1 + hstep, voffA);
;             PG8_WAIT_V(8); PG8_WAIT_L(0); PG8_BAR; PG8_MMA(0, 0, At, B0); PG8_MMA(0, 1, At, B1); PG8_BAR; PG8_SCHED;
;             PG8_LDA(At, 0, 1); PG8_STAGE(PG8_SB(0, 0), b2, voffB); PG8_STAGE(PG8_SB(0, 1), b2 + hstep, voffB); PG8_STAGE(PG8_SA(0, 0), a2, voffA);
;             PG8_WAIT_V(8); PG8_WAIT_L(0); PG8_BAR; PG8_MMA(1, 0, At, B0); PG8_MMA(1, 1, At, B1); PG8_BAR; PG8_SCHED;
.LBB0_757:
	ds_read_b128 v[150:153], v146
	ds_read_b128 v[154:157], v146 offset:1024
	ds_read_b128 v[158:161], v146 offset:2048
	ds_read_b128 v[162:165], v146 offset:3072
	ds_read_b128 v[166:169], v147
	ds_read_b128 v[170:173], v147 offset:1024
	ds_read_b128 v[174:177], v147 offset:2048
	ds_read_b128 v[178:181], v147 offset:3072
	s_add_i32 s53, s24, 2
	s_add_u32 s54, s22, 0x80
	s_addc_u32 s25, s23, 0
	s_cmp_eq_u32 s43, s24
	s_cselect_b32 s24, s2, s54
	s_cselect_b32 s25, s3, s25
	s_cselect_b32 s55, s21, s52
	s_cselect_b32 s54, s20, s51
	v_lshl_add_u64 v[194:195], s[22:23], 0, v[136:137]
	s_add_i32 m0, s31, 0xc000
	ds_read_b128 v[182:185], v148
	ds_read_b128 v[186:189], v148 offset:1024
	ds_read_b128 v[190:193], v148 offset:2048
	ds_read_b128 v[198:201], v148 offset:3072
	ds_read_b128 v[202:205], v148 offset:4096
	ds_read_b128 v[206:209], v148 offset:5120
	ds_read_b128 v[210:213], v148 offset:6144
	ds_read_b128 v[214:217], v148 offset:7168
	global_load_lds_dwordx4 v[194:195], off
	v_lshl_add_u64 v[194:195], s[22:23], 0, v[138:139]
	s_add_i32 m0, s31, 0xe000
	s_nop 0
	global_load_lds_dwordx4 v[194:195], off
	s_waitcnt vmcnt(8)
	s_waitcnt lgkmcnt(0)
	s_barrier
	s_setprio 1
	s_waitcnt lgkmcnt(0)
	v_mfma_f32_16x16x32_bf16 v[120:123], v[150:153], v[182:185], v[120:123]
	v_mfma_f32_16x16x32_bf16 v[124:127], v[158:161], v[182:185], v[124:127]
	v_mfma_f32_16x16x32_bf16 v[116:119], v[150:153], v[190:193], v[116:119]
	v_mfma_f32_16x16x32_bf16 v[112:115], v[158:161], v[190:193], v[112:115]
	v_mfma_f32_16x16x32_bf16 v[108:111], v[150:153], v[202:205], v[108:111]
	v_mfma_f32_16x16x32_bf16 v[104:107], v[158:161], v[202:205], v[104:107]
	v_mfma_f32_16x16x32_bf16 v[100:103], v[150:153], v[210:213], v[100:103]
	v_mfma_f32_16x16x32_bf16 v[96:99], v[158:161], v[210:213], v[96:99]
	v_mfma_f32_16x16x32_bf16 v[120:123], v[154:157], v[186:189], v[120:123]
	v_mfma_f32_16x16x32_bf16 v[124:127], v[162:165], v[186:189], v[124:127]
	v_mfma_f32_16x16x32_bf16 v[116:119], v[154:157], v[198:201], v[116:119]
	v_mfma_f32_16x16x32_bf16 v[112:115], v[162:165], v[198:201], v[112:115]
	v_mfma_f32_16x16x32_bf16 v[108:111], v[154:157], v[206:209], v[108:111]
	v_mfma_f32_16x16x32_bf16 v[104:107], v[162:165], v[206:209], v[104:107]
	v_mfma_f32_16x16x32_bf16 v[100:103], v[154:157], v[214:217], v[100:103]
	v_mfma_f32_16x16x32_bf16 v[96:99], v[162:165], v[214:217], v[96:99]
	s_setprio 0
	s_setprio 1
	v_mfma_f32_16x16x32_bf16 v[60:63], v[166:169], v[182:185], v[60:63]
	v_mfma_f32_16x16x32_bf16 v[56:59], v[174:177], v[182:185], v[56:59]
	v_mfma_f32_16x16x32_bf16 v[52:55], v[166:169], v[190:193], v[52:55]
	v_mfma_f32_16x16x32_bf16 v[48:51], v[174:177], v[190:193], v[48:51]
	v_mfma_f32_16x16x32_bf16 v[44:47], v[166:169], v[202:205], v[44:47]
	v_mfma_f32_16x16x32_bf16 v[40:43], v[174:177], v[202:205], v[40:43]
	v_mfma_f32_16x16x32_bf16 v[36:39], v[166:169], v[210:213], v[36:39]
	v_mfma_f32_16x16x32_bf16 v[32:35], v[174:177], v[210:213], v[32:35]
	v_mfma_f32_16x16x32_bf16 v[60:63], v[170:173], v[186:189], v[60:63]
	v_mfma_f32_16x16x32_bf16 v[56:59], v[178:181], v[186:189], v[56:59]
	v_mfma_f32_16x16x32_bf16 v[52:55], v[170:173], v[198:201], v[52:55]
	v_mfma_f32_16x16x32_bf16 v[48:51], v[178:181], v[198:201], v[48:51]
	v_mfma_f32_16x16x32_bf16 v[44:47], v[170:173], v[206:209], v[44:47]
	v_mfma_f32_16x16x32_bf16 v[40:43], v[178:181], v[206:209], v[40:43]
	v_mfma_f32_16x16x32_bf16 v[36:39], v[170:173], v[214:217], v[36:39]
	v_mfma_f32_16x16x32_bf16 v[32:35], v[178:181], v[214:217], v[32:35]
	s_setprio 0
	s_barrier
	s_add_i32 s56, s44, s27
	v_lshl_add_u64 v[194:195], s[54:55], 0, v[132:133]
	s_mov_b32 m0, s56
	ds_read_b128 v[182:185], v148 offset:16384
	ds_read_b128 v[186:189], v148 offset:17408
	ds_read_b128 v[190:193], v148 offset:18432
	ds_read_b128 v[198:201], v148 offset:19456
	ds_read_b128 v[202:205], v148 offset:20480
	ds_read_b128 v[206:209], v148 offset:21504
	ds_read_b128 v[210:213], v148 offset:22528
	ds_read_b128 v[214:217], v148 offset:23552
	global_load_lds_dwordx4 v[194:195], off
	s_add_i32 m0, s56, 0x2000
	v_lshl_add_u64 v[218:219], s[54:55], 0, v[128:129]
	s_add_u32 s54, s54, s4
	s_addc_u32 s55, s55, s5
	s_add_i32 s56, s45, s27
	global_load_lds_dwordx4 v[218:219], off
	v_lshl_add_u64 v[220:221], s[54:55], 0, v[132:133]
	s_mov_b32 m0, s56
	v_lshl_add_u64 v[222:223], s[54:55], 0, v[128:129]
	global_load_lds_dwordx4 v[220:221], off
	s_add_i32 m0, s56, 0x2000
	v_lshl_add_u64 v[224:225], s[24:25], 0, v[134:135]
	global_load_lds_dwordx4 v[222:223], off
	s_mov_b32 m0, s31
	v_lshl_add_u64 v[226:227], s[24:25], 0, v[130:131]
	global_load_lds_dwordx4 v[224:225], off
	s_mov_b32 m0, s34
	s_nop 0
	global_load_lds_dwordx4 v[226:227], off
	s_waitcnt vmcnt(8)
	s_waitcnt lgkmcnt(0)
	s_barrier
; #define PG8_STAGE(bufoff, gbase, voff) do { _Pragma("unroll") for (int _i = 0; _i < 2; ++_i) \
;         __builtin_amdgcn_global_load_lds((const unsigned*)((const char*)(gbase) + (voff)[_i]), (PG8_LAS unsigned*)(lds + (bufoff) + ldsw + _i * 8192), 16, 0, 0); } while (0)
; #define PG8_LDA(dst, b, h) do { _Pragma("unroll") for (int m = 0; m < 4; ++m) _Pragma("unroll") for (int k = 0; k < 2; ++k) dst[m][k] = *(const PG8_LAS bf16x8*)(lds + PG8_SA(b, h) + aoff + m * 2048 + k * 1024); } while (0)
; #define PG8_LDB(dst, b, h) do { _Pragma("unroll") for (int n = 0; n < 2; ++n) _Pragma("unroll") for (int k = 0; k < 2; ++k) dst[n][k] = *(const PG8_LAS bf16x8*)(lds + PG8_SB(b, h) + boff + n * 2048 + k * 1024); } while (0)
; #define PG8_MMA(ai, bj, At, Bt) do { __builtin_amdgcn_s_setprio(1); _Pragma("unroll") for (int m = 0; m < 4; ++m) _Pragma("unroll") for (int n = 0; n < 2; ++n) _Pragma("unroll") for (int k = 0; k < 2; ++k) \
;         acc[ai][bj][m][n] = __builtin_amdgcn_mfma_f32_16x16x32_bf16(Bt[n][k], At[m][k], acc[ai][bj][m][n], 0, 0, 0); __builtin_amdgcn_s_setprio(0); } while (0)
; #define PG8_WAIT_V(n) asm volatile("s_waitcnt vmcnt(" #n ")" ::: "memory")
; #define PG8_WAIT_L(n) asm volatile("s_waitcnt lgkmcnt(" #n ")" ::: "memory")
; #define PG8_BAR __builtin_amdgcn_s_barrier()
; #define PG8_SCHED __builtin_amdgcn_sched_barrier(0)
; template <class Epi, class Sched, bool ALIGN_EPI = false, bool SP2 = false>
; __device__ __forceinline__ void gemm_phase(PG8_LAS unsigned char* lds, const Gemm g, const Sched& S, const Epi& E) {
;     ...
;             PG8_WAIT_V(8); PG8_WAIT_L(0); PG8_BAR; PG8_MMA(1, 0, At, B0); PG8_MMA(1, 1, At, B1); PG8_BAR; PG8_SCHED;
;             PG8_LDB(B0, 1, 0); PG8_LDB(B1, 1, 1); PG8_SCHED; PG8_LDA(At, 1, 0); PG8_STAGE(PG8_SA(0, 1), a2 + hstep, voffA);
;             PG8_WAIT_V(8); PG8_WAIT_L(0); PG8_BAR; PG8_MMA(0, 0, At, B0); PG8_MMA(0, 1, At, B1); PG8_BAR; PG8_SCHED;
	s_setprio 1
	s_waitcnt lgkmcnt(0)
	v_mfma_f32_16x16x32_bf16 v[92:95], v[150:153], v[182:185], v[92:95]
	v_mfma_f32_16x16x32_bf16 v[88:91], v[158:161], v[182:185], v[88:91]
	v_mfma_f32_16x16x32_bf16 v[84:87], v[150:153], v[190:193], v[84:87]
	v_mfma_f32_16x16x32_bf16 v[80:83], v[158:161], v[190:193], v[80:83]
	v_mfma_f32_16x16x32_bf16 v[76:79], v[150:153], v[202:205], v[76:79]
	v_mfma_f32_16x16x32_bf16 v[72:75], v[158:161], v[202:205], v[72:75]
	v_mfma_f32_16x16x32_bf16 v[68:71], v[150:153], v[210:213], v[68:71]
	v_mfma_f32_16x16x32_bf16 v[64:67], v[158:161], v[210:213], v[64:67]
	v_mfma_f32_16x16x32_bf16 v[92:95], v[154:157], v[186:189], v[92:95]
	v_mfma_f32_16x16x32_bf16 v[88:91], v[162:165], v[186:189], v[88:91]
	v_mfma_f32_16x16x32_bf16 v[84:87], v[154:157], v[198:201], v[84:87]
	v_mfma_f32_16x16x32_bf16 v[80:83], v[162:165], v[198:201], v[80:83]
	v_mfma_f32_16x16x32_bf16 v[76:79], v[154:157], v[206:209], v[76:79]
	v_mfma_f32_16x16x32_bf16 v[72:75], v[162:165], v[206:209], v[72:75]
	v_mfma_f32_16x16x32_bf16 v[68:71], v[154:157], v[214:217], v[68:71]
	v_mfma_f32_16x16x32_bf16 v[64:67], v[162:165], v[214:217], v[64:67]
	s_setprio 0
	s_setprio 1
	v_mfma_f32_16x16x32_bf16 v[28:31], v[166:169], v[182:185], v[28:31]
	v_mfma_f32_16x16x32_bf16 v[24:27], v[174:177], v[182:185], v[24:27]
	v_mfma_f32_16x16x32_bf16 v[20:23], v[166:169], v[190:193], v[20:23]
	v_mfma_f32_16x16x32_bf16 v[16:19], v[174:177], v[190:193], v[16:19]
	v_mfma_f32_16x16x32_bf16 v[12:15], v[166:169], v[202:205], v[12:15]
	v_mfma_f32_16x16x32_bf16 v[8:11], v[174:177], v[202:205], v[8:11]
	v_mfma_f32_16x16x32_bf16 v[4:7], v[166:169], v[210:213], v[4:7]
	v_mfma_f32_16x16x32_bf16 v[0:3], v[174:177], v[210:213], v[0:3]
	v_mfma_f32_16x16x32_bf16 v[28:31], v[170:173], v[186:189], v[28:31]
	v_mfma_f32_16x16x32_bf16 v[24:27], v[178:181], v[186:189], v[24:27]
	v_mfma_f32_16x16x32_bf16 v[20:23], v[170:173], v[198:201], v[20:23]
	v_mfma_f32_16x16x32_bf16 v[16:19], v[178:181], v[198:201], v[16:19]
	v_mfma_f32_16x16x32_bf16 v[12:15], v[170:173], v[206:209], v[12:15]
	v_mfma_f32_16x16x32_bf16 v[8:11], v[178:181], v[206:209], v[8:11]
	v_mfma_f32_16x16x32_bf16 v[4:7], v[170:173], v[214:217], v[4:7]
	v_mfma_f32_16x16x32_bf16 v[0:3], v[178:181], v[214:217], v[0:3]
	s_setprio 0
	s_barrier
	s_add_i32 s54, 0, 0x18000
	s_add_i32 s55, 0, 0x1c000
	v_add_u32_e32 v162, s54, v145
	v_add_u32_e32 v178, s55, v145
	ds_read_b128 v[150:153], v162
	ds_read_b128 v[154:157], v162 offset:1024
	ds_read_b128 v[158:161], v162 offset:2048
	ds_read_b128 v[162:165], v162 offset:3072
	ds_read_b128 v[166:169], v178
	ds_read_b128 v[170:173], v178 offset:1024
	ds_read_b128 v[174:177], v178 offset:2048
	ds_read_b128 v[178:181], v178 offset:3072
	s_add_u32 s24, s24, s4
	s_addc_u32 s25, s25, s5
	s_mov_b32 m0, s35
	v_lshl_add_u64 v[228:229], s[24:25], 0, v[134:135]
	ds_read_b128 v[182:185], v148 offset:32768
	ds_read_b128 v[186:189], v148 offset:33792
	ds_read_b128 v[190:193], v148 offset:34816
	ds_read_b128 v[198:201], v148 offset:35840
	ds_read_b128 v[202:205], v148 offset:36864
	ds_read_b128 v[206:209], v148 offset:37888
	ds_read_b128 v[210:213], v148 offset:38912
	ds_read_b128 v[214:217], v148 offset:39936
	global_load_lds_dwordx4 v[228:229], off
	v_lshl_add_u64 v[228:229], s[24:25], 0, v[130:131]
	s_mov_b32 m0, s36
	s_nop 0
	global_load_lds_dwordx4 v[228:229], off
	s_waitcnt vmcnt(8)
	s_waitcnt lgkmcnt(0)
	s_barrier
	s_setprio 1
	s_waitcnt lgkmcnt(0)
	v_mfma_f32_16x16x32_bf16 v[120:123], v[150:153], v[182:185], v[120:123]
	v_mfma_f32_16x16x32_bf16 v[124:127], v[158:161], v[182:185], v[124:127]
	v_mfma_f32_16x16x32_bf16 v[116:119], v[150:153], v[190:193], v[116:119]
	v_mfma_f32_16x16x32_bf16 v[112:115], v[158:161], v[190:193], v[112:115]
	v_mfma_f32_16x16x32_bf16 v[108:111], v[150:153], v[202:205], v[108:111]
	v_mfma_f32_16x16x32_bf16 v[104:107], v[158:161], v[202:205], v[104:107]
	v_mfma_f32_16x16x32_bf16 v[100:103], v[150:153], v[210:213], v[100:103]
	v_mfma_f32_16x16x32_bf16 v[96:99], v[158:161], v[210:213], v[96:99]
	v_mfma_f32_16x16x32_bf16 v[120:123], v[154:157], v[186:189], v[120:123]
	v_mfma_f32_16x16x32_bf16 v[124:127], v[162:165], v[186:189], v[124:127]
	v_mfma_f32_16x16x32_bf16 v[116:119], v[154:157], v[198:201], v[116:119]
	v_mfma_f32_16x16x32_bf16 v[112:115], v[162:165], v[198:201], v[112:115]
	v_mfma_f32_16x16x32_bf16 v[108:111], v[154:157], v[206:209], v[108:111]
	v_mfma_f32_16x16x32_bf16 v[104:107], v[162:165], v[206:209], v[104:107]
	v_mfma_f32_16x16x32_bf16 v[100:103], v[154:157], v[214:217], v[100:103]
	v_mfma_f32_16x16x32_bf16 v[96:99], v[162:165], v[214:217], v[96:99]
	s_setprio 0
	s_setprio 1
	v_mfma_f32_16x16x32_bf16 v[60:63], v[166:169], v[182:185], v[60:63]
	v_mfma_f32_16x16x32_bf16 v[56:59], v[174:177], v[182:185], v[56:59]
	v_mfma_f32_16x16x32_bf16 v[52:55], v[166:169], v[190:193], v[52:55]
	v_mfma_f32_16x16x32_bf16 v[48:51], v[174:177], v[190:193], v[48:51]
	v_mfma_f32_16x16x32_bf16 v[44:47], v[166:169], v[202:205], v[44:47]
	v_mfma_f32_16x16x32_bf16 v[40:43], v[174:177], v[202:205], v[40:43]
	v_mfma_f32_16x16x32_bf16 v[36:39], v[166:169], v[210:213], v[36:39]
	v_mfma_f32_16x16x32_bf16 v[32:35], v[174:177], v[210:213], v[32:35]
	v_mfma_f32_16x16x32_bf16 v[60:63], v[170:173], v[186:189], v[60:63]
	v_mfma_f32_16x16x32_bf16 v[56:59], v[178:181], v[186:189], v[56:59]
	v_mfma_f32_16x16x32_bf16 v[52:55], v[170:173], v[198:201], v[52:55]
	v_mfma_f32_16x16x32_bf16 v[48:51], v[178:181], v[198:201], v[48:51]
	v_mfma_f32_16x16x32_bf16 v[44:47], v[170:173], v[206:209], v[44:47]
	v_mfma_f32_16x16x32_bf16 v[40:43], v[178:181], v[206:209], v[40:43]
	v_mfma_f32_16x16x32_bf16 v[36:39], v[170:173], v[214:217], v[36:39]
	v_mfma_f32_16x16x32_bf16 v[32:35], v[178:181], v[214:217], v[32:35]
	s_setprio 0
	s_barrier
; #define PG8_STAGE(bufoff, gbase, voff) do { _Pragma("unroll") for (int _i = 0; _i < 2; ++_i) \
;         __builtin_amdgcn_global_load_lds((const unsigned*)((const char*)(gbase) + (voff)[_i]), (PG8_LAS unsigned*)(lds + (bufoff) + ldsw + _i * 8192), 16, 0, 0); } while (0)
; #define PG8_LDA(dst, b, h) do { _Pragma("unroll") for (int m = 0; m < 4; ++m) _Pragma("unroll") for (int k = 0; k < 2; ++k) dst[m][k] = *(const PG8_LAS bf16x8*)(lds + PG8_SA(b, h) + aoff + m * 2048 + k * 1024); } while (0)
; #define PG8_MMA(ai, bj, At, Bt) do { __builtin_amdgcn_s_setprio(1); _Pragma("unroll") for (int m = 0; m < 4; ++m) _Pragma("unroll") for (int n = 0; n < 2; ++n) _Pragma("unroll") for (int k = 0; k < 2; ++k) \
;         acc[ai][bj][m][n] = __builtin_amdgcn_mfma_f32_16x16x32_bf16(Bt[n][k], At[m][k], acc[ai][bj][m][n], 0, 0, 0); __builtin_amdgcn_s_setprio(0); } while (0)
; #define PG8_WAIT_V(n) asm volatile("s_waitcnt vmcnt(" #n ")" ::: "memory")
; #define PG8_WAIT_L(n) asm volatile("s_waitcnt lgkmcnt(" #n ")" ::: "memory")
; #define PG8_BAR __builtin_amdgcn_s_barrier()
; #define PG8_SCHED __builtin_amdgcn_sched_barrier(0)
; template <class Epi, class Sched, bool ALIGN_EPI = false, bool SP2 = false>
; __device__ __forceinline__ void gemm_phase(PG8_LAS unsigned char* lds, const Gemm g, const Sched& S, const Epi& E) {
;     ...
;             PG8_LDA(At, 1, 1); PG8_STAGE(PG8_SB(1, 0), b3, voffB); PG8_STAGE(PG8_SB(1, 1), b3 + hstep, voffB); PG8_STAGE(PG8_SA(1, 0), a3, voffA);
;             PG8_WAIT_V(8); PG8_WAIT_L(0); PG8_BAR; PG8_MMA(1, 0, At, B0); PG8_MMA(1, 1, At, B1); PG8_BAR; PG8_SCHED;
	s_add_i32 s24, s54, s27
	v_lshl_add_u64 v[194:195], v[194:195], 0, s[14:15]
	s_mov_b32 m0, s24
	ds_read_b128 v[182:185], v148 offset:49152
	ds_read_b128 v[186:189], v148 offset:50176
	ds_read_b128 v[190:193], v148 offset:51200
	ds_read_b128 v[198:201], v148 offset:52224
	ds_read_b128 v[202:205], v148 offset:53248
	ds_read_b128 v[206:209], v148 offset:54272
	ds_read_b128 v[210:213], v148 offset:55296
	ds_read_b128 v[214:217], v148 offset:56320
	global_load_lds_dwordx4 v[194:195], off
	v_lshl_add_u64 v[194:195], v[218:219], 0, s[14:15]
	s_add_i32 m0, s24, 0x2000
	s_add_i32 s24, s55, s27
	global_load_lds_dwordx4 v[194:195], off
	v_lshl_add_u64 v[194:195], v[220:221], 0, s[14:15]
	s_mov_b32 m0, s24
	s_nop 0
	global_load_lds_dwordx4 v[194:195], off
	v_lshl_add_u64 v[194:195], v[222:223], 0, s[14:15]
	s_add_i32 m0, s24, 0x2000
	s_nop 0
	global_load_lds_dwordx4 v[194:195], off
	v_lshl_add_u64 v[194:195], v[224:225], 0, s[14:15]
	s_mov_b32 m0, s40
	s_nop 0
	global_load_lds_dwordx4 v[194:195], off
	v_lshl_add_u64 v[194:195], v[226:227], 0, s[14:15]
	s_mov_b32 m0, s41
	s_nop 0
	global_load_lds_dwordx4 v[194:195], off
	s_waitcnt vmcnt(8)
	s_waitcnt lgkmcnt(0)
	s_barrier
	s_setprio 1
	s_waitcnt lgkmcnt(0)
	v_mfma_f32_16x16x32_bf16 v[92:95], v[150:153], v[182:185], v[92:95]
	v_mfma_f32_16x16x32_bf16 v[88:91], v[158:161], v[182:185], v[88:91]
	v_mfma_f32_16x16x32_bf16 v[84:87], v[150:153], v[190:193], v[84:87]
	v_mfma_f32_16x16x32_bf16 v[80:83], v[158:161], v[190:193], v[80:83]
	v_mfma_f32_16x16x32_bf16 v[76:79], v[150:153], v[202:205], v[76:79]
	v_mfma_f32_16x16x32_bf16 v[72:75], v[158:161], v[202:205], v[72:75]
	v_mfma_f32_16x16x32_bf16 v[68:71], v[150:153], v[210:213], v[68:71]
	v_mfma_f32_16x16x32_bf16 v[64:67], v[158:161], v[210:213], v[64:67]
	v_mfma_f32_16x16x32_bf16 v[92:95], v[154:157], v[186:189], v[92:95]
	v_mfma_f32_16x16x32_bf16 v[88:91], v[162:165], v[186:189], v[88:91]
	v_mfma_f32_16x16x32_bf16 v[84:87], v[154:157], v[198:201], v[84:87]
	v_mfma_f32_16x16x32_bf16 v[80:83], v[162:165], v[198:201], v[80:83]
	v_mfma_f32_16x16x32_bf16 v[76:79], v[154:157], v[206:209], v[76:79]
	v_mfma_f32_16x16x32_bf16 v[72:75], v[162:165], v[206:209], v[72:75]
	v_mfma_f32_16x16x32_bf16 v[68:71], v[154:157], v[214:217], v[68:71]
	v_mfma_f32_16x16x32_bf16 v[64:67], v[162:165], v[214:217], v[64:67]
	s_setprio 0
	s_setprio 1
	v_mfma_f32_16x16x32_bf16 v[28:31], v[166:169], v[182:185], v[28:31]
	v_mfma_f32_16x16x32_bf16 v[24:27], v[174:177], v[182:185], v[24:27]
	v_mfma_f32_16x16x32_bf16 v[20:23], v[166:169], v[190:193], v[20:23]
	v_mfma_f32_16x16x32_bf16 v[16:19], v[174:177], v[190:193], v[16:19]
	v_mfma_f32_16x16x32_bf16 v[12:15], v[166:169], v[202:205], v[12:15]
	v_mfma_f32_16x16x32_bf16 v[8:11], v[174:177], v[202:205], v[8:11]
	v_mfma_f32_16x16x32_bf16 v[4:7], v[166:169], v[210:213], v[4:7]
	v_mfma_f32_16x16x32_bf16 v[0:3], v[174:177], v[210:213], v[0:3]
	v_mfma_f32_16x16x32_bf16 v[28:31], v[170:173], v[186:189], v[28:31]
	v_mfma_f32_16x16x32_bf16 v[24:27], v[178:181], v[186:189], v[24:27]
	v_mfma_f32_16x16x32_bf16 v[20:23], v[170:173], v[198:201], v[20:23]
	v_mfma_f32_16x16x32_bf16 v[16:19], v[178:181], v[198:201], v[16:19]
	v_mfma_f32_16x16x32_bf16 v[12:15], v[170:173], v[206:209], v[12:15]
	v_mfma_f32_16x16x32_bf16 v[8:11], v[178:181], v[206:209], v[8:11]
	v_mfma_f32_16x16x32_bf16 v[4:7], v[170:173], v[214:217], v[4:7]
	v_mfma_f32_16x16x32_bf16 v[0:3], v[178:181], v[214:217], v[0:3]
	s_setprio 0
	s_add_u32 s22, s22, 0x100
	s_addc_u32 s23, s23, 0
	s_add_u32 s51, s51, 0x100
	s_addc_u32 s52, s52, 0
	s_cmp_ge_i32 s53, s38
	s_mov_b32 s24, s53
	s_barrier
	s_cbranch_scc0 .LBB0_757

; #define PG8_STAGE(bufoff, gbase, voff) do { _Pragma("unroll") for (int _i = 0; _i < 2; ++_i) \
;         __builtin_amdgcn_global_load_lds((const unsigned*)((const char*)(gbase) + (voff)[_i]), (PG8_LAS unsigned*)(lds + (bufoff) + ldsw + _i * 8192), 16, 0, 0); } while (0)
; #define PG8_LDA(dst, b, h) do { _Pragma("unroll") for (int m = 0; m < 4; ++m) _Pragma("unroll") for (int k = 0; k < 2; ++k) dst[m][k] = *(const PG8_LAS bf16x8*)(lds + PG8_SA(b, h) + aoff + m * 2048 + k * 1024); } while (0)
; #define PG8_LDB(dst, b, h) do { _Pragma("unroll") for (int n = 0; n < 2; ++n) _Pragma("unroll") for (int k = 0; k < 2; ++k) dst[n][k] = *(const PG8_LAS bf16x8*)(lds + PG8_SB(b, h) + boff + n * 2048 + k * 1024); } while (0)
; #define PG8_MMA(ai, bj, At, Bt) do { __builtin_amdgcn_s_setprio(1); _Pragma("unroll") for (int m = 0; m < 4; ++m) _Pragma("unroll") for (int n = 0; n < 2; ++n) _Pragma("unroll") for (int k = 0; k < 2; ++k) \
;         acc[ai][bj][m][n] = __builtin_amdgcn_mfma_f32_16x16x32_bf16(Bt[n][k], At[m][k], acc[ai][bj][m][n], 0, 0, 0); __builtin_amdgcn_s_setprio(0); } while (0)
; #define PG8_WAIT_V(n) asm volatile("s_waitcnt vmcnt(" #n ")" ::: "memory")
; #define PG8_WAIT_L(n) asm volatile("s_waitcnt lgkmcnt(" #n ")" ::: "memory")
; #define PG8_BAR __builtin_amdgcn_s_barrier()
; template <class Epi, class Sched, bool ALIGN_EPI = false, bool SP2 = false>
; __device__ __forceinline__ void gemm_phase(PG8_LAS unsigned char* lds, const Gemm g, const Sched& S, const Epi& E) {
;     ...
;             const char* a1 = cA + (size_t)(t + 1) * kstep;
;             const char* a2 = last ? nA : cA + (size_t)(t + 2) * kstep; const char* b2 = last ? nB : cB + (size_t)(t + 2) * kstep;
;             const char* a3 = a2 + kstep; const char* b3 = b2 + kstep;
;             if (last && has_next) S.a_ready(nxt);
;             if constexpr (SP2) {
;             PG8_LDB(B0, 0, 0); PG8_LDB(B1, 0, 1); PG8_SCHED; PG8_LDA(At, 0, 0); PG8_STAGE(PG8_SA(1, 1), a1 + hstep, voffA);
;             PG8_WAIT_V(8); PG8_WAIT_L(0); PG8_BAR; PG8_MMA(0, 0, At, B0); PG8_MMA(0, 1, At, B1); PG8_BAR; PG8_SCHED;
;             PG8_LDA(At, 0, 1); PG8_STAGE(PG8_SB(0, 0), b2, voffB); PG8_STAGE(PG8_SB(0, 1), b2 + hstep, voffB); PG8_STAGE(PG8_SA(0, 0), a2, voffA);
;             PG8_WAIT_V(8); PG8_WAIT_L(0); PG8_BAR; PG8_MMA(1, 0, At, B0); PG8_MMA(1, 1, At, B1); PG8_BAR; PG8_SCHED;
.Lp9h_b:
	ds_read_b128 v[144:147], v151
	ds_read_b128 v[156:159], v151 offset:1024
	ds_read_b128 v[160:163], v151 offset:2048
	ds_read_b128 v[164:167], v151 offset:3072
	ds_read_b128 v[168:171], v152
	ds_read_b128 v[172:175], v152 offset:1024
	ds_read_b128 v[176:179], v152 offset:2048
	ds_read_b128 v[180:183], v152 offset:3072
	s_add_u32 s26, s24, 0xfffc0080
	s_addc_u32 s27, s25, -1
	s_cmp_eq_u32 s48, 12
	s_cselect_b32 s29, s17, s27
	s_cselect_b32 s28, s23, s26
	s_cselect_b32 s27, s15, s47
	s_cselect_b32 s26, s45, s46
	v_lshl_add_u64 v[218:219], s[24:25], 0, v[136:137]
	s_add_i32 m0, s31, 0xc000
	ds_read_b128 v[184:187], v153
	ds_read_b128 v[188:191], v153 offset:1024
	ds_read_b128 v[192:195], v153 offset:2048
	ds_read_b128 v[198:201], v153 offset:3072
	ds_read_b128 v[202:205], v153 offset:4096
	ds_read_b128 v[206:209], v153 offset:5120
	ds_read_b128 v[210:213], v153 offset:6144
	ds_read_b128 v[214:217], v153 offset:7168
	global_load_lds_dwordx4 v[218:219], off
	v_lshl_add_u64 v[218:219], s[24:25], 0, v[138:139]
	s_add_i32 m0, s31, 0xe000
	s_nop 0
	global_load_lds_dwordx4 v[218:219], off
	s_waitcnt vmcnt(8)
	s_waitcnt lgkmcnt(0)
	s_barrier
	s_setprio 1
	s_waitcnt lgkmcnt(0)
	v_mfma_f32_16x16x32_bf16 v[124:127], v[144:147], v[184:187], v[124:127]
	v_mfma_f32_16x16x32_bf16 v[120:123], v[160:163], v[184:187], v[120:123]
	v_mfma_f32_16x16x32_bf16 v[108:111], v[144:147], v[192:195], v[108:111]
	v_mfma_f32_16x16x32_bf16 v[104:107], v[160:163], v[192:195], v[104:107]
	v_mfma_f32_16x16x32_bf16 v[92:95], v[144:147], v[202:205], v[92:95]
	v_mfma_f32_16x16x32_bf16 v[88:91], v[160:163], v[202:205], v[88:91]
	v_mfma_f32_16x16x32_bf16 v[76:79], v[144:147], v[210:213], v[76:79]
	v_mfma_f32_16x16x32_bf16 v[72:75], v[160:163], v[210:213], v[72:75]
	v_mfma_f32_16x16x32_bf16 v[124:127], v[156:159], v[188:191], v[124:127]
	v_mfma_f32_16x16x32_bf16 v[120:123], v[164:167], v[188:191], v[120:123]
	v_mfma_f32_16x16x32_bf16 v[108:111], v[156:159], v[198:201], v[108:111]
	v_mfma_f32_16x16x32_bf16 v[104:107], v[164:167], v[198:201], v[104:107]
	v_mfma_f32_16x16x32_bf16 v[92:95], v[156:159], v[206:209], v[92:95]
	v_mfma_f32_16x16x32_bf16 v[88:91], v[164:167], v[206:209], v[88:91]
	v_mfma_f32_16x16x32_bf16 v[76:79], v[156:159], v[214:217], v[76:79]
	v_mfma_f32_16x16x32_bf16 v[72:75], v[164:167], v[214:217], v[72:75]
	s_setprio 0
	s_setprio 1
	v_mfma_f32_16x16x32_bf16 v[116:119], v[168:171], v[184:187], v[116:119]
	v_mfma_f32_16x16x32_bf16 v[112:115], v[176:179], v[184:187], v[112:115]
	v_mfma_f32_16x16x32_bf16 v[100:103], v[168:171], v[192:195], v[100:103]
	v_mfma_f32_16x16x32_bf16 v[96:99], v[176:179], v[192:195], v[96:99]
	v_mfma_f32_16x16x32_bf16 v[84:87], v[168:171], v[202:205], v[84:87]
	v_mfma_f32_16x16x32_bf16 v[80:83], v[176:179], v[202:205], v[80:83]
	v_mfma_f32_16x16x32_bf16 v[68:71], v[168:171], v[210:213], v[68:71]
	v_mfma_f32_16x16x32_bf16 v[64:67], v[176:179], v[210:213], v[64:67]
	v_mfma_f32_16x16x32_bf16 v[116:119], v[172:175], v[188:191], v[116:119]
	v_mfma_f32_16x16x32_bf16 v[112:115], v[180:183], v[188:191], v[112:115]
	v_mfma_f32_16x16x32_bf16 v[100:103], v[172:175], v[198:201], v[100:103]
	v_mfma_f32_16x16x32_bf16 v[96:99], v[180:183], v[198:201], v[96:99]
	v_mfma_f32_16x16x32_bf16 v[84:87], v[172:175], v[206:209], v[84:87]
	v_mfma_f32_16x16x32_bf16 v[80:83], v[180:183], v[206:209], v[80:83]
	v_mfma_f32_16x16x32_bf16 v[68:71], v[172:175], v[214:217], v[68:71]
	v_mfma_f32_16x16x32_bf16 v[64:67], v[180:183], v[214:217], v[64:67]
	s_setprio 0
	s_barrier
	s_add_i32 s49, s42, s30
	v_lshl_add_u64 v[218:219], s[26:27], 0, v[130:131]
	s_mov_b32 m0, s49
	ds_read_b128 v[184:187], v153 offset:16384
	ds_read_b128 v[188:191], v153 offset:17408
	ds_read_b128 v[192:195], v153 offset:18432
	ds_read_b128 v[198:201], v153 offset:19456
	ds_read_b128 v[202:205], v153 offset:20480
	ds_read_b128 v[206:209], v153 offset:21504
	ds_read_b128 v[210:213], v153 offset:22528
	ds_read_b128 v[214:217], v153 offset:23552
	global_load_lds_dwordx4 v[218:219], off
	s_add_i32 m0, s49, 0x2000
	s_add_u32 s50, s26, 0x40000
	v_lshl_add_u64 v[220:221], s[26:27], 0, v[134:135]
	s_addc_u32 s51, s27, 0
	s_add_i32 s49, s43, s30
	global_load_lds_dwordx4 v[220:221], off
	v_lshl_add_u64 v[222:223], s[50:51], 0, v[130:131]
	s_mov_b32 m0, s49
	v_lshl_add_u64 v[224:225], s[28:29], 0, v[132:133]
	global_load_lds_dwordx4 v[222:223], off
	v_lshl_add_u64 v[222:223], s[50:51], 0, v[134:135]
	s_add_i32 m0, s49, 0x2000
	s_nop 0
	global_load_lds_dwordx4 v[222:223], off
	v_lshl_add_u64 v[222:223], s[28:29], 0, v[128:129]
	s_mov_b32 m0, s31
	s_nop 0
	global_load_lds_dwordx4 v[222:223], off
	s_mov_b32 m0, s33
	s_nop 0
	global_load_lds_dwordx4 v[224:225], off
	s_waitcnt vmcnt(8)
	s_waitcnt lgkmcnt(0)
	s_barrier
; #define PG8_STAGE(bufoff, gbase, voff) do { _Pragma("unroll") for (int _i = 0; _i < 2; ++_i) \
;         __builtin_amdgcn_global_load_lds((const unsigned*)((const char*)(gbase) + (voff)[_i]), (PG8_LAS unsigned*)(lds + (bufoff) + ldsw + _i * 8192), 16, 0, 0); } while (0)
; #define PG8_LDA(dst, b, h) do { _Pragma("unroll") for (int m = 0; m < 4; ++m) _Pragma("unroll") for (int k = 0; k < 2; ++k) dst[m][k] = *(const PG8_LAS bf16x8*)(lds + PG8_SA(b, h) + aoff + m * 2048 + k * 1024); } while (0)
; #define PG8_LDB(dst, b, h) do { _Pragma("unroll") for (int n = 0; n < 2; ++n) _Pragma("unroll") for (int k = 0; k < 2; ++k) dst[n][k] = *(const PG8_LAS bf16x8*)(lds + PG8_SB(b, h) + boff + n * 2048 + k * 1024); } while (0)
; #define PG8_MMA(ai, bj, At, Bt) do { __builtin_amdgcn_s_setprio(1); _Pragma("unroll") for (int m = 0; m < 4; ++m) _Pragma("unroll") for (int n = 0; n < 2; ++n) _Pragma("unroll") for (int k = 0; k < 2; ++k) \
;         acc[ai][bj][m][n] = __builtin_amdgcn_mfma_f32_16x16x32_bf16(Bt[n][k], At[m][k], acc[ai][bj][m][n], 0, 0, 0); __builtin_amdgcn_s_setprio(0); } while (0)
; #define PG8_WAIT_V(n) asm volatile("s_waitcnt vmcnt(" #n ")" ::: "memory")
; #define PG8_WAIT_L(n) asm volatile("s_waitcnt lgkmcnt(" #n ")" ::: "memory")
; #define PG8_BAR __builtin_amdgcn_s_barrier()
; #define PG8_SCHED __builtin_amdgcn_sched_barrier(0)
; template <class Epi, class Sched, bool ALIGN_EPI = false, bool SP2 = false>
; __device__ __forceinline__ void gemm_phase(PG8_LAS unsigned char* lds, const Gemm g, const Sched& S, const Epi& E) {
;     ...
;             PG8_WAIT_V(8); PG8_WAIT_L(0); PG8_BAR; PG8_MMA(1, 0, At, B0); PG8_MMA(1, 1, At, B1); PG8_BAR; PG8_SCHED;
;             PG8_LDB(B0, 1, 0); PG8_LDB(B1, 1, 1); PG8_SCHED; PG8_LDA(At, 1, 0); PG8_STAGE(PG8_SA(0, 1), a2 + hstep, voffA);
;             PG8_WAIT_V(8); PG8_WAIT_L(0); PG8_BAR; PG8_MMA(0, 0, At, B0); PG8_MMA(0, 1, At, B1); PG8_BAR; PG8_SCHED;
	s_setprio 1
	s_waitcnt lgkmcnt(0)
	v_mfma_f32_16x16x32_bf16 v[60:63], v[144:147], v[184:187], v[60:63]
	v_mfma_f32_16x16x32_bf16 v[56:59], v[160:163], v[184:187], v[56:59]
	v_mfma_f32_16x16x32_bf16 v[44:47], v[144:147], v[192:195], v[44:47]
	v_mfma_f32_16x16x32_bf16 v[40:43], v[160:163], v[192:195], v[40:43]
	v_mfma_f32_16x16x32_bf16 v[28:31], v[144:147], v[202:205], v[28:31]
	v_mfma_f32_16x16x32_bf16 v[24:27], v[160:163], v[202:205], v[24:27]
	v_mfma_f32_16x16x32_bf16 v[12:15], v[144:147], v[210:213], v[12:15]
	v_mfma_f32_16x16x32_bf16 v[8:11], v[160:163], v[210:213], v[8:11]
	v_mfma_f32_16x16x32_bf16 v[60:63], v[156:159], v[188:191], v[60:63]
	v_mfma_f32_16x16x32_bf16 v[56:59], v[164:167], v[188:191], v[56:59]
	v_mfma_f32_16x16x32_bf16 v[44:47], v[156:159], v[198:201], v[44:47]
	v_mfma_f32_16x16x32_bf16 v[40:43], v[164:167], v[198:201], v[40:43]
	v_mfma_f32_16x16x32_bf16 v[28:31], v[156:159], v[206:209], v[28:31]
	v_mfma_f32_16x16x32_bf16 v[24:27], v[164:167], v[206:209], v[24:27]
	v_mfma_f32_16x16x32_bf16 v[12:15], v[156:159], v[214:217], v[12:15]
	v_mfma_f32_16x16x32_bf16 v[8:11], v[164:167], v[214:217], v[8:11]
	s_setprio 0
	s_setprio 1
	v_mfma_f32_16x16x32_bf16 v[52:55], v[168:171], v[184:187], v[52:55]
	v_mfma_f32_16x16x32_bf16 v[48:51], v[176:179], v[184:187], v[48:51]
	v_mfma_f32_16x16x32_bf16 v[36:39], v[168:171], v[192:195], v[36:39]
	v_mfma_f32_16x16x32_bf16 v[32:35], v[176:179], v[192:195], v[32:35]
	v_mfma_f32_16x16x32_bf16 v[20:23], v[168:171], v[202:205], v[20:23]
	v_mfma_f32_16x16x32_bf16 v[16:19], v[176:179], v[202:205], v[16:19]
	v_mfma_f32_16x16x32_bf16 v[4:7], v[168:171], v[210:213], v[4:7]
	v_mfma_f32_16x16x32_bf16 v[0:3], v[176:179], v[210:213], v[0:3]
	v_mfma_f32_16x16x32_bf16 v[52:55], v[172:175], v[188:191], v[52:55]
	v_mfma_f32_16x16x32_bf16 v[48:51], v[180:183], v[188:191], v[48:51]
	v_mfma_f32_16x16x32_bf16 v[36:39], v[172:175], v[198:201], v[36:39]
	v_mfma_f32_16x16x32_bf16 v[32:35], v[180:183], v[198:201], v[32:35]
	v_mfma_f32_16x16x32_bf16 v[20:23], v[172:175], v[206:209], v[20:23]
	v_mfma_f32_16x16x32_bf16 v[16:19], v[180:183], v[206:209], v[16:19]
	v_mfma_f32_16x16x32_bf16 v[4:7], v[172:175], v[214:217], v[4:7]
	v_mfma_f32_16x16x32_bf16 v[0:3], v[180:183], v[214:217], v[0:3]
	s_setprio 0
	s_barrier
	s_add_i32 s49, 0, 0x18000
	v_add_u32_e32 v155, s49, v149
	s_add_i32 s50, 0, 0x1c000
	ds_read_b128 v[144:147], v155
	ds_read_b128 v[156:159], v155 offset:1024
	ds_read_b128 v[160:163], v155 offset:2048
	ds_read_b128 v[164:167], v155 offset:3072
	v_add_u32_e32 v155, s50, v149
	ds_read_b128 v[168:171], v155
	ds_read_b128 v[172:175], v155 offset:1024
	ds_read_b128 v[176:179], v155 offset:2048
	ds_read_b128 v[180:183], v155 offset:3072
	s_add_u32 s28, s28, 0x40000
	s_addc_u32 s29, s29, 0
	s_mov_b32 m0, s34
	v_lshl_add_u64 v[226:227], s[28:29], 0, v[128:129]
	ds_read_b128 v[184:187], v153 offset:32768
	ds_read_b128 v[188:191], v153 offset:33792
	ds_read_b128 v[192:195], v153 offset:34816
	ds_read_b128 v[198:201], v153 offset:35840
	ds_read_b128 v[202:205], v153 offset:36864
	ds_read_b128 v[206:209], v153 offset:37888
	ds_read_b128 v[210:213], v153 offset:38912
	ds_read_b128 v[214:217], v153 offset:39936
	global_load_lds_dwordx4 v[226:227], off
	v_lshl_add_u64 v[226:227], s[28:29], 0, v[132:133]
	s_mov_b32 m0, s35
	s_nop 0
	global_load_lds_dwordx4 v[226:227], off
	s_waitcnt vmcnt(8)
	s_waitcnt lgkmcnt(0)
	s_barrier
	s_setprio 1
	s_waitcnt lgkmcnt(0)
	v_mfma_f32_16x16x32_bf16 v[124:127], v[144:147], v[184:187], v[124:127]
	v_mfma_f32_16x16x32_bf16 v[120:123], v[160:163], v[184:187], v[120:123]
	v_mfma_f32_16x16x32_bf16 v[108:111], v[144:147], v[192:195], v[108:111]
	v_mfma_f32_16x16x32_bf16 v[104:107], v[160:163], v[192:195], v[104:107]
	v_mfma_f32_16x16x32_bf16 v[92:95], v[144:147], v[202:205], v[92:95]
	v_mfma_f32_16x16x32_bf16 v[88:91], v[160:163], v[202:205], v[88:91]
	v_mfma_f32_16x16x32_bf16 v[76:79], v[144:147], v[210:213], v[76:79]
	v_mfma_f32_16x16x32_bf16 v[72:75], v[160:163], v[210:213], v[72:75]
	v_mfma_f32_16x16x32_bf16 v[124:127], v[156:159], v[188:191], v[124:127]
	v_mfma_f32_16x16x32_bf16 v[120:123], v[164:167], v[188:191], v[120:123]
	v_mfma_f32_16x16x32_bf16 v[108:111], v[156:159], v[198:201], v[108:111]
	v_mfma_f32_16x16x32_bf16 v[104:107], v[164:167], v[198:201], v[104:107]
	v_mfma_f32_16x16x32_bf16 v[92:95], v[156:159], v[206:209], v[92:95]
	v_mfma_f32_16x16x32_bf16 v[88:91], v[164:167], v[206:209], v[88:91]
	v_mfma_f32_16x16x32_bf16 v[76:79], v[156:159], v[214:217], v[76:79]
	v_mfma_f32_16x16x32_bf16 v[72:75], v[164:167], v[214:217], v[72:75]
	s_setprio 0
	s_setprio 1
	v_mfma_f32_16x16x32_bf16 v[116:119], v[168:171], v[184:187], v[116:119]
	v_mfma_f32_16x16x32_bf16 v[112:115], v[176:179], v[184:187], v[112:115]
	v_mfma_f32_16x16x32_bf16 v[100:103], v[168:171], v[192:195], v[100:103]
	v_mfma_f32_16x16x32_bf16 v[96:99], v[176:179], v[192:195], v[96:99]
	v_mfma_f32_16x16x32_bf16 v[84:87], v[168:171], v[202:205], v[84:87]
	v_mfma_f32_16x16x32_bf16 v[80:83], v[176:179], v[202:205], v[80:83]
	v_mfma_f32_16x16x32_bf16 v[68:71], v[168:171], v[210:213], v[68:71]
	v_mfma_f32_16x16x32_bf16 v[64:67], v[176:179], v[210:213], v[64:67]
	v_mfma_f32_16x16x32_bf16 v[116:119], v[172:175], v[188:191], v[116:119]
	v_mfma_f32_16x16x32_bf16 v[112:115], v[180:183], v[188:191], v[112:115]
	v_mfma_f32_16x16x32_bf16 v[100:103], v[172:175], v[198:201], v[100:103]
	v_mfma_f32_16x16x32_bf16 v[96:99], v[180:183], v[198:201], v[96:99]
	v_mfma_f32_16x16x32_bf16 v[84:87], v[172:175], v[206:209], v[84:87]
	v_mfma_f32_16x16x32_bf16 v[80:83], v[180:183], v[206:209], v[80:83]
	v_mfma_f32_16x16x32_bf16 v[68:71], v[172:175], v[214:217], v[68:71]
	v_mfma_f32_16x16x32_bf16 v[64:67], v[180:183], v[214:217], v[64:67]
	s_setprio 0
	s_barrier
; #define PG8_STAGE(bufoff, gbase, voff) do { _Pragma("unroll") for (int _i = 0; _i < 2; ++_i) \
;         __builtin_amdgcn_global_load_lds((const unsigned*)((const char*)(gbase) + (voff)[_i]), (PG8_LAS unsigned*)(lds + (bufoff) + ldsw + _i * 8192), 16, 0, 0); } while (0)
; #define PG8_LDA(dst, b, h) do { _Pragma("unroll") for (int m = 0; m < 4; ++m) _Pragma("unroll") for (int k = 0; k < 2; ++k) dst[m][k] = *(const PG8_LAS bf16x8*)(lds + PG8_SA(b, h) + aoff + m * 2048 + k * 1024); } while (0)
; #define PG8_MMA(ai, bj, At, Bt) do { __builtin_amdgcn_s_setprio(1); _Pragma("unroll") for (int m = 0; m < 4; ++m) _Pragma("unroll") for (int n = 0; n < 2; ++n) _Pragma("unroll") for (int k = 0; k < 2; ++k) \
;         acc[ai][bj][m][n] = __builtin_amdgcn_mfma_f32_16x16x32_bf16(Bt[n][k], At[m][k], acc[ai][bj][m][n], 0, 0, 0); __builtin_amdgcn_s_setprio(0); } while (0)
; #define PG8_WAIT_V(n) asm volatile("s_waitcnt vmcnt(" #n ")" ::: "memory")
; #define PG8_WAIT_L(n) asm volatile("s_waitcnt lgkmcnt(" #n ")" ::: "memory")
; #define PG8_BAR __builtin_amdgcn_s_barrier()
; #define PG8_SCHED __builtin_amdgcn_sched_barrier(0)
; template <class Epi, class Sched, bool ALIGN_EPI = false, bool SP2 = false>
; __device__ __forceinline__ void gemm_phase(PG8_LAS unsigned char* lds, const Gemm g, const Sched& S, const Epi& E) {
;     ...
;             PG8_LDA(At, 1, 1); PG8_STAGE(PG8_SB(1, 0), b3, voffB); PG8_STAGE(PG8_SB(1, 1), b3 + hstep, voffB); PG8_STAGE(PG8_SA(1, 0), a3, voffA);
;             PG8_WAIT_V(8); PG8_WAIT_L(0); PG8_BAR; PG8_MMA(1, 0, At, B0); PG8_MMA(1, 1, At, B1); PG8_BAR; PG8_SCHED;
;     ...
;         if constexpr (ALIGN_EPI) { if (wr == 0) PG8_BAR; }
	s_add_i32 s28, s49, s30
	v_lshl_add_u64 v[218:219], v[218:219], 0, s[10:11]
	s_mov_b32 m0, s28
	ds_read_b128 v[184:187], v153 offset:49152
	ds_read_b128 v[188:191], v153 offset:50176
	ds_read_b128 v[192:195], v153 offset:51200
	ds_read_b128 v[198:201], v153 offset:52224
	ds_read_b128 v[202:205], v153 offset:53248
	ds_read_b128 v[206:209], v153 offset:54272
	ds_read_b128 v[210:213], v153 offset:55296
	ds_read_b128 v[214:217], v153 offset:56320
	global_load_lds_dwordx4 v[218:219], off
	s_add_i32 m0, s28, 0x2000
	s_add_u32 s26, s26, 0x40080
	v_lshl_add_u64 v[218:219], v[220:221], 0, s[10:11]
	s_addc_u32 s27, s27, 0
	s_add_i32 s28, s50, s30
	global_load_lds_dwordx4 v[218:219], off
	v_lshl_add_u64 v[218:219], s[26:27], 0, v[130:131]
	s_mov_b32 m0, s28
	s_nop 0
	global_load_lds_dwordx4 v[218:219], off
	v_lshl_add_u64 v[218:219], s[26:27], 0, v[134:135]
	s_add_i32 m0, s28, 0x2000
	s_nop 0
	global_load_lds_dwordx4 v[218:219], off
	v_lshl_add_u64 v[218:219], v[222:223], 0, s[10:11]
	s_mov_b32 m0, s39
	s_nop 0
	global_load_lds_dwordx4 v[218:219], off
	v_lshl_add_u64 v[218:219], v[224:225], 0, s[10:11]
	s_mov_b32 m0, s40
	s_nop 0
	global_load_lds_dwordx4 v[218:219], off
	s_waitcnt vmcnt(8)
	s_waitcnt lgkmcnt(0)
	s_barrier
	s_setprio 1
	s_waitcnt lgkmcnt(0)
	v_mfma_f32_16x16x32_bf16 v[60:63], v[144:147], v[184:187], v[60:63]
	v_mfma_f32_16x16x32_bf16 v[56:59], v[160:163], v[184:187], v[56:59]
	v_mfma_f32_16x16x32_bf16 v[44:47], v[144:147], v[192:195], v[44:47]
	v_mfma_f32_16x16x32_bf16 v[40:43], v[160:163], v[192:195], v[40:43]
	v_mfma_f32_16x16x32_bf16 v[28:31], v[144:147], v[202:205], v[28:31]
	v_mfma_f32_16x16x32_bf16 v[24:27], v[160:163], v[202:205], v[24:27]
	v_mfma_f32_16x16x32_bf16 v[12:15], v[144:147], v[210:213], v[12:15]
	v_mfma_f32_16x16x32_bf16 v[8:11], v[160:163], v[210:213], v[8:11]
	v_mfma_f32_16x16x32_bf16 v[60:63], v[156:159], v[188:191], v[60:63]
	v_mfma_f32_16x16x32_bf16 v[56:59], v[164:167], v[188:191], v[56:59]
	v_mfma_f32_16x16x32_bf16 v[44:47], v[156:159], v[198:201], v[44:47]
	v_mfma_f32_16x16x32_bf16 v[40:43], v[164:167], v[198:201], v[40:43]
	v_mfma_f32_16x16x32_bf16 v[28:31], v[156:159], v[206:209], v[28:31]
	v_mfma_f32_16x16x32_bf16 v[24:27], v[164:167], v[206:209], v[24:27]
	v_mfma_f32_16x16x32_bf16 v[12:15], v[156:159], v[214:217], v[12:15]
	v_mfma_f32_16x16x32_bf16 v[8:11], v[164:167], v[214:217], v[8:11]
	s_setprio 0
	s_setprio 1
	v_mfma_f32_16x16x32_bf16 v[52:55], v[168:171], v[184:187], v[52:55]
	v_mfma_f32_16x16x32_bf16 v[48:51], v[176:179], v[184:187], v[48:51]
	v_mfma_f32_16x16x32_bf16 v[36:39], v[168:171], v[192:195], v[36:39]
	v_mfma_f32_16x16x32_bf16 v[32:35], v[176:179], v[192:195], v[32:35]
	v_mfma_f32_16x16x32_bf16 v[20:23], v[168:171], v[202:205], v[20:23]
	v_mfma_f32_16x16x32_bf16 v[16:19], v[176:179], v[202:205], v[16:19]
	v_mfma_f32_16x16x32_bf16 v[4:7], v[168:171], v[210:213], v[4:7]
	v_mfma_f32_16x16x32_bf16 v[0:3], v[176:179], v[210:213], v[0:3]
	v_mfma_f32_16x16x32_bf16 v[52:55], v[172:175], v[188:191], v[52:55]
	v_mfma_f32_16x16x32_bf16 v[48:51], v[180:183], v[188:191], v[48:51]
	v_mfma_f32_16x16x32_bf16 v[36:39], v[172:175], v[198:201], v[36:39]
	v_mfma_f32_16x16x32_bf16 v[32:35], v[180:183], v[198:201], v[32:35]
	v_mfma_f32_16x16x32_bf16 v[20:23], v[172:175], v[206:209], v[20:23]
	v_mfma_f32_16x16x32_bf16 v[16:19], v[180:183], v[206:209], v[16:19]
	v_mfma_f32_16x16x32_bf16 v[4:7], v[172:175], v[214:217], v[4:7]
	v_mfma_f32_16x16x32_bf16 v[0:3], v[180:183], v[214:217], v[0:3]
	s_setprio 0
	s_add_i32 s48, s48, 2
	s_add_u32 s24, s24, 0x100
	s_addc_u32 s25, s25, 0
	s_add_u32 s46, s46, 0x100
	s_addc_u32 s47, s47, 0
	s_cmp_gt_u32 s48, 13
	s_barrier
	s_cbranch_scc0 .LBB0_991
	s_and_b64 vcc, exec, s[12:13]
	s_cbranch_vccz .LBB0_994
	s_barrier

; #define PG8_STAGE(bufoff, gbase, voff) do { _Pragma("unroll") for (int _i = 0; _i < 2; ++_i) \
;         __builtin_amdgcn_global_load_lds((const unsigned*)((const char*)(gbase) + (voff)[_i]), (PG8_LAS unsigned*)(lds + (bufoff) + ldsw + _i * 8192), 16, 0, 0); } while (0)
; #define PG8_LDA(dst, b, h) do { _Pragma("unroll") for (int m = 0; m < 4; ++m) _Pragma("unroll") for (int k = 0; k < 2; ++k) dst[m][k] = *(const PG8_LAS bf16x8*)(lds + PG8_SA(b, h) + aoff + m * 2048 + k * 1024); } while (0)
; #define PG8_LDB(dst, b, h) do { _Pragma("unroll") for (int n = 0; n < 2; ++n) _Pragma("unroll") for (int k = 0; k < 2; ++k) dst[n][k] = *(const PG8_LAS bf16x8*)(lds + PG8_SB(b, h) + boff + n * 2048 + k * 1024); } while (0)
; #define PG8_MMA(ai, bj, At, Bt) do { __builtin_amdgcn_s_setprio(1); _Pragma("unroll") for (int m = 0; m < 4; ++m) _Pragma("unroll") for (int n = 0; n < 2; ++n) _Pragma("unroll") for (int k = 0; k < 2; ++k) \
;         acc[ai][bj][m][n] = __builtin_amdgcn_mfma_f32_16x16x32_bf16(Bt[n][k], At[m][k], acc[ai][bj][m][n], 0, 0, 0); __builtin_amdgcn_s_setprio(0); } while (0)
; #define PG8_WAIT_V(n) asm volatile("s_waitcnt vmcnt(" #n ")" ::: "memory")
; #define PG8_WAIT_L(n) asm volatile("s_waitcnt lgkmcnt(" #n ")" ::: "memory")
; #define PG8_BAR __builtin_amdgcn_s_barrier()
; template <class Epi, class Sched, bool ALIGN_EPI = false, bool SP2 = false>
; __device__ __forceinline__ void gemm_phase(PG8_LAS unsigned char* lds, const Gemm g, const Sched& S, const Epi& E) {
;     ...
;             const char* a1 = cA + (size_t)(t + 1) * kstep;
;             const char* a2 = last ? nA : cA + (size_t)(t + 2) * kstep; const char* b2 = last ? nB : cB + (size_t)(t + 2) * kstep;
;             const char* a3 = a2 + kstep; const char* b3 = b2 + kstep;
;             if (last && has_next) S.a_ready(nxt);
;             if constexpr (SP2) {
;             PG8_LDB(B0, 0, 0); PG8_LDB(B1, 0, 1); PG8_SCHED; PG8_LDA(At, 0, 0); PG8_STAGE(PG8_SA(1, 1), a1 + hstep, voffA);
;             PG8_WAIT_V(8); PG8_WAIT_L(0); PG8_BAR; PG8_MMA(0, 0, At, B0); PG8_MMA(0, 1, At, B1); PG8_BAR; PG8_SCHED;
;             PG8_LDA(At, 0, 1); PG8_STAGE(PG8_SB(0, 0), b2, voffB); PG8_STAGE(PG8_SB(0, 1), b2 + hstep, voffB); PG8_STAGE(PG8_SA(0, 0), a2, voffA);
;             PG8_WAIT_V(8); PG8_WAIT_L(0); PG8_BAR; PG8_MMA(1, 0, At, B0); PG8_MMA(1, 1, At, B1); PG8_BAR; PG8_SCHED;
.LBB0_1146:
	ds_read_b128 v[144:147], v153
	ds_read_b128 v[156:159], v153 offset:1024
	ds_read_b128 v[160:163], v153 offset:2048
	ds_read_b128 v[164:167], v153 offset:3072
	ds_read_b128 v[168:171], v154
	ds_read_b128 v[172:175], v154 offset:1024
	ds_read_b128 v[176:179], v154 offset:2048
	ds_read_b128 v[180:183], v154 offset:3072
	s_add_u32 s28, s26, 0xfffc0080
	s_addc_u32 s29, s27, -1
	s_cmp_eq_u32 s50, 12
	s_cselect_b32 s31, s3, s29
	s_cselect_b32 s30, s19, s28
	s_cselect_b32 s29, s17, s49
	s_cselect_b32 s28, s47, s48
	v_lshl_add_u64 v[218:219], s[26:27], 0, v[136:137]
	s_add_i32 m0, s25, 0xc000
	ds_read_b128 v[184:187], v155
	ds_read_b128 v[188:191], v155 offset:1024
	ds_read_b128 v[192:195], v155 offset:2048
	ds_read_b128 v[198:201], v155 offset:3072
	ds_read_b128 v[202:205], v155 offset:4096
	ds_read_b128 v[206:209], v155 offset:5120
	ds_read_b128 v[210:213], v155 offset:6144
	ds_read_b128 v[214:217], v155 offset:7168
	global_load_lds_dwordx4 v[218:219], off
	v_lshl_add_u64 v[218:219], s[26:27], 0, v[138:139]
	s_add_i32 m0, s25, 0xe000
	s_nop 0
	global_load_lds_dwordx4 v[218:219], off
	s_waitcnt vmcnt(8)
	s_waitcnt lgkmcnt(0)
	s_barrier
	s_setprio 1
	s_waitcnt lgkmcnt(0)
	v_mfma_f32_16x16x32_bf16 v[124:127], v[144:147], v[184:187], v[124:127]
	v_mfma_f32_16x16x32_bf16 v[116:119], v[160:163], v[184:187], v[116:119]
	v_mfma_f32_16x16x32_bf16 v[108:111], v[144:147], v[192:195], v[108:111]
	v_mfma_f32_16x16x32_bf16 v[100:103], v[160:163], v[192:195], v[100:103]
	v_mfma_f32_16x16x32_bf16 v[92:95], v[144:147], v[202:205], v[92:95]
	v_mfma_f32_16x16x32_bf16 v[84:87], v[160:163], v[202:205], v[84:87]
	v_mfma_f32_16x16x32_bf16 v[76:79], v[144:147], v[210:213], v[76:79]
	v_mfma_f32_16x16x32_bf16 v[68:71], v[160:163], v[210:213], v[68:71]
	v_mfma_f32_16x16x32_bf16 v[124:127], v[156:159], v[188:191], v[124:127]
	v_mfma_f32_16x16x32_bf16 v[116:119], v[164:167], v[188:191], v[116:119]
	v_mfma_f32_16x16x32_bf16 v[108:111], v[156:159], v[198:201], v[108:111]
	v_mfma_f32_16x16x32_bf16 v[100:103], v[164:167], v[198:201], v[100:103]
	v_mfma_f32_16x16x32_bf16 v[92:95], v[156:159], v[206:209], v[92:95]
	v_mfma_f32_16x16x32_bf16 v[84:87], v[164:167], v[206:209], v[84:87]
	v_mfma_f32_16x16x32_bf16 v[76:79], v[156:159], v[214:217], v[76:79]
	v_mfma_f32_16x16x32_bf16 v[68:71], v[164:167], v[214:217], v[68:71]
	s_setprio 0
	s_setprio 1
	v_mfma_f32_16x16x32_bf16 v[120:123], v[168:171], v[184:187], v[120:123]
	v_mfma_f32_16x16x32_bf16 v[112:115], v[176:179], v[184:187], v[112:115]
	v_mfma_f32_16x16x32_bf16 v[104:107], v[168:171], v[192:195], v[104:107]
	v_mfma_f32_16x16x32_bf16 v[96:99], v[176:179], v[192:195], v[96:99]
	v_mfma_f32_16x16x32_bf16 v[88:91], v[168:171], v[202:205], v[88:91]
	v_mfma_f32_16x16x32_bf16 v[80:83], v[176:179], v[202:205], v[80:83]
	v_mfma_f32_16x16x32_bf16 v[72:75], v[168:171], v[210:213], v[72:75]
	v_mfma_f32_16x16x32_bf16 v[64:67], v[176:179], v[210:213], v[64:67]
	v_mfma_f32_16x16x32_bf16 v[120:123], v[172:175], v[188:191], v[120:123]
	v_mfma_f32_16x16x32_bf16 v[112:115], v[180:183], v[188:191], v[112:115]
	v_mfma_f32_16x16x32_bf16 v[104:107], v[172:175], v[198:201], v[104:107]
	v_mfma_f32_16x16x32_bf16 v[96:99], v[180:183], v[198:201], v[96:99]
	v_mfma_f32_16x16x32_bf16 v[88:91], v[172:175], v[206:209], v[88:91]
	v_mfma_f32_16x16x32_bf16 v[80:83], v[180:183], v[206:209], v[80:83]
	v_mfma_f32_16x16x32_bf16 v[72:75], v[172:175], v[214:217], v[72:75]
	v_mfma_f32_16x16x32_bf16 v[64:67], v[180:183], v[214:217], v[64:67]
	s_setprio 0
	s_barrier
	s_add_i32 s51, s44, s33
	v_lshl_add_u64 v[218:219], s[28:29], 0, v[130:131]
	s_mov_b32 m0, s51
	ds_read_b128 v[184:187], v155 offset:16384
	ds_read_b128 v[188:191], v155 offset:17408
	ds_read_b128 v[192:195], v155 offset:18432
	ds_read_b128 v[198:201], v155 offset:19456
	ds_read_b128 v[202:205], v155 offset:20480
	ds_read_b128 v[206:209], v155 offset:21504
	ds_read_b128 v[210:213], v155 offset:22528
	ds_read_b128 v[214:217], v155 offset:23552
	global_load_lds_dwordx4 v[218:219], off
	s_add_i32 m0, s51, 0x2000
	s_add_u32 s52, s28, 0x40000
	v_lshl_add_u64 v[220:221], s[28:29], 0, v[134:135]
	s_addc_u32 s53, s29, 0
	s_add_i32 s51, s45, s33
	global_load_lds_dwordx4 v[220:221], off
	v_lshl_add_u64 v[222:223], s[52:53], 0, v[130:131]
	s_mov_b32 m0, s51
	v_lshl_add_u64 v[224:225], s[30:31], 0, v[132:133]
	global_load_lds_dwordx4 v[222:223], off
	v_lshl_add_u64 v[222:223], s[52:53], 0, v[134:135]
	s_add_i32 m0, s51, 0x2000
	s_nop 0
	global_load_lds_dwordx4 v[222:223], off
	v_lshl_add_u64 v[222:223], s[30:31], 0, v[128:129]
	s_mov_b32 m0, s25
	s_nop 0
	global_load_lds_dwordx4 v[222:223], off
	s_mov_b32 m0, s34
	s_nop 0
	global_load_lds_dwordx4 v[224:225], off
	s_waitcnt vmcnt(8)
	s_waitcnt lgkmcnt(0)
	s_barrier
; #define PG8_STAGE(bufoff, gbase, voff) do { _Pragma("unroll") for (int _i = 0; _i < 2; ++_i) \
;         __builtin_amdgcn_global_load_lds((const unsigned*)((const char*)(gbase) + (voff)[_i]), (PG8_LAS unsigned*)(lds + (bufoff) + ldsw + _i * 8192), 16, 0, 0); } while (0)
; #define PG8_LDA(dst, b, h) do { _Pragma("unroll") for (int m = 0; m < 4; ++m) _Pragma("unroll") for (int k = 0; k < 2; ++k) dst[m][k] = *(const PG8_LAS bf16x8*)(lds + PG8_SA(b, h) + aoff + m * 2048 + k * 1024); } while (0)
; #define PG8_LDB(dst, b, h) do { _Pragma("unroll") for (int n = 0; n < 2; ++n) _Pragma("unroll") for (int k = 0; k < 2; ++k) dst[n][k] = *(const PG8_LAS bf16x8*)(lds + PG8_SB(b, h) + boff + n * 2048 + k * 1024); } while (0)
; #define PG8_MMA(ai, bj, At, Bt) do { __builtin_amdgcn_s_setprio(1); _Pragma("unroll") for (int m = 0; m < 4; ++m) _Pragma("unroll") for (int n = 0; n < 2; ++n) _Pragma("unroll") for (int k = 0; k < 2; ++k) \
;         acc[ai][bj][m][n] = __builtin_amdgcn_mfma_f32_16x16x32_bf16(Bt[n][k], At[m][k], acc[ai][bj][m][n], 0, 0, 0); __builtin_amdgcn_s_setprio(0); } while (0)
; #define PG8_WAIT_V(n) asm volatile("s_waitcnt vmcnt(" #n ")" ::: "memory")
; #define PG8_WAIT_L(n) asm volatile("s_waitcnt lgkmcnt(" #n ")" ::: "memory")
; #define PG8_BAR __builtin_amdgcn_s_barrier()
; #define PG8_SCHED __builtin_amdgcn_sched_barrier(0)
; template <class Epi, class Sched, bool ALIGN_EPI = false, bool SP2 = false>
; __device__ __forceinline__ void gemm_phase(PG8_LAS unsigned char* lds, const Gemm g, const Sched& S, const Epi& E) {
;     ...
;             PG8_WAIT_V(8); PG8_WAIT_L(0); PG8_BAR; PG8_MMA(1, 0, At, B0); PG8_MMA(1, 1, At, B1); PG8_BAR; PG8_SCHED;
;             PG8_LDB(B0, 1, 0); PG8_LDB(B1, 1, 1); PG8_SCHED; PG8_LDA(At, 1, 0); PG8_STAGE(PG8_SA(0, 1), a2 + hstep, voffA);
;             PG8_WAIT_V(8); PG8_WAIT_L(0); PG8_BAR; PG8_MMA(0, 0, At, B0); PG8_MMA(0, 1, At, B1); PG8_BAR; PG8_SCHED;
	s_setprio 1
	s_waitcnt lgkmcnt(0)
	v_mfma_f32_16x16x32_bf16 v[60:63], v[144:147], v[184:187], v[60:63]
	v_mfma_f32_16x16x32_bf16 v[52:55], v[160:163], v[184:187], v[52:55]
	v_mfma_f32_16x16x32_bf16 v[44:47], v[144:147], v[192:195], v[44:47]
	v_mfma_f32_16x16x32_bf16 v[36:39], v[160:163], v[192:195], v[36:39]
	v_mfma_f32_16x16x32_bf16 v[28:31], v[144:147], v[202:205], v[28:31]
	v_mfma_f32_16x16x32_bf16 v[20:23], v[160:163], v[202:205], v[20:23]
	v_mfma_f32_16x16x32_bf16 v[12:15], v[144:147], v[210:213], v[12:15]
	v_mfma_f32_16x16x32_bf16 v[4:7], v[160:163], v[210:213], v[4:7]
	v_mfma_f32_16x16x32_bf16 v[60:63], v[156:159], v[188:191], v[60:63]
	v_mfma_f32_16x16x32_bf16 v[52:55], v[164:167], v[188:191], v[52:55]
	v_mfma_f32_16x16x32_bf16 v[44:47], v[156:159], v[198:201], v[44:47]
	v_mfma_f32_16x16x32_bf16 v[36:39], v[164:167], v[198:201], v[36:39]
	v_mfma_f32_16x16x32_bf16 v[28:31], v[156:159], v[206:209], v[28:31]
	v_mfma_f32_16x16x32_bf16 v[20:23], v[164:167], v[206:209], v[20:23]
	v_mfma_f32_16x16x32_bf16 v[12:15], v[156:159], v[214:217], v[12:15]
	v_mfma_f32_16x16x32_bf16 v[4:7], v[164:167], v[214:217], v[4:7]
	s_setprio 0
	s_setprio 1
	v_mfma_f32_16x16x32_bf16 v[56:59], v[168:171], v[184:187], v[56:59]
	v_mfma_f32_16x16x32_bf16 v[48:51], v[176:179], v[184:187], v[48:51]
	v_mfma_f32_16x16x32_bf16 v[40:43], v[168:171], v[192:195], v[40:43]
	v_mfma_f32_16x16x32_bf16 v[32:35], v[176:179], v[192:195], v[32:35]
	v_mfma_f32_16x16x32_bf16 v[24:27], v[168:171], v[202:205], v[24:27]
	v_mfma_f32_16x16x32_bf16 v[16:19], v[176:179], v[202:205], v[16:19]
	v_mfma_f32_16x16x32_bf16 v[8:11], v[168:171], v[210:213], v[8:11]
	v_mfma_f32_16x16x32_bf16 v[0:3], v[176:179], v[210:213], v[0:3]
	v_mfma_f32_16x16x32_bf16 v[56:59], v[172:175], v[188:191], v[56:59]
	v_mfma_f32_16x16x32_bf16 v[48:51], v[180:183], v[188:191], v[48:51]
	v_mfma_f32_16x16x32_bf16 v[40:43], v[172:175], v[198:201], v[40:43]
	v_mfma_f32_16x16x32_bf16 v[32:35], v[180:183], v[198:201], v[32:35]
	v_mfma_f32_16x16x32_bf16 v[24:27], v[172:175], v[206:209], v[24:27]
	v_mfma_f32_16x16x32_bf16 v[16:19], v[180:183], v[206:209], v[16:19]
	v_mfma_f32_16x16x32_bf16 v[8:11], v[172:175], v[214:217], v[8:11]
	v_mfma_f32_16x16x32_bf16 v[0:3], v[180:183], v[214:217], v[0:3]
	s_setprio 0
	s_barrier
	s_add_i32 s51, 0, 0x18000
	v_add_u32_e32 v148, s51, v151
	s_add_i32 s52, 0, 0x1c000
	ds_read_b128 v[144:147], v148
	ds_read_b128 v[156:159], v148 offset:1024
	ds_read_b128 v[160:163], v148 offset:2048
	ds_read_b128 v[164:167], v148 offset:3072
	v_add_u32_e32 v148, s52, v151
	ds_read_b128 v[168:171], v148
	ds_read_b128 v[172:175], v148 offset:1024
	ds_read_b128 v[176:179], v148 offset:2048
	ds_read_b128 v[180:183], v148 offset:3072
	s_add_u32 s30, s30, 0x40000
	s_addc_u32 s31, s31, 0
	s_mov_b32 m0, s35
	v_lshl_add_u64 v[226:227], s[30:31], 0, v[128:129]
	ds_read_b128 v[184:187], v155 offset:32768
	ds_read_b128 v[188:191], v155 offset:33792
	ds_read_b128 v[192:195], v155 offset:34816
	ds_read_b128 v[198:201], v155 offset:35840
	ds_read_b128 v[202:205], v155 offset:36864
	ds_read_b128 v[206:209], v155 offset:37888
	ds_read_b128 v[210:213], v155 offset:38912
	ds_read_b128 v[214:217], v155 offset:39936
	global_load_lds_dwordx4 v[226:227], off
	v_lshl_add_u64 v[226:227], s[30:31], 0, v[132:133]
	s_mov_b32 m0, s36
	s_nop 0
	global_load_lds_dwordx4 v[226:227], off
	s_waitcnt vmcnt(8)
	s_waitcnt lgkmcnt(0)
	s_barrier
	s_setprio 1
	s_waitcnt lgkmcnt(0)
	v_mfma_f32_16x16x32_bf16 v[124:127], v[144:147], v[184:187], v[124:127]
	v_mfma_f32_16x16x32_bf16 v[116:119], v[160:163], v[184:187], v[116:119]
	v_mfma_f32_16x16x32_bf16 v[108:111], v[144:147], v[192:195], v[108:111]
	v_mfma_f32_16x16x32_bf16 v[100:103], v[160:163], v[192:195], v[100:103]
	v_mfma_f32_16x16x32_bf16 v[92:95], v[144:147], v[202:205], v[92:95]
	v_mfma_f32_16x16x32_bf16 v[84:87], v[160:163], v[202:205], v[84:87]
	v_mfma_f32_16x16x32_bf16 v[76:79], v[144:147], v[210:213], v[76:79]
	v_mfma_f32_16x16x32_bf16 v[68:71], v[160:163], v[210:213], v[68:71]
	v_mfma_f32_16x16x32_bf16 v[124:127], v[156:159], v[188:191], v[124:127]
	v_mfma_f32_16x16x32_bf16 v[116:119], v[164:167], v[188:191], v[116:119]
	v_mfma_f32_16x16x32_bf16 v[108:111], v[156:159], v[198:201], v[108:111]
	v_mfma_f32_16x16x32_bf16 v[100:103], v[164:167], v[198:201], v[100:103]
	v_mfma_f32_16x16x32_bf16 v[92:95], v[156:159], v[206:209], v[92:95]
	v_mfma_f32_16x16x32_bf16 v[84:87], v[164:167], v[206:209], v[84:87]
	v_mfma_f32_16x16x32_bf16 v[76:79], v[156:159], v[214:217], v[76:79]
	v_mfma_f32_16x16x32_bf16 v[68:71], v[164:167], v[214:217], v[68:71]
	s_setprio 0
	s_setprio 1
	v_mfma_f32_16x16x32_bf16 v[120:123], v[168:171], v[184:187], v[120:123]
	v_mfma_f32_16x16x32_bf16 v[112:115], v[176:179], v[184:187], v[112:115]
	v_mfma_f32_16x16x32_bf16 v[104:107], v[168:171], v[192:195], v[104:107]
	v_mfma_f32_16x16x32_bf16 v[96:99], v[176:179], v[192:195], v[96:99]
	v_mfma_f32_16x16x32_bf16 v[88:91], v[168:171], v[202:205], v[88:91]
	v_mfma_f32_16x16x32_bf16 v[80:83], v[176:179], v[202:205], v[80:83]
	v_mfma_f32_16x16x32_bf16 v[72:75], v[168:171], v[210:213], v[72:75]
	v_mfma_f32_16x16x32_bf16 v[64:67], v[176:179], v[210:213], v[64:67]
	v_mfma_f32_16x16x32_bf16 v[120:123], v[172:175], v[188:191], v[120:123]
	v_mfma_f32_16x16x32_bf16 v[112:115], v[180:183], v[188:191], v[112:115]
	v_mfma_f32_16x16x32_bf16 v[104:107], v[172:175], v[198:201], v[104:107]
	v_mfma_f32_16x16x32_bf16 v[96:99], v[180:183], v[198:201], v[96:99]
	v_mfma_f32_16x16x32_bf16 v[88:91], v[172:175], v[206:209], v[88:91]
	v_mfma_f32_16x16x32_bf16 v[80:83], v[180:183], v[206:209], v[80:83]
	v_mfma_f32_16x16x32_bf16 v[72:75], v[172:175], v[214:217], v[72:75]
	v_mfma_f32_16x16x32_bf16 v[64:67], v[180:183], v[214:217], v[64:67]
	s_setprio 0
	s_barrier
; #define PG8_STAGE(bufoff, gbase, voff) do { _Pragma("unroll") for (int _i = 0; _i < 2; ++_i) \
;         __builtin_amdgcn_global_load_lds((const unsigned*)((const char*)(gbase) + (voff)[_i]), (PG8_LAS unsigned*)(lds + (bufoff) + ldsw + _i * 8192), 16, 0, 0); } while (0)
; #define PG8_LDA(dst, b, h) do { _Pragma("unroll") for (int m = 0; m < 4; ++m) _Pragma("unroll") for (int k = 0; k < 2; ++k) dst[m][k] = *(const PG8_LAS bf16x8*)(lds + PG8_SA(b, h) + aoff + m * 2048 + k * 1024); } while (0)
; #define PG8_MMA(ai, bj, At, Bt) do { __builtin_amdgcn_s_setprio(1); _Pragma("unroll") for (int m = 0; m < 4; ++m) _Pragma("unroll") for (int n = 0; n < 2; ++n) _Pragma("unroll") for (int k = 0; k < 2; ++k) \
;         acc[ai][bj][m][n] = __builtin_amdgcn_mfma_f32_16x16x32_bf16(Bt[n][k], At[m][k], acc[ai][bj][m][n], 0, 0, 0); __builtin_amdgcn_s_setprio(0); } while (0)
; #define PG8_WAIT_V(n) asm volatile("s_waitcnt vmcnt(" #n ")" ::: "memory")
; #define PG8_WAIT_L(n) asm volatile("s_waitcnt lgkmcnt(" #n ")" ::: "memory")
; #define PG8_BAR __builtin_amdgcn_s_barrier()
; #define PG8_SCHED __builtin_amdgcn_sched_barrier(0)
; template <class Epi, class Sched, bool ALIGN_EPI = false, bool SP2 = false>
; __device__ __forceinline__ void gemm_phase(PG8_LAS unsigned char* lds, const Gemm g, const Sched& S, const Epi& E) {
;     ...
;             PG8_LDA(At, 1, 1); PG8_STAGE(PG8_SB(1, 0), b3, voffB); PG8_STAGE(PG8_SB(1, 1), b3 + hstep, voffB); PG8_STAGE(PG8_SA(1, 0), a3, voffA);
;             PG8_WAIT_V(8); PG8_WAIT_L(0); PG8_BAR; PG8_MMA(1, 0, At, B0); PG8_MMA(1, 1, At, B1); PG8_BAR; PG8_SCHED;
;     ...
;         if constexpr (ALIGN_EPI) { if (wr == 0) PG8_BAR; }
	s_add_i32 s30, s51, s33
	v_lshl_add_u64 v[218:219], v[218:219], 0, s[12:13]
	s_mov_b32 m0, s30
	ds_read_b128 v[184:187], v155 offset:49152
	ds_read_b128 v[188:191], v155 offset:50176
	ds_read_b128 v[192:195], v155 offset:51200
	ds_read_b128 v[198:201], v155 offset:52224
	ds_read_b128 v[202:205], v155 offset:53248
	ds_read_b128 v[206:209], v155 offset:54272
	ds_read_b128 v[210:213], v155 offset:55296
	ds_read_b128 v[214:217], v155 offset:56320
	global_load_lds_dwordx4 v[218:219], off
	s_add_i32 m0, s30, 0x2000
	s_add_u32 s28, s28, 0x40080
	v_lshl_add_u64 v[218:219], v[220:221], 0, s[12:13]
	s_addc_u32 s29, s29, 0
	s_add_i32 s30, s52, s33
	global_load_lds_dwordx4 v[218:219], off
	v_lshl_add_u64 v[218:219], s[28:29], 0, v[130:131]
	s_mov_b32 m0, s30
	s_nop 0
	global_load_lds_dwordx4 v[218:219], off
	v_lshl_add_u64 v[218:219], s[28:29], 0, v[134:135]
	s_add_i32 m0, s30, 0x2000
	s_nop 0
	global_load_lds_dwordx4 v[218:219], off
	v_lshl_add_u64 v[218:219], v[222:223], 0, s[12:13]
	s_mov_b32 m0, s40
	s_nop 0
	global_load_lds_dwordx4 v[218:219], off
	v_lshl_add_u64 v[218:219], v[224:225], 0, s[12:13]
	s_mov_b32 m0, s41
	s_nop 0
	global_load_lds_dwordx4 v[218:219], off
	s_waitcnt vmcnt(8)
	s_waitcnt lgkmcnt(0)
	s_barrier
	s_setprio 1
	s_waitcnt lgkmcnt(0)
	v_mfma_f32_16x16x32_bf16 v[60:63], v[144:147], v[184:187], v[60:63]
	v_mfma_f32_16x16x32_bf16 v[52:55], v[160:163], v[184:187], v[52:55]
	v_mfma_f32_16x16x32_bf16 v[44:47], v[144:147], v[192:195], v[44:47]
	v_mfma_f32_16x16x32_bf16 v[36:39], v[160:163], v[192:195], v[36:39]
	v_mfma_f32_16x16x32_bf16 v[28:31], v[144:147], v[202:205], v[28:31]
	v_mfma_f32_16x16x32_bf16 v[20:23], v[160:163], v[202:205], v[20:23]
	v_mfma_f32_16x16x32_bf16 v[12:15], v[144:147], v[210:213], v[12:15]
	v_mfma_f32_16x16x32_bf16 v[4:7], v[160:163], v[210:213], v[4:7]
	v_mfma_f32_16x16x32_bf16 v[60:63], v[156:159], v[188:191], v[60:63]
	v_mfma_f32_16x16x32_bf16 v[52:55], v[164:167], v[188:191], v[52:55]
	v_mfma_f32_16x16x32_bf16 v[44:47], v[156:159], v[198:201], v[44:47]
	v_mfma_f32_16x16x32_bf16 v[36:39], v[164:167], v[198:201], v[36:39]
	v_mfma_f32_16x16x32_bf16 v[28:31], v[156:159], v[206:209], v[28:31]
	v_mfma_f32_16x16x32_bf16 v[20:23], v[164:167], v[206:209], v[20:23]
	v_mfma_f32_16x16x32_bf16 v[12:15], v[156:159], v[214:217], v[12:15]
	v_mfma_f32_16x16x32_bf16 v[4:7], v[164:167], v[214:217], v[4:7]
	s_setprio 0
	s_setprio 1
	v_mfma_f32_16x16x32_bf16 v[56:59], v[168:171], v[184:187], v[56:59]
	v_mfma_f32_16x16x32_bf16 v[48:51], v[176:179], v[184:187], v[48:51]
	v_mfma_f32_16x16x32_bf16 v[40:43], v[168:171], v[192:195], v[40:43]
	v_mfma_f32_16x16x32_bf16 v[32:35], v[176:179], v[192:195], v[32:35]
	v_mfma_f32_16x16x32_bf16 v[24:27], v[168:171], v[202:205], v[24:27]
	v_mfma_f32_16x16x32_bf16 v[16:19], v[176:179], v[202:205], v[16:19]
	v_mfma_f32_16x16x32_bf16 v[8:11], v[168:171], v[210:213], v[8:11]
	v_mfma_f32_16x16x32_bf16 v[0:3], v[176:179], v[210:213], v[0:3]
	v_mfma_f32_16x16x32_bf16 v[56:59], v[172:175], v[188:191], v[56:59]
	v_mfma_f32_16x16x32_bf16 v[48:51], v[180:183], v[188:191], v[48:51]
	v_mfma_f32_16x16x32_bf16 v[40:43], v[172:175], v[198:201], v[40:43]
	v_mfma_f32_16x16x32_bf16 v[32:35], v[180:183], v[198:201], v[32:35]
	v_mfma_f32_16x16x32_bf16 v[24:27], v[172:175], v[206:209], v[24:27]
	v_mfma_f32_16x16x32_bf16 v[16:19], v[180:183], v[206:209], v[16:19]
	v_mfma_f32_16x16x32_bf16 v[8:11], v[172:175], v[214:217], v[8:11]
	v_mfma_f32_16x16x32_bf16 v[0:3], v[180:183], v[214:217], v[0:3]
	s_setprio 0
	s_add_i32 s50, s50, 2
	s_add_u32 s26, s26, 0x100
	s_addc_u32 s27, s27, 0
	s_add_u32 s48, s48, 0x100
	s_addc_u32 s49, s49, 0
	s_cmp_gt_u32 s50, 13
	s_barrier
	s_cbranch_scc0 .LBB0_1146
	s_and_b64 vcc, exec, s[14:15]
	s_cbranch_vccz .LBB0_1149
	s_barrier

; #define PG8_STAGE(bufoff, gbase, voff) do { _Pragma("unroll") for (int _i = 0; _i < 2; ++_i) \
;         __builtin_amdgcn_global_load_lds((const unsigned*)((const char*)(gbase) + (voff)[_i]), (PG8_LAS unsigned*)(lds + (bufoff) + ldsw + _i * 8192), 16, 0, 0); } while (0)
; #define PG8_LDA(dst, b, h) do { _Pragma("unroll") for (int m = 0; m < 4; ++m) _Pragma("unroll") for (int k = 0; k < 2; ++k) dst[m][k] = *(const PG8_LAS bf16x8*)(lds + PG8_SA(b, h) + aoff + m * 2048 + k * 1024); } while (0)
; #define PG8_LDB(dst, b, h) do { _Pragma("unroll") for (int n = 0; n < 2; ++n) _Pragma("unroll") for (int k = 0; k < 2; ++k) dst[n][k] = *(const PG8_LAS bf16x8*)(lds + PG8_SB(b, h) + boff + n * 2048 + k * 1024); } while (0)
; #define PG8_MMA(ai, bj, At, Bt) do { __builtin_amdgcn_s_setprio(1); _Pragma("unroll") for (int m = 0; m < 4; ++m) _Pragma("unroll") for (int n = 0; n < 2; ++n) _Pragma("unroll") for (int k = 0; k < 2; ++k) \
;         acc[ai][bj][m][n] = __builtin_amdgcn_mfma_f32_16x16x32_bf16(Bt[n][k], At[m][k], acc[ai][bj][m][n], 0, 0, 0); __builtin_amdgcn_s_setprio(0); } while (0)
; #define PG8_WAIT_V(n) asm volatile("s_waitcnt vmcnt(" #n ")" ::: "memory")
; #define PG8_WAIT_L(n) asm volatile("s_waitcnt lgkmcnt(" #n ")" ::: "memory")
; #define PG8_BAR __builtin_amdgcn_s_barrier()
; template <class Epi, class Sched, bool ALIGN_EPI = false, bool SP2 = false>
; __device__ __forceinline__ void gemm_phase(PG8_LAS unsigned char* lds, const Gemm g, const Sched& S, const Epi& E) {
;     ...
;             const char* a1 = cA + (size_t)(t + 1) * kstep;
;             const char* a2 = last ? nA : cA + (size_t)(t + 2) * kstep; const char* b2 = last ? nB : cB + (size_t)(t + 2) * kstep;
;             const char* a3 = a2 + kstep; const char* b3 = b2 + kstep;
;             if (last && has_next) S.a_ready(nxt);
;             if constexpr (SP2) {
;             PG8_LDB(B0, 0, 0); PG8_LDB(B1, 0, 1); PG8_SCHED; PG8_LDA(At, 0, 0); PG8_STAGE(PG8_SA(1, 1), a1 + hstep, voffA);
;             PG8_WAIT_V(8); PG8_WAIT_L(0); PG8_BAR; PG8_MMA(0, 0, At, B0); PG8_MMA(0, 1, At, B1); PG8_BAR; PG8_SCHED;
;             PG8_LDA(At, 0, 1); PG8_STAGE(PG8_SB(0, 0), b2, voffB); PG8_STAGE(PG8_SB(0, 1), b2 + hstep, voffB); PG8_STAGE(PG8_SA(0, 0), a2, voffA);
;             PG8_WAIT_V(8); PG8_WAIT_L(0); PG8_BAR; PG8_MMA(1, 0, At, B0); PG8_MMA(1, 1, At, B1); PG8_BAR; PG8_SCHED;
.LBB0_1239:
	ds_read_b128 v[144:147], v151
	ds_read_b128 v[156:159], v151 offset:1024
	ds_read_b128 v[160:163], v151 offset:2048
	ds_read_b128 v[164:167], v151 offset:3072
	ds_read_b128 v[168:171], v152
	ds_read_b128 v[172:175], v152 offset:1024
	ds_read_b128 v[176:179], v152 offset:2048
	ds_read_b128 v[180:183], v152 offset:3072
	s_add_u32 s20, s18, 0xfff50080
	s_addc_u32 s21, s19, -1
	s_cmp_eq_u32 s44, 40
	s_cselect_b32 s23, s5, s21
	s_cselect_b32 s22, s4, s20
	s_cselect_b32 s21, s17, s43
	s_cselect_b32 s20, s16, s42
	v_lshl_add_u64 v[218:219], s[18:19], 0, v[136:137]
	s_add_i32 m0, s25, 0xc000
	ds_read_b128 v[184:187], v153
	ds_read_b128 v[188:191], v153 offset:1024
	ds_read_b128 v[192:195], v153 offset:2048
	ds_read_b128 v[198:201], v153 offset:3072
	ds_read_b128 v[202:205], v153 offset:4096
	ds_read_b128 v[206:209], v153 offset:5120
	ds_read_b128 v[210:213], v153 offset:6144
	ds_read_b128 v[214:217], v153 offset:7168
	global_load_lds_dwordx4 v[218:219], off
	v_lshl_add_u64 v[218:219], s[18:19], 0, v[138:139]
	s_add_i32 m0, s25, 0xe000
	s_nop 0
	global_load_lds_dwordx4 v[218:219], off
	s_waitcnt vmcnt(8)
	s_waitcnt lgkmcnt(0)
	s_barrier
	s_setprio 1
	s_waitcnt lgkmcnt(0)
	v_mfma_f32_16x16x32_bf16 v[124:127], v[144:147], v[184:187], v[124:127]
	v_mfma_f32_16x16x32_bf16 v[120:123], v[160:163], v[184:187], v[120:123]
	v_mfma_f32_16x16x32_bf16 v[108:111], v[144:147], v[192:195], v[108:111]
	v_mfma_f32_16x16x32_bf16 v[104:107], v[160:163], v[192:195], v[104:107]
	v_mfma_f32_16x16x32_bf16 v[92:95], v[144:147], v[202:205], v[92:95]
	v_mfma_f32_16x16x32_bf16 v[88:91], v[160:163], v[202:205], v[88:91]
	v_mfma_f32_16x16x32_bf16 v[76:79], v[144:147], v[210:213], v[76:79]
	v_mfma_f32_16x16x32_bf16 v[72:75], v[160:163], v[210:213], v[72:75]
	v_mfma_f32_16x16x32_bf16 v[124:127], v[156:159], v[188:191], v[124:127]
	v_mfma_f32_16x16x32_bf16 v[120:123], v[164:167], v[188:191], v[120:123]
	v_mfma_f32_16x16x32_bf16 v[108:111], v[156:159], v[198:201], v[108:111]
	v_mfma_f32_16x16x32_bf16 v[104:107], v[164:167], v[198:201], v[104:107]
	v_mfma_f32_16x16x32_bf16 v[92:95], v[156:159], v[206:209], v[92:95]
	v_mfma_f32_16x16x32_bf16 v[88:91], v[164:167], v[206:209], v[88:91]
	v_mfma_f32_16x16x32_bf16 v[76:79], v[156:159], v[214:217], v[76:79]
	v_mfma_f32_16x16x32_bf16 v[72:75], v[164:167], v[214:217], v[72:75]
	s_setprio 0
	s_setprio 1
	v_mfma_f32_16x16x32_bf16 v[116:119], v[168:171], v[184:187], v[116:119]
	v_mfma_f32_16x16x32_bf16 v[112:115], v[176:179], v[184:187], v[112:115]
	v_mfma_f32_16x16x32_bf16 v[100:103], v[168:171], v[192:195], v[100:103]
	v_mfma_f32_16x16x32_bf16 v[96:99], v[176:179], v[192:195], v[96:99]
	v_mfma_f32_16x16x32_bf16 v[84:87], v[168:171], v[202:205], v[84:87]
	v_mfma_f32_16x16x32_bf16 v[80:83], v[176:179], v[202:205], v[80:83]
	v_mfma_f32_16x16x32_bf16 v[68:71], v[168:171], v[210:213], v[68:71]
	v_mfma_f32_16x16x32_bf16 v[64:67], v[176:179], v[210:213], v[64:67]
	v_mfma_f32_16x16x32_bf16 v[116:119], v[172:175], v[188:191], v[116:119]
	v_mfma_f32_16x16x32_bf16 v[112:115], v[180:183], v[188:191], v[112:115]
	v_mfma_f32_16x16x32_bf16 v[100:103], v[172:175], v[198:201], v[100:103]
	v_mfma_f32_16x16x32_bf16 v[96:99], v[180:183], v[198:201], v[96:99]
	v_mfma_f32_16x16x32_bf16 v[84:87], v[172:175], v[206:209], v[84:87]
	v_mfma_f32_16x16x32_bf16 v[80:83], v[180:183], v[206:209], v[80:83]
	v_mfma_f32_16x16x32_bf16 v[68:71], v[172:175], v[214:217], v[68:71]
	v_mfma_f32_16x16x32_bf16 v[64:67], v[180:183], v[214:217], v[64:67]
	s_setprio 0
	s_barrier
	s_add_i32 s45, s36, s24
	v_lshl_add_u64 v[218:219], s[20:21], 0, v[130:131]
	s_mov_b32 m0, s45
	ds_read_b128 v[184:187], v153 offset:16384
	ds_read_b128 v[188:191], v153 offset:17408
	ds_read_b128 v[192:195], v153 offset:18432
	ds_read_b128 v[198:201], v153 offset:19456
	ds_read_b128 v[202:205], v153 offset:20480
	ds_read_b128 v[206:209], v153 offset:21504
	ds_read_b128 v[210:213], v153 offset:22528
	ds_read_b128 v[214:217], v153 offset:23552
	global_load_lds_dwordx4 v[218:219], off
	s_add_i32 m0, s45, 0x2000
	s_add_u32 s46, s20, 0xb0000
	v_lshl_add_u64 v[220:221], s[20:21], 0, v[134:135]
	s_addc_u32 s47, s21, 0
	s_add_i32 s45, s37, s24
	global_load_lds_dwordx4 v[220:221], off
	v_lshl_add_u64 v[222:223], s[46:47], 0, v[130:131]
	s_mov_b32 m0, s45
	v_lshl_add_u64 v[224:225], s[22:23], 0, v[132:133]
	global_load_lds_dwordx4 v[222:223], off
	v_lshl_add_u64 v[222:223], s[46:47], 0, v[134:135]
	s_add_i32 m0, s45, 0x2000
	s_nop 0
	global_load_lds_dwordx4 v[222:223], off
	v_lshl_add_u64 v[222:223], s[22:23], 0, v[128:129]
	s_mov_b32 m0, s25
	s_nop 0
	global_load_lds_dwordx4 v[222:223], off
	s_mov_b32 m0, s26
	s_nop 0
	global_load_lds_dwordx4 v[224:225], off
	s_waitcnt vmcnt(8)
	s_waitcnt lgkmcnt(0)
	s_barrier
; #define PG8_STAGE(bufoff, gbase, voff) do { _Pragma("unroll") for (int _i = 0; _i < 2; ++_i) \
;         __builtin_amdgcn_global_load_lds((const unsigned*)((const char*)(gbase) + (voff)[_i]), (PG8_LAS unsigned*)(lds + (bufoff) + ldsw + _i * 8192), 16, 0, 0); } while (0)
; #define PG8_LDA(dst, b, h) do { _Pragma("unroll") for (int m = 0; m < 4; ++m) _Pragma("unroll") for (int k = 0; k < 2; ++k) dst[m][k] = *(const PG8_LAS bf16x8*)(lds + PG8_SA(b, h) + aoff + m * 2048 + k * 1024); } while (0)
; #define PG8_LDB(dst, b, h) do { _Pragma("unroll") for (int n = 0; n < 2; ++n) _Pragma("unroll") for (int k = 0; k < 2; ++k) dst[n][k] = *(const PG8_LAS bf16x8*)(lds + PG8_SB(b, h) + boff + n * 2048 + k * 1024); } while (0)
; #define PG8_MMA(ai, bj, At, Bt) do { __builtin_amdgcn_s_setprio(1); _Pragma("unroll") for (int m = 0; m < 4; ++m) _Pragma("unroll") for (int n = 0; n < 2; ++n) _Pragma("unroll") for (int k = 0; k < 2; ++k) \
;         acc[ai][bj][m][n] = __builtin_amdgcn_mfma_f32_16x16x32_bf16(Bt[n][k], At[m][k], acc[ai][bj][m][n], 0, 0, 0); __builtin_amdgcn_s_setprio(0); } while (0)
; #define PG8_WAIT_V(n) asm volatile("s_waitcnt vmcnt(" #n ")" ::: "memory")
; #define PG8_WAIT_L(n) asm volatile("s_waitcnt lgkmcnt(" #n ")" ::: "memory")
; #define PG8_BAR __builtin_amdgcn_s_barrier()
; #define PG8_SCHED __builtin_amdgcn_sched_barrier(0)
; template <class Epi, class Sched, bool ALIGN_EPI = false, bool SP2 = false>
; __device__ __forceinline__ void gemm_phase(PG8_LAS unsigned char* lds, const Gemm g, const Sched& S, const Epi& E) {
;     ...
;             PG8_WAIT_V(8); PG8_WAIT_L(0); PG8_BAR; PG8_MMA(1, 0, At, B0); PG8_MMA(1, 1, At, B1); PG8_BAR; PG8_SCHED;
;             PG8_LDB(B0, 1, 0); PG8_LDB(B1, 1, 1); PG8_SCHED; PG8_LDA(At, 1, 0); PG8_STAGE(PG8_SA(0, 1), a2 + hstep, voffA);
;             PG8_WAIT_V(8); PG8_WAIT_L(0); PG8_BAR; PG8_MMA(0, 0, At, B0); PG8_MMA(0, 1, At, B1); PG8_BAR; PG8_SCHED;
	s_setprio 1
	s_waitcnt lgkmcnt(0)
	v_mfma_f32_16x16x32_bf16 v[60:63], v[144:147], v[184:187], v[60:63]
	v_mfma_f32_16x16x32_bf16 v[56:59], v[160:163], v[184:187], v[56:59]
	v_mfma_f32_16x16x32_bf16 v[44:47], v[144:147], v[192:195], v[44:47]
	v_mfma_f32_16x16x32_bf16 v[40:43], v[160:163], v[192:195], v[40:43]
	v_mfma_f32_16x16x32_bf16 v[28:31], v[144:147], v[202:205], v[28:31]
	v_mfma_f32_16x16x32_bf16 v[24:27], v[160:163], v[202:205], v[24:27]
	v_mfma_f32_16x16x32_bf16 v[12:15], v[144:147], v[210:213], v[12:15]
	v_mfma_f32_16x16x32_bf16 v[8:11], v[160:163], v[210:213], v[8:11]
	v_mfma_f32_16x16x32_bf16 v[60:63], v[156:159], v[188:191], v[60:63]
	v_mfma_f32_16x16x32_bf16 v[56:59], v[164:167], v[188:191], v[56:59]
	v_mfma_f32_16x16x32_bf16 v[44:47], v[156:159], v[198:201], v[44:47]
	v_mfma_f32_16x16x32_bf16 v[40:43], v[164:167], v[198:201], v[40:43]
	v_mfma_f32_16x16x32_bf16 v[28:31], v[156:159], v[206:209], v[28:31]
	v_mfma_f32_16x16x32_bf16 v[24:27], v[164:167], v[206:209], v[24:27]
	v_mfma_f32_16x16x32_bf16 v[12:15], v[156:159], v[214:217], v[12:15]
	v_mfma_f32_16x16x32_bf16 v[8:11], v[164:167], v[214:217], v[8:11]
	s_setprio 0
	s_setprio 1
	v_mfma_f32_16x16x32_bf16 v[52:55], v[168:171], v[184:187], v[52:55]
	v_mfma_f32_16x16x32_bf16 v[48:51], v[176:179], v[184:187], v[48:51]
	v_mfma_f32_16x16x32_bf16 v[36:39], v[168:171], v[192:195], v[36:39]
	v_mfma_f32_16x16x32_bf16 v[32:35], v[176:179], v[192:195], v[32:35]
	v_mfma_f32_16x16x32_bf16 v[20:23], v[168:171], v[202:205], v[20:23]
	v_mfma_f32_16x16x32_bf16 v[16:19], v[176:179], v[202:205], v[16:19]
	v_mfma_f32_16x16x32_bf16 v[4:7], v[168:171], v[210:213], v[4:7]
	v_mfma_f32_16x16x32_bf16 v[0:3], v[176:179], v[210:213], v[0:3]
	v_mfma_f32_16x16x32_bf16 v[52:55], v[172:175], v[188:191], v[52:55]
	v_mfma_f32_16x16x32_bf16 v[48:51], v[180:183], v[188:191], v[48:51]
	v_mfma_f32_16x16x32_bf16 v[36:39], v[172:175], v[198:201], v[36:39]
	v_mfma_f32_16x16x32_bf16 v[32:35], v[180:183], v[198:201], v[32:35]
	v_mfma_f32_16x16x32_bf16 v[20:23], v[172:175], v[206:209], v[20:23]
	v_mfma_f32_16x16x32_bf16 v[16:19], v[180:183], v[206:209], v[16:19]
	v_mfma_f32_16x16x32_bf16 v[4:7], v[172:175], v[214:217], v[4:7]
	v_mfma_f32_16x16x32_bf16 v[0:3], v[180:183], v[214:217], v[0:3]
	s_setprio 0
	s_barrier
	s_add_i32 s45, 0, 0x18000
	v_add_u32_e32 v155, s45, v149
	s_add_i32 s46, 0, 0x1c000
	ds_read_b128 v[144:147], v155
	ds_read_b128 v[156:159], v155 offset:1024
	ds_read_b128 v[160:163], v155 offset:2048
	ds_read_b128 v[164:167], v155 offset:3072
	v_add_u32_e32 v155, s46, v149
	ds_read_b128 v[168:171], v155
	ds_read_b128 v[172:175], v155 offset:1024
	ds_read_b128 v[176:179], v155 offset:2048
	ds_read_b128 v[180:183], v155 offset:3072
	s_add_u32 s22, s22, 0xb0000
	s_addc_u32 s23, s23, 0
	s_mov_b32 m0, s27
	v_lshl_add_u64 v[226:227], s[22:23], 0, v[128:129]
	ds_read_b128 v[184:187], v153 offset:32768
	ds_read_b128 v[188:191], v153 offset:33792
	ds_read_b128 v[192:195], v153 offset:34816
	ds_read_b128 v[198:201], v153 offset:35840
	ds_read_b128 v[202:205], v153 offset:36864
	ds_read_b128 v[206:209], v153 offset:37888
	ds_read_b128 v[210:213], v153 offset:38912
	ds_read_b128 v[214:217], v153 offset:39936
	global_load_lds_dwordx4 v[226:227], off
	v_lshl_add_u64 v[226:227], s[22:23], 0, v[132:133]
	s_mov_b32 m0, s28
	s_nop 0
	global_load_lds_dwordx4 v[226:227], off
	s_waitcnt vmcnt(8)
	s_waitcnt lgkmcnt(0)
	s_barrier
	s_setprio 1
	s_waitcnt lgkmcnt(0)
	v_mfma_f32_16x16x32_bf16 v[124:127], v[144:147], v[184:187], v[124:127]
	v_mfma_f32_16x16x32_bf16 v[120:123], v[160:163], v[184:187], v[120:123]
	v_mfma_f32_16x16x32_bf16 v[108:111], v[144:147], v[192:195], v[108:111]
	v_mfma_f32_16x16x32_bf16 v[104:107], v[160:163], v[192:195], v[104:107]
	v_mfma_f32_16x16x32_bf16 v[92:95], v[144:147], v[202:205], v[92:95]
	v_mfma_f32_16x16x32_bf16 v[88:91], v[160:163], v[202:205], v[88:91]
	v_mfma_f32_16x16x32_bf16 v[76:79], v[144:147], v[210:213], v[76:79]
	v_mfma_f32_16x16x32_bf16 v[72:75], v[160:163], v[210:213], v[72:75]
	v_mfma_f32_16x16x32_bf16 v[124:127], v[156:159], v[188:191], v[124:127]
	v_mfma_f32_16x16x32_bf16 v[120:123], v[164:167], v[188:191], v[120:123]
	v_mfma_f32_16x16x32_bf16 v[108:111], v[156:159], v[198:201], v[108:111]
	v_mfma_f32_16x16x32_bf16 v[104:107], v[164:167], v[198:201], v[104:107]
	v_mfma_f32_16x16x32_bf16 v[92:95], v[156:159], v[206:209], v[92:95]
	v_mfma_f32_16x16x32_bf16 v[88:91], v[164:167], v[206:209], v[88:91]
	v_mfma_f32_16x16x32_bf16 v[76:79], v[156:159], v[214:217], v[76:79]
	v_mfma_f32_16x16x32_bf16 v[72:75], v[164:167], v[214:217], v[72:75]
	s_setprio 0
	s_setprio 1
	v_mfma_f32_16x16x32_bf16 v[116:119], v[168:171], v[184:187], v[116:119]
	v_mfma_f32_16x16x32_bf16 v[112:115], v[176:179], v[184:187], v[112:115]
	v_mfma_f32_16x16x32_bf16 v[100:103], v[168:171], v[192:195], v[100:103]
	v_mfma_f32_16x16x32_bf16 v[96:99], v[176:179], v[192:195], v[96:99]
	v_mfma_f32_16x16x32_bf16 v[84:87], v[168:171], v[202:205], v[84:87]
	v_mfma_f32_16x16x32_bf16 v[80:83], v[176:179], v[202:205], v[80:83]
	v_mfma_f32_16x16x32_bf16 v[68:71], v[168:171], v[210:213], v[68:71]
	v_mfma_f32_16x16x32_bf16 v[64:67], v[176:179], v[210:213], v[64:67]
	v_mfma_f32_16x16x32_bf16 v[116:119], v[172:175], v[188:191], v[116:119]
	v_mfma_f32_16x16x32_bf16 v[112:115], v[180:183], v[188:191], v[112:115]
	v_mfma_f32_16x16x32_bf16 v[100:103], v[172:175], v[198:201], v[100:103]
	v_mfma_f32_16x16x32_bf16 v[96:99], v[180:183], v[198:201], v[96:99]
	v_mfma_f32_16x16x32_bf16 v[84:87], v[172:175], v[206:209], v[84:87]
	v_mfma_f32_16x16x32_bf16 v[80:83], v[180:183], v[206:209], v[80:83]
	v_mfma_f32_16x16x32_bf16 v[68:71], v[172:175], v[214:217], v[68:71]
	v_mfma_f32_16x16x32_bf16 v[64:67], v[180:183], v[214:217], v[64:67]
	s_setprio 0
	s_barrier
; #define PG8_STAGE(bufoff, gbase, voff) do { _Pragma("unroll") for (int _i = 0; _i < 2; ++_i) \
;         __builtin_amdgcn_global_load_lds((const unsigned*)((const char*)(gbase) + (voff)[_i]), (PG8_LAS unsigned*)(lds + (bufoff) + ldsw + _i * 8192), 16, 0, 0); } while (0)
; #define PG8_LDA(dst, b, h) do { _Pragma("unroll") for (int m = 0; m < 4; ++m) _Pragma("unroll") for (int k = 0; k < 2; ++k) dst[m][k] = *(const PG8_LAS bf16x8*)(lds + PG8_SA(b, h) + aoff + m * 2048 + k * 1024); } while (0)
; #define PG8_MMA(ai, bj, At, Bt) do { __builtin_amdgcn_s_setprio(1); _Pragma("unroll") for (int m = 0; m < 4; ++m) _Pragma("unroll") for (int n = 0; n < 2; ++n) _Pragma("unroll") for (int k = 0; k < 2; ++k) \
;         acc[ai][bj][m][n] = __builtin_amdgcn_mfma_f32_16x16x32_bf16(Bt[n][k], At[m][k], acc[ai][bj][m][n], 0, 0, 0); __builtin_amdgcn_s_setprio(0); } while (0)
; #define PG8_WAIT_V(n) asm volatile("s_waitcnt vmcnt(" #n ")" ::: "memory")
; #define PG8_WAIT_L(n) asm volatile("s_waitcnt lgkmcnt(" #n ")" ::: "memory")
; #define PG8_BAR __builtin_amdgcn_s_barrier()
; #define PG8_SCHED __builtin_amdgcn_sched_barrier(0)
; template <class Epi, class Sched, bool ALIGN_EPI = false, bool SP2 = false>
; __device__ __forceinline__ void gemm_phase(PG8_LAS unsigned char* lds, const Gemm g, const Sched& S, const Epi& E) {
;     ...
;             PG8_LDA(At, 1, 1); PG8_STAGE(PG8_SB(1, 0), b3, voffB); PG8_STAGE(PG8_SB(1, 1), b3 + hstep, voffB); PG8_STAGE(PG8_SA(1, 0), a3, voffA);
;             PG8_WAIT_V(8); PG8_WAIT_L(0); PG8_BAR; PG8_MMA(1, 0, At, B0); PG8_MMA(1, 1, At, B1); PG8_BAR; PG8_SCHED;
;     ...
;         if constexpr (ALIGN_EPI) { if (wr == 0) PG8_BAR; }
	s_add_i32 s22, s45, s24
	v_lshl_add_u64 v[218:219], v[218:219], 0, s[12:13]
	s_mov_b32 m0, s22
	ds_read_b128 v[184:187], v153 offset:49152
	ds_read_b128 v[188:191], v153 offset:50176
	ds_read_b128 v[192:195], v153 offset:51200
	ds_read_b128 v[198:201], v153 offset:52224
	ds_read_b128 v[202:205], v153 offset:53248
	ds_read_b128 v[206:209], v153 offset:54272
	ds_read_b128 v[210:213], v153 offset:55296
	ds_read_b128 v[214:217], v153 offset:56320
	global_load_lds_dwordx4 v[218:219], off
	s_add_i32 m0, s22, 0x2000
	s_add_u32 s20, s20, 0xb0080
	v_lshl_add_u64 v[218:219], v[220:221], 0, s[12:13]
	s_addc_u32 s21, s21, 0
	s_add_i32 s22, s46, s24
	global_load_lds_dwordx4 v[218:219], off
	v_lshl_add_u64 v[218:219], s[20:21], 0, v[130:131]
	s_mov_b32 m0, s22
	s_nop 0
	global_load_lds_dwordx4 v[218:219], off
	v_lshl_add_u64 v[218:219], s[20:21], 0, v[134:135]
	s_add_i32 m0, s22, 0x2000
	s_nop 0
	global_load_lds_dwordx4 v[218:219], off
	v_lshl_add_u64 v[218:219], v[222:223], 0, s[12:13]
	s_mov_b32 m0, s33
	s_nop 0
	global_load_lds_dwordx4 v[218:219], off
	v_lshl_add_u64 v[218:219], v[224:225], 0, s[12:13]
	s_mov_b32 m0, s34
	s_nop 0
	global_load_lds_dwordx4 v[218:219], off
	s_waitcnt vmcnt(8)
	s_waitcnt lgkmcnt(0)
	s_barrier
	s_setprio 1
	s_waitcnt lgkmcnt(0)
	v_mfma_f32_16x16x32_bf16 v[60:63], v[144:147], v[184:187], v[60:63]
	v_mfma_f32_16x16x32_bf16 v[56:59], v[160:163], v[184:187], v[56:59]
	v_mfma_f32_16x16x32_bf16 v[44:47], v[144:147], v[192:195], v[44:47]
	v_mfma_f32_16x16x32_bf16 v[40:43], v[160:163], v[192:195], v[40:43]
	v_mfma_f32_16x16x32_bf16 v[28:31], v[144:147], v[202:205], v[28:31]
	v_mfma_f32_16x16x32_bf16 v[24:27], v[160:163], v[202:205], v[24:27]
	v_mfma_f32_16x16x32_bf16 v[12:15], v[144:147], v[210:213], v[12:15]
	v_mfma_f32_16x16x32_bf16 v[8:11], v[160:163], v[210:213], v[8:11]
	v_mfma_f32_16x16x32_bf16 v[60:63], v[156:159], v[188:191], v[60:63]
	v_mfma_f32_16x16x32_bf16 v[56:59], v[164:167], v[188:191], v[56:59]
	v_mfma_f32_16x16x32_bf16 v[44:47], v[156:159], v[198:201], v[44:47]
	v_mfma_f32_16x16x32_bf16 v[40:43], v[164:167], v[198:201], v[40:43]
	v_mfma_f32_16x16x32_bf16 v[28:31], v[156:159], v[206:209], v[28:31]
	v_mfma_f32_16x16x32_bf16 v[24:27], v[164:167], v[206:209], v[24:27]
	v_mfma_f32_16x16x32_bf16 v[12:15], v[156:159], v[214:217], v[12:15]
	v_mfma_f32_16x16x32_bf16 v[8:11], v[164:167], v[214:217], v[8:11]
	s_setprio 0
	s_setprio 1
	v_mfma_f32_16x16x32_bf16 v[52:55], v[168:171], v[184:187], v[52:55]
	v_mfma_f32_16x16x32_bf16 v[48:51], v[176:179], v[184:187], v[48:51]
	v_mfma_f32_16x16x32_bf16 v[36:39], v[168:171], v[192:195], v[36:39]
	v_mfma_f32_16x16x32_bf16 v[32:35], v[176:179], v[192:195], v[32:35]
	v_mfma_f32_16x16x32_bf16 v[20:23], v[168:171], v[202:205], v[20:23]
	v_mfma_f32_16x16x32_bf16 v[16:19], v[176:179], v[202:205], v[16:19]
	v_mfma_f32_16x16x32_bf16 v[4:7], v[168:171], v[210:213], v[4:7]
	v_mfma_f32_16x16x32_bf16 v[0:3], v[176:179], v[210:213], v[0:3]
	v_mfma_f32_16x16x32_bf16 v[52:55], v[172:175], v[188:191], v[52:55]
	v_mfma_f32_16x16x32_bf16 v[48:51], v[180:183], v[188:191], v[48:51]
	v_mfma_f32_16x16x32_bf16 v[36:39], v[172:175], v[198:201], v[36:39]
	v_mfma_f32_16x16x32_bf16 v[32:35], v[180:183], v[198:201], v[32:35]
	v_mfma_f32_16x16x32_bf16 v[20:23], v[172:175], v[206:209], v[20:23]
	v_mfma_f32_16x16x32_bf16 v[16:19], v[180:183], v[206:209], v[16:19]
	v_mfma_f32_16x16x32_bf16 v[4:7], v[172:175], v[214:217], v[4:7]
	v_mfma_f32_16x16x32_bf16 v[0:3], v[180:183], v[214:217], v[0:3]
	s_setprio 0
	s_add_i32 s44, s44, 2
	s_add_u32 s18, s18, 0x100
	s_addc_u32 s19, s19, 0
	s_add_u32 s42, s42, 0x100
	s_addc_u32 s43, s43, 0
	s_cmp_gt_u32 s44, 41
	s_barrier
	s_cbranch_scc0 .LBB0_1239
	s_and_b64 vcc, exec, s[14:15]
	s_cbranch_vccz .LBB0_1242
	s_barrier
